# lever 4 A/B: v12 with inverted priorities (loader segments prio 1, MFMA segments prio 0)
# baseline (speedup 1.0000x reference)
; #define PG8_STAGE(bufoff, gbase, voff) do { _Pragma("unroll") for (int _i = 0; _i < 2; ++_i) \
;         __builtin_amdgcn_global_load_lds((const unsigned*)((const char*)(gbase) + (voff)[_i]), (PG8_LAS unsigned*)(lds + (bufoff) + ldsw + _i * 8192), 16, 0, 0); } while (0)
; #define PG8_LDA(dst, b, h) do { _Pragma("unroll") for (int m = 0; m < 4; ++m) _Pragma("unroll") for (int k = 0; k < 2; ++k) dst[m][k] = *(const PG8_LAS bf16x8*)(lds + PG8_SA(b, h) + aoff + m * 2048 + k * 1024); } while (0)
; #define PG8_LDB(dst, b, h) do { _Pragma("unroll") for (int n = 0; n < 2; ++n) _Pragma("unroll") for (int k = 0; k < 2; ++k) dst[n][k] = *(const PG8_LAS bf16x8*)(lds + PG8_SB(b, h) + boff + n * 2048 + k * 1024); } while (0)
; template <class Epi, class Sched, bool ALIGN_EPI = false, bool SP2 = false>
; __device__ __forceinline__ void gemm_phase(PG8_LAS unsigned char* lds, const Gemm g, const Sched& S, const Epi& E) {
;     ...
;         for (; t < tend; t += 2) {
;             const bool last = (t == nt - 2);
;             const char* a1 = cA + (size_t)(t + 1) * kstep;
;             const char* a2 = last ? nA : cA + (size_t)(t + 2) * kstep; const char* b2 = last ? nB : cB + (size_t)(t + 2) * kstep;
;             const char* a3 = a2 + kstep; const char* b3 = b2 + kstep;
;             if (last && has_next) S.a_ready(nxt);
;             if constexpr (SP2) {
;             PG8_LDB(B0, 0, 0); PG8_LDB(B1, 0, 1); PG8_SCHED; PG8_LDA(At, 0, 0); PG8_STAGE(PG8_SA(1, 1), a1 + hstep, voffA);
;             PG8_WAIT_V(8); PG8_WAIT_L(0); PG8_BAR; PG8_MMA(0, 0, At, B0); PG8_MMA(0, 1, At, B1); PG8_BAR; PG8_SCHED;
;             PG8_LDA(At, 0, 1); PG8_STAGE(PG8_SB(0, 0), b2, voffB); PG8_STAGE(PG8_SB(0, 1), b2 + hstep, voffB); PG8_STAGE(PG8_SA(0, 0), a2, voffA);
;             PG8_WAIT_V(8); PG8_WAIT_L(0); PG8_BAR; PG8_MMA(1, 0, At, B0); PG8_MMA(1, 1, At, B1); PG8_BAR; PG8_SCHED;
;             PG8_LDB(B0, 1, 0); PG8_LDB(B1, 1, 1); PG8_SCHED; PG8_LDA(At, 1, 0); PG8_STAGE(PG8_SA(0, 1), a2 + hstep, voffA);
;             PG8_WAIT_V(8); PG8_WAIT_L(0); PG8_BAR; PG8_MMA(0, 0, At, B0); PG8_MMA(0, 1, At, B1); PG8_BAR; PG8_SCHED;
;             PG8_LDA(At, 1, 1); PG8_STAGE(PG8_SB(1, 0), b3, voffB); PG8_STAGE(PG8_SB(1, 1), b3 + hstep, voffB); PG8_STAGE(PG8_SA(1, 0), a3, voffA);
;             PG8_WAIT_V(8); PG8_WAIT_L(0); PG8_BAR; PG8_MMA(1, 0, At, B0); PG8_MMA(1, 1, At, B1); PG8_BAR; PG8_SCHED;
.LBB0_115:
	ds_read_b128 v[154:157], v150
	ds_read_b128 v[158:161], v150 offset:1024
	ds_read_b128 v[162:165], v150 offset:2048
	ds_read_b128 v[166:169], v150 offset:3072
	ds_read_b128 v[170:173], v151
	ds_read_b128 v[174:177], v151 offset:1024
	ds_read_b128 v[180:183], v151 offset:2048
	ds_read_b128 v[184:187], v151 offset:3072
	s_add_u32 s50, s48, 0x4000
	s_addc_u32 s51, s49, 0
	s_cmp_eq_u32 s76, 60
	s_cselect_b32 s74, s64, s50
	s_cselect_b32 s75, s25, s51
	s_cselect_b32 s72, s65, s68
	s_cselect_b32 s73, s19, s69
	s_add_u32 s50, s74, 0x8000
	s_addc_u32 s51, s75, 0
	s_sub_u32 s50, s48, 0x4000
	s_subb_u32 s51, s49, 0
	s_mov_b32 m0, s58
	s_nop 0
	global_load_lds_dwordx4 v130, s[50:51]
	s_mov_b32 m0, s59
	s_nop 0
	global_load_lds_dwordx4 v134, s[50:51]
	s_add_i32 m0, s28, 0xc000
	ds_read_b128 v[188:191], v152
	ds_read_b128 v[196:199], v152 offset:1024
	ds_read_b128 v[200:203], v152 offset:2048
	ds_read_b128 v[204:207], v152 offset:3072
	ds_read_b128 v[208:211], v152 offset:4096
	ds_read_b128 v[212:215], v152 offset:5120
	ds_read_b128 v[216:219], v152 offset:6144
	ds_read_b128 v[220:223], v152 offset:7168
	global_load_lds_dwordx4 v140, s[48:49]
	s_add_i32 m0, s28, 0xe000
	s_nop 0
	global_load_lds_dwordx4 v142, s[48:49]
	s_waitcnt vmcnt(8)
	s_waitcnt lgkmcnt(0)
	s_barrier
	s_setprio 0
	s_waitcnt lgkmcnt(0)
	v_mfma_f32_16x16x32_bf16 v[126:129], v[154:157], v[188:191], v[126:129]
	v_mfma_f32_16x16x32_bf16 v[126:129], v[158:161], v[196:199], v[126:129]
	v_mfma_f32_16x16x32_bf16 v[110:113], v[154:157], v[200:203], v[110:113]
	v_mfma_f32_16x16x32_bf16 v[110:113], v[158:161], v[204:207], v[110:113]
	v_mfma_f32_16x16x32_bf16 v[94:97], v[154:157], v[208:211], v[94:97]
	v_mfma_f32_16x16x32_bf16 v[94:97], v[158:161], v[212:215], v[94:97]
	v_mfma_f32_16x16x32_bf16 v[78:81], v[154:157], v[216:219], v[78:81]
	v_mfma_f32_16x16x32_bf16 v[78:81], v[158:161], v[220:223], v[78:81]
	v_mfma_f32_16x16x32_bf16 v[70:73], v[162:165], v[216:219], v[70:73]
	v_mfma_f32_16x16x32_bf16 v[70:73], v[166:169], v[220:223], v[70:73]
	v_mfma_f32_16x16x32_bf16 v[86:89], v[162:165], v[208:211], v[86:89]
	v_mfma_f32_16x16x32_bf16 v[86:89], v[166:169], v[212:215], v[86:89]
	v_mfma_f32_16x16x32_bf16 v[102:105], v[162:165], v[200:203], v[102:105]
	v_mfma_f32_16x16x32_bf16 v[102:105], v[166:169], v[204:207], v[102:105]
	v_mfma_f32_16x16x32_bf16 v[118:121], v[162:165], v[188:191], v[118:121]
	v_mfma_f32_16x16x32_bf16 v[118:121], v[166:169], v[196:199], v[118:121]
	v_mfma_f32_16x16x32_bf16 v[122:125], v[170:173], v[188:191], v[122:125]
	v_mfma_f32_16x16x32_bf16 v[122:125], v[174:177], v[196:199], v[122:125]
	v_mfma_f32_16x16x32_bf16 v[106:109], v[170:173], v[200:203], v[106:109]
	v_mfma_f32_16x16x32_bf16 v[106:109], v[174:177], v[204:207], v[106:109]
	v_mfma_f32_16x16x32_bf16 v[90:93], v[170:173], v[208:211], v[90:93]
	v_mfma_f32_16x16x32_bf16 v[90:93], v[174:177], v[212:215], v[90:93]
	v_mfma_f32_16x16x32_bf16 v[74:77], v[170:173], v[216:219], v[74:77]
	v_mfma_f32_16x16x32_bf16 v[74:77], v[174:177], v[220:223], v[74:77]
	v_mfma_f32_16x16x32_bf16 v[66:69], v[180:183], v[216:219], v[66:69]
	v_mfma_f32_16x16x32_bf16 v[66:69], v[184:187], v[220:223], v[66:69]
	v_mfma_f32_16x16x32_bf16 v[82:85], v[180:183], v[208:211], v[82:85]
	v_mfma_f32_16x16x32_bf16 v[82:85], v[184:187], v[212:215], v[82:85]
	v_mfma_f32_16x16x32_bf16 v[98:101], v[180:183], v[200:203], v[98:101]
	v_mfma_f32_16x16x32_bf16 v[98:101], v[184:187], v[204:207], v[98:101]
	v_mfma_f32_16x16x32_bf16 v[114:117], v[180:183], v[188:191], v[114:117]
	v_mfma_f32_16x16x32_bf16 v[114:117], v[184:187], v[196:199], v[114:117]
	s_setprio 1
	s_barrier
	s_add_i32 s77, s61, s3
	s_mov_b32 m0, s77
	ds_read_b128 v[188:191], v152 offset:16384
	ds_read_b128 v[196:199], v152 offset:17408
	ds_read_b128 v[200:203], v152 offset:18432
	ds_read_b128 v[204:207], v152 offset:19456
	ds_read_b128 v[208:211], v152 offset:20480
	ds_read_b128 v[212:215], v152 offset:21504
	ds_read_b128 v[216:219], v152 offset:22528
	ds_read_b128 v[220:223], v152 offset:23552
	global_load_lds_dwordx4 v132, s[72:73]
	s_add_i32 m0, s77, 0x2000
	s_add_u32 s78, s72, 0x4000
	s_addc_u32 s79, s73, 0
	s_add_i32 s77, s62, s3
	global_load_lds_dwordx4 v136, s[72:73]
	s_mov_b32 m0, s77
	s_nop 0
	global_load_lds_dwordx4 v132, s[78:79]
	s_add_i32 m0, s77, 0x2000
	s_nop 0
	global_load_lds_dwordx4 v136, s[78:79]
	s_waitcnt vmcnt(6)
	s_waitcnt lgkmcnt(0)
	s_barrier
	s_setprio 0
	s_waitcnt lgkmcnt(0)
	v_mfma_f32_16x16x32_bf16 v[62:65], v[154:157], v[188:191], v[62:65]
	v_mfma_f32_16x16x32_bf16 v[62:65], v[158:161], v[196:199], v[62:65]
	v_mfma_f32_16x16x32_bf16 v[46:49], v[154:157], v[200:203], v[46:49]
	v_mfma_f32_16x16x32_bf16 v[46:49], v[158:161], v[204:207], v[46:49]
	v_mfma_f32_16x16x32_bf16 v[30:33], v[154:157], v[208:211], v[30:33]
	v_mfma_f32_16x16x32_bf16 v[30:33], v[158:161], v[212:215], v[30:33]
	v_mfma_f32_16x16x32_bf16 v[14:17], v[154:157], v[216:219], v[14:17]
	v_mfma_f32_16x16x32_bf16 v[14:17], v[158:161], v[220:223], v[14:17]
	v_mfma_f32_16x16x32_bf16 v[6:9], v[162:165], v[216:219], v[6:9]
	v_mfma_f32_16x16x32_bf16 v[6:9], v[166:169], v[220:223], v[6:9]
	v_mfma_f32_16x16x32_bf16 v[22:25], v[162:165], v[208:211], v[22:25]
	v_mfma_f32_16x16x32_bf16 v[22:25], v[166:169], v[212:215], v[22:25]
	v_mfma_f32_16x16x32_bf16 v[38:41], v[162:165], v[200:203], v[38:41]
	v_mfma_f32_16x16x32_bf16 v[38:41], v[166:169], v[204:207], v[38:41]
	v_mfma_f32_16x16x32_bf16 v[54:57], v[162:165], v[188:191], v[54:57]
	v_mfma_f32_16x16x32_bf16 v[54:57], v[166:169], v[196:199], v[54:57]
	v_mfma_f32_16x16x32_bf16 v[58:61], v[170:173], v[188:191], v[58:61]
	v_mfma_f32_16x16x32_bf16 v[58:61], v[174:177], v[196:199], v[58:61]
	v_mfma_f32_16x16x32_bf16 v[42:45], v[170:173], v[200:203], v[42:45]
	v_mfma_f32_16x16x32_bf16 v[42:45], v[174:177], v[204:207], v[42:45]
	v_mfma_f32_16x16x32_bf16 v[26:29], v[170:173], v[208:211], v[26:29]
	v_mfma_f32_16x16x32_bf16 v[26:29], v[174:177], v[212:215], v[26:29]
	v_mfma_f32_16x16x32_bf16 v[10:13], v[170:173], v[216:219], v[10:13]
	v_mfma_f32_16x16x32_bf16 v[10:13], v[174:177], v[220:223], v[10:13]
	v_mfma_f32_16x16x32_bf16 v[2:5], v[180:183], v[216:219], v[2:5]
	v_mfma_f32_16x16x32_bf16 v[2:5], v[184:187], v[220:223], v[2:5]
	v_mfma_f32_16x16x32_bf16 v[18:21], v[180:183], v[208:211], v[18:21]
	v_mfma_f32_16x16x32_bf16 v[18:21], v[184:187], v[212:215], v[18:21]
	v_mfma_f32_16x16x32_bf16 v[34:37], v[180:183], v[200:203], v[34:37]
	v_mfma_f32_16x16x32_bf16 v[34:37], v[184:187], v[204:207], v[34:37]
	v_mfma_f32_16x16x32_bf16 v[50:53], v[180:183], v[188:191], v[50:53]
	v_mfma_f32_16x16x32_bf16 v[50:53], v[184:187], v[196:199], v[50:53]
	s_setprio 1
	s_barrier
; #define PG8_STAGE(bufoff, gbase, voff) do { _Pragma("unroll") for (int _i = 0; _i < 2; ++_i) \
;         __builtin_amdgcn_global_load_lds((const unsigned*)((const char*)(gbase) + (voff)[_i]), (PG8_LAS unsigned*)(lds + (bufoff) + ldsw + _i * 8192), 16, 0, 0); } while (0)
; #define PG8_LDA(dst, b, h) do { _Pragma("unroll") for (int m = 0; m < 4; ++m) _Pragma("unroll") for (int k = 0; k < 2; ++k) dst[m][k] = *(const PG8_LAS bf16x8*)(lds + PG8_SA(b, h) + aoff + m * 2048 + k * 1024); } while (0)
; #define PG8_LDB(dst, b, h) do { _Pragma("unroll") for (int n = 0; n < 2; ++n) _Pragma("unroll") for (int k = 0; k < 2; ++k) dst[n][k] = *(const PG8_LAS bf16x8*)(lds + PG8_SB(b, h) + boff + n * 2048 + k * 1024); } while (0)
; template <class Epi, class Sched, bool ALIGN_EPI = false, bool SP2 = false>
; __device__ __forceinline__ void gemm_phase(PG8_LAS unsigned char* lds, const Gemm g, const Sched& S, const Epi& E) {
;     ...
;         for (; t < tend; t += 2) {
;             const bool last = (t == nt - 2);
;             const char* a1 = cA + (size_t)(t + 1) * kstep;
;             const char* a2 = last ? nA : cA + (size_t)(t + 2) * kstep; const char* b2 = last ? nB : cB + (size_t)(t + 2) * kstep;
;             const char* a3 = a2 + kstep; const char* b3 = b2 + kstep;
;             if (last && has_next) S.a_ready(nxt);
;             if constexpr (SP2) {
;             PG8_LDB(B0, 0, 0); PG8_LDB(B1, 0, 1); PG8_SCHED; PG8_LDA(At, 0, 0); PG8_STAGE(PG8_SA(1, 1), a1 + hstep, voffA);
;             PG8_WAIT_V(8); PG8_WAIT_L(0); PG8_BAR; PG8_MMA(0, 0, At, B0); PG8_MMA(0, 1, At, B1); PG8_BAR; PG8_SCHED;
;             PG8_LDA(At, 0, 1); PG8_STAGE(PG8_SB(0, 0), b2, voffB); PG8_STAGE(PG8_SB(0, 1), b2 + hstep, voffB); PG8_STAGE(PG8_SA(0, 0), a2, voffA);
;             PG8_WAIT_V(8); PG8_WAIT_L(0); PG8_BAR; PG8_MMA(1, 0, At, B0); PG8_MMA(1, 1, At, B1); PG8_BAR; PG8_SCHED;
;             PG8_LDB(B0, 1, 0); PG8_LDB(B1, 1, 1); PG8_SCHED; PG8_LDA(At, 1, 0); PG8_STAGE(PG8_SA(0, 1), a2 + hstep, voffA);
;             PG8_WAIT_V(8); PG8_WAIT_L(0); PG8_BAR; PG8_MMA(0, 0, At, B0); PG8_MMA(0, 1, At, B1); PG8_BAR; PG8_SCHED;
;             PG8_LDA(At, 1, 1); PG8_STAGE(PG8_SB(1, 0), b3, voffB); PG8_STAGE(PG8_SB(1, 1), b3 + hstep, voffB); PG8_STAGE(PG8_SA(1, 0), a3, voffA);
;             PG8_WAIT_V(8); PG8_WAIT_L(0); PG8_BAR; PG8_MMA(1, 0, At, B0); PG8_MMA(1, 1, At, B1); PG8_BAR; PG8_SCHED;
	s_add_i32 s77, 0, 0x18000
	v_add_u32_e32 v138, s77, v148
	s_add_i32 s78, 0, 0x1c000
	ds_read_b128 v[154:157], v138
	ds_read_b128 v[158:161], v138 offset:1024
	ds_read_b128 v[162:165], v138 offset:2048
	ds_read_b128 v[166:169], v138 offset:3072
	v_add_u32_e32 v138, s78, v148
	ds_read_b128 v[170:173], v138
	ds_read_b128 v[174:177], v138 offset:1024
	ds_read_b128 v[180:183], v138 offset:2048
	ds_read_b128 v[184:187], v138 offset:3072
	s_mov_b32 m0, s28
	s_nop 0
	global_load_lds_dwordx4 v130, s[74:75]
	s_mov_b32 m0, s29
	s_nop 0
	global_load_lds_dwordx4 v134, s[74:75]
	s_add_u32 s74, s74, 0x4000
	s_addc_u32 s75, s75, 0
	s_mov_b32 m0, s30
	ds_read_b128 v[188:191], v152 offset:32768
	ds_read_b128 v[196:199], v152 offset:33792
	ds_read_b128 v[200:203], v152 offset:34816
	ds_read_b128 v[204:207], v152 offset:35840
	ds_read_b128 v[208:211], v152 offset:36864
	ds_read_b128 v[212:215], v152 offset:37888
	ds_read_b128 v[216:219], v152 offset:38912
	ds_read_b128 v[220:223], v152 offset:39936
	global_load_lds_dwordx4 v130, s[74:75]
	s_mov_b32 m0, s31
	s_nop 0
	global_load_lds_dwordx4 v134, s[74:75]
	s_waitcnt vmcnt(8)
	s_waitcnt lgkmcnt(0)
	s_barrier
	s_setprio 0
	s_waitcnt lgkmcnt(0)
	v_mfma_f32_16x16x32_bf16 v[126:129], v[154:157], v[188:191], v[126:129]
	v_mfma_f32_16x16x32_bf16 v[126:129], v[158:161], v[196:199], v[126:129]
	v_mfma_f32_16x16x32_bf16 v[110:113], v[154:157], v[200:203], v[110:113]
	v_mfma_f32_16x16x32_bf16 v[110:113], v[158:161], v[204:207], v[110:113]
	v_mfma_f32_16x16x32_bf16 v[94:97], v[154:157], v[208:211], v[94:97]
	v_mfma_f32_16x16x32_bf16 v[94:97], v[158:161], v[212:215], v[94:97]
	v_mfma_f32_16x16x32_bf16 v[78:81], v[154:157], v[216:219], v[78:81]
	v_mfma_f32_16x16x32_bf16 v[78:81], v[158:161], v[220:223], v[78:81]
	v_mfma_f32_16x16x32_bf16 v[70:73], v[162:165], v[216:219], v[70:73]
	v_mfma_f32_16x16x32_bf16 v[70:73], v[166:169], v[220:223], v[70:73]
	v_mfma_f32_16x16x32_bf16 v[86:89], v[162:165], v[208:211], v[86:89]
	v_mfma_f32_16x16x32_bf16 v[86:89], v[166:169], v[212:215], v[86:89]
	v_mfma_f32_16x16x32_bf16 v[102:105], v[162:165], v[200:203], v[102:105]
	v_mfma_f32_16x16x32_bf16 v[102:105], v[166:169], v[204:207], v[102:105]
	v_mfma_f32_16x16x32_bf16 v[118:121], v[162:165], v[188:191], v[118:121]
	v_mfma_f32_16x16x32_bf16 v[118:121], v[166:169], v[196:199], v[118:121]
	v_mfma_f32_16x16x32_bf16 v[122:125], v[170:173], v[188:191], v[122:125]
	v_mfma_f32_16x16x32_bf16 v[122:125], v[174:177], v[196:199], v[122:125]
	v_mfma_f32_16x16x32_bf16 v[106:109], v[170:173], v[200:203], v[106:109]
	v_mfma_f32_16x16x32_bf16 v[106:109], v[174:177], v[204:207], v[106:109]
	v_mfma_f32_16x16x32_bf16 v[90:93], v[170:173], v[208:211], v[90:93]
	v_mfma_f32_16x16x32_bf16 v[90:93], v[174:177], v[212:215], v[90:93]
	v_mfma_f32_16x16x32_bf16 v[74:77], v[170:173], v[216:219], v[74:77]
	v_mfma_f32_16x16x32_bf16 v[74:77], v[174:177], v[220:223], v[74:77]
	v_mfma_f32_16x16x32_bf16 v[66:69], v[180:183], v[216:219], v[66:69]
	v_mfma_f32_16x16x32_bf16 v[66:69], v[184:187], v[220:223], v[66:69]
	v_mfma_f32_16x16x32_bf16 v[82:85], v[180:183], v[208:211], v[82:85]
	v_mfma_f32_16x16x32_bf16 v[82:85], v[184:187], v[212:215], v[82:85]
	v_mfma_f32_16x16x32_bf16 v[98:101], v[180:183], v[200:203], v[98:101]
	v_mfma_f32_16x16x32_bf16 v[98:101], v[184:187], v[204:207], v[98:101]
	v_mfma_f32_16x16x32_bf16 v[114:117], v[180:183], v[188:191], v[114:117]
	v_mfma_f32_16x16x32_bf16 v[114:117], v[184:187], v[196:199], v[114:117]
	s_setprio 1
	s_barrier
	s_add_u32 s74, s72, 0x8000
	s_addc_u32 s75, s73, 0
	s_add_i32 s77, s77, s3
	s_mov_b32 m0, s77
	ds_read_b128 v[188:191], v152 offset:49152
	ds_read_b128 v[196:199], v152 offset:50176
	ds_read_b128 v[200:203], v152 offset:51200
	ds_read_b128 v[204:207], v152 offset:52224
	ds_read_b128 v[208:211], v152 offset:53248
	ds_read_b128 v[212:215], v152 offset:54272
	ds_read_b128 v[216:219], v152 offset:55296
	ds_read_b128 v[220:223], v152 offset:56320
	global_load_lds_dwordx4 v132, s[74:75]
	s_add_i32 m0, s77, 0x2000
	s_add_u32 s72, s72, 0xc000
	v_lshl_add_u64 v[224:225], s[74:75], 0, v[136:137]
	s_addc_u32 s73, s73, 0
	s_add_i32 s74, s78, s3
	global_load_lds_dwordx4 v[224:225], off
	s_mov_b32 m0, s74
	s_nop 0
	global_load_lds_dwordx4 v132, s[72:73]
	s_add_i32 m0, s74, 0x2000
	s_nop 0
	global_load_lds_dwordx4 v136, s[72:73]
	s_waitcnt vmcnt(6)
	s_waitcnt lgkmcnt(0)
	s_barrier
	s_setprio 0
	s_waitcnt lgkmcnt(0)
	v_mfma_f32_16x16x32_bf16 v[62:65], v[154:157], v[188:191], v[62:65]
	v_mfma_f32_16x16x32_bf16 v[62:65], v[158:161], v[196:199], v[62:65]
	v_mfma_f32_16x16x32_bf16 v[46:49], v[154:157], v[200:203], v[46:49]
	v_mfma_f32_16x16x32_bf16 v[46:49], v[158:161], v[204:207], v[46:49]
	v_mfma_f32_16x16x32_bf16 v[30:33], v[154:157], v[208:211], v[30:33]
	v_mfma_f32_16x16x32_bf16 v[30:33], v[158:161], v[212:215], v[30:33]
	v_mfma_f32_16x16x32_bf16 v[14:17], v[154:157], v[216:219], v[14:17]
	v_mfma_f32_16x16x32_bf16 v[14:17], v[158:161], v[220:223], v[14:17]
	v_mfma_f32_16x16x32_bf16 v[6:9], v[162:165], v[216:219], v[6:9]
	v_mfma_f32_16x16x32_bf16 v[6:9], v[166:169], v[220:223], v[6:9]
	v_mfma_f32_16x16x32_bf16 v[22:25], v[162:165], v[208:211], v[22:25]
	v_mfma_f32_16x16x32_bf16 v[22:25], v[166:169], v[212:215], v[22:25]
	v_mfma_f32_16x16x32_bf16 v[38:41], v[162:165], v[200:203], v[38:41]
	v_mfma_f32_16x16x32_bf16 v[38:41], v[166:169], v[204:207], v[38:41]
	v_mfma_f32_16x16x32_bf16 v[54:57], v[162:165], v[188:191], v[54:57]
	v_mfma_f32_16x16x32_bf16 v[54:57], v[166:169], v[196:199], v[54:57]
	v_mfma_f32_16x16x32_bf16 v[58:61], v[170:173], v[188:191], v[58:61]
	v_mfma_f32_16x16x32_bf16 v[58:61], v[174:177], v[196:199], v[58:61]
	v_mfma_f32_16x16x32_bf16 v[42:45], v[170:173], v[200:203], v[42:45]
	v_mfma_f32_16x16x32_bf16 v[42:45], v[174:177], v[204:207], v[42:45]
	v_mfma_f32_16x16x32_bf16 v[26:29], v[170:173], v[208:211], v[26:29]
	v_mfma_f32_16x16x32_bf16 v[26:29], v[174:177], v[212:215], v[26:29]
	v_mfma_f32_16x16x32_bf16 v[10:13], v[170:173], v[216:219], v[10:13]
	v_mfma_f32_16x16x32_bf16 v[10:13], v[174:177], v[220:223], v[10:13]
	v_mfma_f32_16x16x32_bf16 v[2:5], v[180:183], v[216:219], v[2:5]
	v_mfma_f32_16x16x32_bf16 v[2:5], v[184:187], v[220:223], v[2:5]
	v_mfma_f32_16x16x32_bf16 v[18:21], v[180:183], v[208:211], v[18:21]
	v_mfma_f32_16x16x32_bf16 v[18:21], v[184:187], v[212:215], v[18:21]
	v_mfma_f32_16x16x32_bf16 v[34:37], v[180:183], v[200:203], v[34:37]
	v_mfma_f32_16x16x32_bf16 v[34:37], v[184:187], v[204:207], v[34:37]
	v_mfma_f32_16x16x32_bf16 v[50:53], v[180:183], v[188:191], v[50:53]
	v_mfma_f32_16x16x32_bf16 v[50:53], v[184:187], v[196:199], v[50:53]
	s_setprio 1
	s_barrier
	s_add_i32 s76, s76, 2
	s_add_u32 s48, s48, 0x10000
	s_addc_u32 s49, s49, 0
	s_add_u32 s68, s68, 0x10000
	s_addc_u32 s69, s69, 0
	s_cmp_gt_u32 s76, 61
	s_cbranch_scc0 .LBB0_115
	s_setprio 0
	s_and_b64 vcc, exec, s[14:15]
	s_cbranch_vccz .LBB0_118
	s_barrier

; #define PG8_STAGE(bufoff, gbase, voff) do { _Pragma("unroll") for (int _i = 0; _i < 2; ++_i) \
;         __builtin_amdgcn_global_load_lds((const unsigned*)((const char*)(gbase) + (voff)[_i]), (PG8_LAS unsigned*)(lds + (bufoff) + ldsw + _i * 8192), 16, 0, 0); } while (0)
; #define PG8_LDA(dst, b, h) do { _Pragma("unroll") for (int m = 0; m < 4; ++m) _Pragma("unroll") for (int k = 0; k < 2; ++k) dst[m][k] = *(const PG8_LAS bf16x8*)(lds + PG8_SA(b, h) + aoff + m * 2048 + k * 1024); } while (0)
; #define PG8_LDB(dst, b, h) do { _Pragma("unroll") for (int n = 0; n < 2; ++n) _Pragma("unroll") for (int k = 0; k < 2; ++k) dst[n][k] = *(const PG8_LAS bf16x8*)(lds + PG8_SB(b, h) + boff + n * 2048 + k * 1024); } while (0)
; template <class Epi, class Sched, bool ALIGN_EPI = false, bool SP2 = false>
; __device__ __forceinline__ void gemm_phase(PG8_LAS unsigned char* lds, const Gemm g, const Sched& S, const Epi& E) {
;     ...
;         for (; t < tend; t += 2) {
;             const bool last = (t == nt - 2);
;             const char* a1 = cA + (size_t)(t + 1) * kstep;
;             const char* a2 = last ? nA : cA + (size_t)(t + 2) * kstep; const char* b2 = last ? nB : cB + (size_t)(t + 2) * kstep;
;             const char* a3 = a2 + kstep; const char* b3 = b2 + kstep;
;             if (last && has_next) S.a_ready(nxt);
;             if constexpr (SP2) {
;             PG8_LDB(B0, 0, 0); PG8_LDB(B1, 0, 1); PG8_SCHED; PG8_LDA(At, 0, 0); PG8_STAGE(PG8_SA(1, 1), a1 + hstep, voffA);
;             PG8_WAIT_V(8); PG8_WAIT_L(0); PG8_BAR; PG8_MMA(0, 0, At, B0); PG8_MMA(0, 1, At, B1); PG8_BAR; PG8_SCHED;
;             PG8_LDA(At, 0, 1); PG8_STAGE(PG8_SB(0, 0), b2, voffB); PG8_STAGE(PG8_SB(0, 1), b2 + hstep, voffB); PG8_STAGE(PG8_SA(0, 0), a2, voffA);
;             PG8_WAIT_V(8); PG8_WAIT_L(0); PG8_BAR; PG8_MMA(1, 0, At, B0); PG8_MMA(1, 1, At, B1); PG8_BAR; PG8_SCHED;
;             PG8_LDB(B0, 1, 0); PG8_LDB(B1, 1, 1); PG8_SCHED; PG8_LDA(At, 1, 0); PG8_STAGE(PG8_SA(0, 1), a2 + hstep, voffA);
;             PG8_WAIT_V(8); PG8_WAIT_L(0); PG8_BAR; PG8_MMA(0, 0, At, B0); PG8_MMA(0, 1, At, B1); PG8_BAR; PG8_SCHED;
;             PG8_LDA(At, 1, 1); PG8_STAGE(PG8_SB(1, 0), b3, voffB); PG8_STAGE(PG8_SB(1, 1), b3 + hstep, voffB); PG8_STAGE(PG8_SA(1, 0), a3, voffA);
;             PG8_WAIT_V(8); PG8_WAIT_L(0); PG8_BAR; PG8_MMA(1, 0, At, B0); PG8_MMA(1, 1, At, B1); PG8_BAR; PG8_SCHED;
.LBB0_200:
	ds_read_b128 v[148:151], v154
	ds_read_b128 v[158:161], v154 offset:1024
	ds_read_b128 v[162:165], v154 offset:2048
	ds_read_b128 v[166:169], v154 offset:3072
	ds_read_b128 v[170:173], v155
	ds_read_b128 v[174:177], v155 offset:1024
	ds_read_b128 v[180:183], v155 offset:2048
	ds_read_b128 v[184:187], v155 offset:3072
	s_add_u32 s46, s44, 0x4000
	s_addc_u32 s47, s45, 0
	s_cmpk_eq_i32 s76, 0xa8
	s_cselect_b32 s50, s6, s46
	s_cselect_b32 s51, s7, s47
	s_cselect_b32 s48, s24, s74
	s_cselect_b32 s49, s25, s75
	s_add_u32 s46, s50, 0x8000
	s_addc_u32 s47, s51, 0
	s_sub_u32 s46, s44, 0x4000
	s_subb_u32 s47, s45, 0
	s_mov_b32 m0, s57
	s_nop 0
	global_load_lds_dwordx4 v130, s[46:47]
	s_mov_b32 m0, s58
	s_nop 0
	global_load_lds_dwordx4 v134, s[46:47]
	s_add_i32 m0, s26, 0xc000
	ds_read_b128 v[188:191], v156
	ds_read_b128 v[196:199], v156 offset:1024
	ds_read_b128 v[200:203], v156 offset:2048
	ds_read_b128 v[204:207], v156 offset:3072
	ds_read_b128 v[208:211], v156 offset:4096
	ds_read_b128 v[212:215], v156 offset:5120
	ds_read_b128 v[216:219], v156 offset:6144
	ds_read_b128 v[220:223], v156 offset:7168
	global_load_lds_dwordx4 v140, s[44:45]
	s_add_i32 m0, s26, 0xe000
	s_nop 0
	global_load_lds_dwordx4 v142, s[44:45]
	s_waitcnt vmcnt(8)
	s_waitcnt lgkmcnt(0)
	s_barrier
	s_setprio 0
	s_waitcnt lgkmcnt(0)
	v_mfma_f32_16x16x32_bf16 v[126:129], v[148:151], v[188:191], v[126:129]
	v_mfma_f32_16x16x32_bf16 v[126:129], v[158:161], v[196:199], v[126:129]
	v_mfma_f32_16x16x32_bf16 v[110:113], v[148:151], v[200:203], v[110:113]
	v_mfma_f32_16x16x32_bf16 v[110:113], v[158:161], v[204:207], v[110:113]
	v_mfma_f32_16x16x32_bf16 v[94:97], v[148:151], v[208:211], v[94:97]
	v_mfma_f32_16x16x32_bf16 v[94:97], v[158:161], v[212:215], v[94:97]
	v_mfma_f32_16x16x32_bf16 v[78:81], v[148:151], v[216:219], v[78:81]
	v_mfma_f32_16x16x32_bf16 v[78:81], v[158:161], v[220:223], v[78:81]
	v_mfma_f32_16x16x32_bf16 v[74:77], v[162:165], v[216:219], v[74:77]
	v_mfma_f32_16x16x32_bf16 v[74:77], v[166:169], v[220:223], v[74:77]
	v_mfma_f32_16x16x32_bf16 v[90:93], v[162:165], v[208:211], v[90:93]
	v_mfma_f32_16x16x32_bf16 v[90:93], v[166:169], v[212:215], v[90:93]
	v_mfma_f32_16x16x32_bf16 v[106:109], v[162:165], v[200:203], v[106:109]
	v_mfma_f32_16x16x32_bf16 v[106:109], v[166:169], v[204:207], v[106:109]
	v_mfma_f32_16x16x32_bf16 v[122:125], v[162:165], v[188:191], v[122:125]
	v_mfma_f32_16x16x32_bf16 v[122:125], v[166:169], v[196:199], v[122:125]
	v_mfma_f32_16x16x32_bf16 v[118:121], v[170:173], v[188:191], v[118:121]
	v_mfma_f32_16x16x32_bf16 v[118:121], v[174:177], v[196:199], v[118:121]
	v_mfma_f32_16x16x32_bf16 v[102:105], v[170:173], v[200:203], v[102:105]
	v_mfma_f32_16x16x32_bf16 v[102:105], v[174:177], v[204:207], v[102:105]
	v_mfma_f32_16x16x32_bf16 v[86:89], v[170:173], v[208:211], v[86:89]
	v_mfma_f32_16x16x32_bf16 v[86:89], v[174:177], v[212:215], v[86:89]
	v_mfma_f32_16x16x32_bf16 v[70:73], v[170:173], v[216:219], v[70:73]
	v_mfma_f32_16x16x32_bf16 v[70:73], v[174:177], v[220:223], v[70:73]
	v_mfma_f32_16x16x32_bf16 v[66:69], v[180:183], v[216:219], v[66:69]
	v_mfma_f32_16x16x32_bf16 v[66:69], v[184:187], v[220:223], v[66:69]
	v_mfma_f32_16x16x32_bf16 v[82:85], v[180:183], v[208:211], v[82:85]
	v_mfma_f32_16x16x32_bf16 v[82:85], v[184:187], v[212:215], v[82:85]
	v_mfma_f32_16x16x32_bf16 v[98:101], v[180:183], v[200:203], v[98:101]
	v_mfma_f32_16x16x32_bf16 v[98:101], v[184:187], v[204:207], v[98:101]
	v_mfma_f32_16x16x32_bf16 v[114:117], v[180:183], v[188:191], v[114:117]
	v_mfma_f32_16x16x32_bf16 v[114:117], v[184:187], v[196:199], v[114:117]
	s_setprio 1
	s_barrier
	s_add_i32 s77, s59, s3
	s_mov_b32 m0, s77
	ds_read_b128 v[188:191], v156 offset:16384
	ds_read_b128 v[196:199], v156 offset:17408
	ds_read_b128 v[200:203], v156 offset:18432
	ds_read_b128 v[204:207], v156 offset:19456
	ds_read_b128 v[208:211], v156 offset:20480
	ds_read_b128 v[212:215], v156 offset:21504
	ds_read_b128 v[216:219], v156 offset:22528
	ds_read_b128 v[220:223], v156 offset:23552
	global_load_lds_dwordx4 v132, s[48:49]
	s_add_i32 m0, s77, 0x2000
	s_add_u32 s78, s48, 0x4000
	s_addc_u32 s79, s49, 0
	s_add_i32 s77, s61, s3
	global_load_lds_dwordx4 v136, s[48:49]
	s_mov_b32 m0, s77
	s_nop 0
	global_load_lds_dwordx4 v132, s[78:79]
	s_add_i32 m0, s77, 0x2000
	s_nop 0
	global_load_lds_dwordx4 v136, s[78:79]
	s_waitcnt vmcnt(6)
	s_waitcnt lgkmcnt(0)
	s_barrier
	s_setprio 0
	s_waitcnt lgkmcnt(0)
	v_mfma_f32_16x16x32_bf16 v[62:65], v[148:151], v[188:191], v[62:65]
	v_mfma_f32_16x16x32_bf16 v[62:65], v[158:161], v[196:199], v[62:65]
	v_mfma_f32_16x16x32_bf16 v[46:49], v[148:151], v[200:203], v[46:49]
	v_mfma_f32_16x16x32_bf16 v[46:49], v[158:161], v[204:207], v[46:49]
	v_mfma_f32_16x16x32_bf16 v[30:33], v[148:151], v[208:211], v[30:33]
	v_mfma_f32_16x16x32_bf16 v[30:33], v[158:161], v[212:215], v[30:33]
	v_mfma_f32_16x16x32_bf16 v[14:17], v[148:151], v[216:219], v[14:17]
	v_mfma_f32_16x16x32_bf16 v[14:17], v[158:161], v[220:223], v[14:17]
	v_mfma_f32_16x16x32_bf16 v[10:13], v[162:165], v[216:219], v[10:13]
	v_mfma_f32_16x16x32_bf16 v[10:13], v[166:169], v[220:223], v[10:13]
	v_mfma_f32_16x16x32_bf16 v[26:29], v[162:165], v[208:211], v[26:29]
	v_mfma_f32_16x16x32_bf16 v[26:29], v[166:169], v[212:215], v[26:29]
	v_mfma_f32_16x16x32_bf16 v[42:45], v[162:165], v[200:203], v[42:45]
	v_mfma_f32_16x16x32_bf16 v[42:45], v[166:169], v[204:207], v[42:45]
	v_mfma_f32_16x16x32_bf16 v[58:61], v[162:165], v[188:191], v[58:61]
	v_mfma_f32_16x16x32_bf16 v[58:61], v[166:169], v[196:199], v[58:61]
	v_mfma_f32_16x16x32_bf16 v[54:57], v[170:173], v[188:191], v[54:57]
	v_mfma_f32_16x16x32_bf16 v[54:57], v[174:177], v[196:199], v[54:57]
	v_mfma_f32_16x16x32_bf16 v[38:41], v[170:173], v[200:203], v[38:41]
	v_mfma_f32_16x16x32_bf16 v[38:41], v[174:177], v[204:207], v[38:41]
	v_mfma_f32_16x16x32_bf16 v[22:25], v[170:173], v[208:211], v[22:25]
	v_mfma_f32_16x16x32_bf16 v[22:25], v[174:177], v[212:215], v[22:25]
	v_mfma_f32_16x16x32_bf16 v[6:9], v[170:173], v[216:219], v[6:9]
	v_mfma_f32_16x16x32_bf16 v[6:9], v[174:177], v[220:223], v[6:9]
	v_mfma_f32_16x16x32_bf16 v[2:5], v[180:183], v[216:219], v[2:5]
	v_mfma_f32_16x16x32_bf16 v[2:5], v[184:187], v[220:223], v[2:5]
	v_mfma_f32_16x16x32_bf16 v[18:21], v[180:183], v[208:211], v[18:21]
	v_mfma_f32_16x16x32_bf16 v[18:21], v[184:187], v[212:215], v[18:21]
	v_mfma_f32_16x16x32_bf16 v[34:37], v[180:183], v[200:203], v[34:37]
	v_mfma_f32_16x16x32_bf16 v[34:37], v[184:187], v[204:207], v[34:37]
	v_mfma_f32_16x16x32_bf16 v[50:53], v[180:183], v[188:191], v[50:53]
	v_mfma_f32_16x16x32_bf16 v[50:53], v[184:187], v[196:199], v[50:53]
	s_setprio 1
	s_barrier
; #define PG8_STAGE(bufoff, gbase, voff) do { _Pragma("unroll") for (int _i = 0; _i < 2; ++_i) \
;         __builtin_amdgcn_global_load_lds((const unsigned*)((const char*)(gbase) + (voff)[_i]), (PG8_LAS unsigned*)(lds + (bufoff) + ldsw + _i * 8192), 16, 0, 0); } while (0)
; #define PG8_LDA(dst, b, h) do { _Pragma("unroll") for (int m = 0; m < 4; ++m) _Pragma("unroll") for (int k = 0; k < 2; ++k) dst[m][k] = *(const PG8_LAS bf16x8*)(lds + PG8_SA(b, h) + aoff + m * 2048 + k * 1024); } while (0)
; #define PG8_LDB(dst, b, h) do { _Pragma("unroll") for (int n = 0; n < 2; ++n) _Pragma("unroll") for (int k = 0; k < 2; ++k) dst[n][k] = *(const PG8_LAS bf16x8*)(lds + PG8_SB(b, h) + boff + n * 2048 + k * 1024); } while (0)
; template <class Epi, class Sched, bool ALIGN_EPI = false, bool SP2 = false>
; __device__ __forceinline__ void gemm_phase(PG8_LAS unsigned char* lds, const Gemm g, const Sched& S, const Epi& E) {
;     ...
;         for (; t < tend; t += 2) {
;             const bool last = (t == nt - 2);
;             const char* a1 = cA + (size_t)(t + 1) * kstep;
;             const char* a2 = last ? nA : cA + (size_t)(t + 2) * kstep; const char* b2 = last ? nB : cB + (size_t)(t + 2) * kstep;
;             const char* a3 = a2 + kstep; const char* b3 = b2 + kstep;
;             if (last && has_next) S.a_ready(nxt);
;             if constexpr (SP2) {
;             PG8_LDB(B0, 0, 0); PG8_LDB(B1, 0, 1); PG8_SCHED; PG8_LDA(At, 0, 0); PG8_STAGE(PG8_SA(1, 1), a1 + hstep, voffA);
;             PG8_WAIT_V(8); PG8_WAIT_L(0); PG8_BAR; PG8_MMA(0, 0, At, B0); PG8_MMA(0, 1, At, B1); PG8_BAR; PG8_SCHED;
;             PG8_LDA(At, 0, 1); PG8_STAGE(PG8_SB(0, 0), b2, voffB); PG8_STAGE(PG8_SB(0, 1), b2 + hstep, voffB); PG8_STAGE(PG8_SA(0, 0), a2, voffA);
;             PG8_WAIT_V(8); PG8_WAIT_L(0); PG8_BAR; PG8_MMA(1, 0, At, B0); PG8_MMA(1, 1, At, B1); PG8_BAR; PG8_SCHED;
;             PG8_LDB(B0, 1, 0); PG8_LDB(B1, 1, 1); PG8_SCHED; PG8_LDA(At, 1, 0); PG8_STAGE(PG8_SA(0, 1), a2 + hstep, voffA);
;             PG8_WAIT_V(8); PG8_WAIT_L(0); PG8_BAR; PG8_MMA(0, 0, At, B0); PG8_MMA(0, 1, At, B1); PG8_BAR; PG8_SCHED;
;             PG8_LDA(At, 1, 1); PG8_STAGE(PG8_SB(1, 0), b3, voffB); PG8_STAGE(PG8_SB(1, 1), b3 + hstep, voffB); PG8_STAGE(PG8_SA(1, 0), a3, voffA);
;             PG8_WAIT_V(8); PG8_WAIT_L(0); PG8_BAR; PG8_MMA(1, 0, At, B0); PG8_MMA(1, 1, At, B1); PG8_BAR; PG8_SCHED;
	s_add_i32 s77, 0, 0x18000
	v_add_u32_e32 v138, s77, v153
	s_add_i32 s78, 0, 0x1c000
	ds_read_b128 v[148:151], v138
	ds_read_b128 v[158:161], v138 offset:1024
	ds_read_b128 v[162:165], v138 offset:2048
	ds_read_b128 v[166:169], v138 offset:3072
	v_add_u32_e32 v138, s78, v153
	ds_read_b128 v[170:173], v138
	ds_read_b128 v[174:177], v138 offset:1024
	ds_read_b128 v[180:183], v138 offset:2048
	ds_read_b128 v[184:187], v138 offset:3072
	s_mov_b32 m0, s26
	s_nop 0
	global_load_lds_dwordx4 v130, s[50:51]
	s_mov_b32 m0, s27
	s_nop 0
	global_load_lds_dwordx4 v134, s[50:51]
	s_add_u32 s50, s50, 0x4000
	s_addc_u32 s51, s51, 0
	s_mov_b32 m0, s28
	ds_read_b128 v[188:191], v156 offset:32768
	ds_read_b128 v[196:199], v156 offset:33792
	ds_read_b128 v[200:203], v156 offset:34816
	ds_read_b128 v[204:207], v156 offset:35840
	ds_read_b128 v[208:211], v156 offset:36864
	ds_read_b128 v[212:215], v156 offset:37888
	ds_read_b128 v[216:219], v156 offset:38912
	ds_read_b128 v[220:223], v156 offset:39936
	global_load_lds_dwordx4 v130, s[50:51]
	s_mov_b32 m0, s29
	s_nop 0
	global_load_lds_dwordx4 v134, s[50:51]
	s_waitcnt vmcnt(8)
	s_waitcnt lgkmcnt(0)
	s_barrier
	s_setprio 0
	s_waitcnt lgkmcnt(0)
	v_mfma_f32_16x16x32_bf16 v[126:129], v[148:151], v[188:191], v[126:129]
	v_mfma_f32_16x16x32_bf16 v[126:129], v[158:161], v[196:199], v[126:129]
	v_mfma_f32_16x16x32_bf16 v[110:113], v[148:151], v[200:203], v[110:113]
	v_mfma_f32_16x16x32_bf16 v[110:113], v[158:161], v[204:207], v[110:113]
	v_mfma_f32_16x16x32_bf16 v[94:97], v[148:151], v[208:211], v[94:97]
	v_mfma_f32_16x16x32_bf16 v[94:97], v[158:161], v[212:215], v[94:97]
	v_mfma_f32_16x16x32_bf16 v[78:81], v[148:151], v[216:219], v[78:81]
	v_mfma_f32_16x16x32_bf16 v[78:81], v[158:161], v[220:223], v[78:81]
	v_mfma_f32_16x16x32_bf16 v[74:77], v[162:165], v[216:219], v[74:77]
	v_mfma_f32_16x16x32_bf16 v[74:77], v[166:169], v[220:223], v[74:77]
	v_mfma_f32_16x16x32_bf16 v[90:93], v[162:165], v[208:211], v[90:93]
	v_mfma_f32_16x16x32_bf16 v[90:93], v[166:169], v[212:215], v[90:93]
	v_mfma_f32_16x16x32_bf16 v[106:109], v[162:165], v[200:203], v[106:109]
	v_mfma_f32_16x16x32_bf16 v[106:109], v[166:169], v[204:207], v[106:109]
	v_mfma_f32_16x16x32_bf16 v[122:125], v[162:165], v[188:191], v[122:125]
	v_mfma_f32_16x16x32_bf16 v[122:125], v[166:169], v[196:199], v[122:125]
	v_mfma_f32_16x16x32_bf16 v[118:121], v[170:173], v[188:191], v[118:121]
	v_mfma_f32_16x16x32_bf16 v[118:121], v[174:177], v[196:199], v[118:121]
	v_mfma_f32_16x16x32_bf16 v[102:105], v[170:173], v[200:203], v[102:105]
	v_mfma_f32_16x16x32_bf16 v[102:105], v[174:177], v[204:207], v[102:105]
	v_mfma_f32_16x16x32_bf16 v[86:89], v[170:173], v[208:211], v[86:89]
	v_mfma_f32_16x16x32_bf16 v[86:89], v[174:177], v[212:215], v[86:89]
	v_mfma_f32_16x16x32_bf16 v[70:73], v[170:173], v[216:219], v[70:73]
	v_mfma_f32_16x16x32_bf16 v[70:73], v[174:177], v[220:223], v[70:73]
	v_mfma_f32_16x16x32_bf16 v[66:69], v[180:183], v[216:219], v[66:69]
	v_mfma_f32_16x16x32_bf16 v[66:69], v[184:187], v[220:223], v[66:69]
	v_mfma_f32_16x16x32_bf16 v[82:85], v[180:183], v[208:211], v[82:85]
	v_mfma_f32_16x16x32_bf16 v[82:85], v[184:187], v[212:215], v[82:85]
	v_mfma_f32_16x16x32_bf16 v[98:101], v[180:183], v[200:203], v[98:101]
	v_mfma_f32_16x16x32_bf16 v[98:101], v[184:187], v[204:207], v[98:101]
	v_mfma_f32_16x16x32_bf16 v[114:117], v[180:183], v[188:191], v[114:117]
	v_mfma_f32_16x16x32_bf16 v[114:117], v[184:187], v[196:199], v[114:117]
	s_setprio 1
	s_barrier
	s_add_u32 s50, s48, 0x8000
	s_addc_u32 s51, s49, 0
	s_add_i32 s77, s77, s3
	s_mov_b32 m0, s77
	ds_read_b128 v[188:191], v156 offset:49152
	ds_read_b128 v[196:199], v156 offset:50176
	ds_read_b128 v[200:203], v156 offset:51200
	ds_read_b128 v[204:207], v156 offset:52224
	ds_read_b128 v[208:211], v156 offset:53248
	ds_read_b128 v[212:215], v156 offset:54272
	ds_read_b128 v[216:219], v156 offset:55296
	ds_read_b128 v[220:223], v156 offset:56320
	global_load_lds_dwordx4 v132, s[50:51]
	s_add_i32 m0, s77, 0x2000
	s_add_u32 s48, s48, 0xc000
	v_lshl_add_u64 v[224:225], s[50:51], 0, v[136:137]
	s_addc_u32 s49, s49, 0
	s_add_i32 s50, s78, s3
	global_load_lds_dwordx4 v[224:225], off
	s_mov_b32 m0, s50
	s_nop 0
	global_load_lds_dwordx4 v132, s[48:49]
	s_add_i32 m0, s50, 0x2000
	s_nop 0
	global_load_lds_dwordx4 v136, s[48:49]
	s_waitcnt vmcnt(6)
	s_waitcnt lgkmcnt(0)
	s_barrier
	s_setprio 0
	s_waitcnt lgkmcnt(0)
	v_mfma_f32_16x16x32_bf16 v[62:65], v[148:151], v[188:191], v[62:65]
	v_mfma_f32_16x16x32_bf16 v[62:65], v[158:161], v[196:199], v[62:65]
	v_mfma_f32_16x16x32_bf16 v[46:49], v[148:151], v[200:203], v[46:49]
	v_mfma_f32_16x16x32_bf16 v[46:49], v[158:161], v[204:207], v[46:49]
	v_mfma_f32_16x16x32_bf16 v[30:33], v[148:151], v[208:211], v[30:33]
	v_mfma_f32_16x16x32_bf16 v[30:33], v[158:161], v[212:215], v[30:33]
	v_mfma_f32_16x16x32_bf16 v[14:17], v[148:151], v[216:219], v[14:17]
	v_mfma_f32_16x16x32_bf16 v[14:17], v[158:161], v[220:223], v[14:17]
	v_mfma_f32_16x16x32_bf16 v[10:13], v[162:165], v[216:219], v[10:13]
	v_mfma_f32_16x16x32_bf16 v[10:13], v[166:169], v[220:223], v[10:13]
	v_mfma_f32_16x16x32_bf16 v[26:29], v[162:165], v[208:211], v[26:29]
	v_mfma_f32_16x16x32_bf16 v[26:29], v[166:169], v[212:215], v[26:29]
	v_mfma_f32_16x16x32_bf16 v[42:45], v[162:165], v[200:203], v[42:45]
	v_mfma_f32_16x16x32_bf16 v[42:45], v[166:169], v[204:207], v[42:45]
	v_mfma_f32_16x16x32_bf16 v[58:61], v[162:165], v[188:191], v[58:61]
	v_mfma_f32_16x16x32_bf16 v[58:61], v[166:169], v[196:199], v[58:61]
	v_mfma_f32_16x16x32_bf16 v[54:57], v[170:173], v[188:191], v[54:57]
	v_mfma_f32_16x16x32_bf16 v[54:57], v[174:177], v[196:199], v[54:57]
	v_mfma_f32_16x16x32_bf16 v[38:41], v[170:173], v[200:203], v[38:41]
	v_mfma_f32_16x16x32_bf16 v[38:41], v[174:177], v[204:207], v[38:41]
	v_mfma_f32_16x16x32_bf16 v[22:25], v[170:173], v[208:211], v[22:25]
	v_mfma_f32_16x16x32_bf16 v[22:25], v[174:177], v[212:215], v[22:25]
	v_mfma_f32_16x16x32_bf16 v[6:9], v[170:173], v[216:219], v[6:9]
	v_mfma_f32_16x16x32_bf16 v[6:9], v[174:177], v[220:223], v[6:9]
	v_mfma_f32_16x16x32_bf16 v[2:5], v[180:183], v[216:219], v[2:5]
	v_mfma_f32_16x16x32_bf16 v[2:5], v[184:187], v[220:223], v[2:5]
	v_mfma_f32_16x16x32_bf16 v[18:21], v[180:183], v[208:211], v[18:21]
	v_mfma_f32_16x16x32_bf16 v[18:21], v[184:187], v[212:215], v[18:21]
	v_mfma_f32_16x16x32_bf16 v[34:37], v[180:183], v[200:203], v[34:37]
	v_mfma_f32_16x16x32_bf16 v[34:37], v[184:187], v[204:207], v[34:37]
	v_mfma_f32_16x16x32_bf16 v[50:53], v[180:183], v[188:191], v[50:53]
	v_mfma_f32_16x16x32_bf16 v[50:53], v[184:187], v[196:199], v[50:53]
	s_setprio 1
	s_barrier
	s_add_i32 s76, s76, 2
	s_add_u32 s44, s44, 0x10000
	s_addc_u32 s45, s45, 0
	s_add_u32 s74, s74, 0x10000
	s_addc_u32 s75, s75, 0
	s_cmpk_gt_u32 s76, 0xa9
	s_cbranch_scc0 .LBB0_200
	s_setprio 0
	s_and_b64 vcc, exec, s[18:19]
	s_cbranch_vccz .LBB0_203
	s_barrier

; #define PG8_STAGE(bufoff, gbase, voff) do { _Pragma("unroll") for (int _i = 0; _i < 2; ++_i) \
;         __builtin_amdgcn_global_load_lds((const unsigned*)((const char*)(gbase) + (voff)[_i]), (PG8_LAS unsigned*)(lds + (bufoff) + ldsw + _i * 8192), 16, 0, 0); } while (0)
; #define PG8_LDA(dst, b, h) do { _Pragma("unroll") for (int m = 0; m < 4; ++m) _Pragma("unroll") for (int k = 0; k < 2; ++k) dst[m][k] = *(const PG8_LAS bf16x8*)(lds + PG8_SA(b, h) + aoff + m * 2048 + k * 1024); } while (0)
; #define PG8_LDB(dst, b, h) do { _Pragma("unroll") for (int n = 0; n < 2; ++n) _Pragma("unroll") for (int k = 0; k < 2; ++k) dst[n][k] = *(const PG8_LAS bf16x8*)(lds + PG8_SB(b, h) + boff + n * 2048 + k * 1024); } while (0)
; template <class Epi, class Sched, bool ALIGN_EPI = false, bool SP2 = false>
; __device__ __forceinline__ void gemm_phase(PG8_LAS unsigned char* lds, const Gemm g, const Sched& S, const Epi& E) {
;     ...
;         for (; t < tend; t += 2) {
;             const bool last = (t == nt - 2);
;             const char* a1 = cA + (size_t)(t + 1) * kstep;
;             const char* a2 = last ? nA : cA + (size_t)(t + 2) * kstep; const char* b2 = last ? nB : cB + (size_t)(t + 2) * kstep;
;             const char* a3 = a2 + kstep; const char* b3 = b2 + kstep;
;             if (last && has_next) S.a_ready(nxt);
;             if constexpr (SP2) {
;             PG8_LDB(B0, 0, 0); PG8_LDB(B1, 0, 1); PG8_SCHED; PG8_LDA(At, 0, 0); PG8_STAGE(PG8_SA(1, 1), a1 + hstep, voffA);
;             PG8_WAIT_V(8); PG8_WAIT_L(0); PG8_BAR; PG8_MMA(0, 0, At, B0); PG8_MMA(0, 1, At, B1); PG8_BAR; PG8_SCHED;
;             PG8_LDA(At, 0, 1); PG8_STAGE(PG8_SB(0, 0), b2, voffB); PG8_STAGE(PG8_SB(0, 1), b2 + hstep, voffB); PG8_STAGE(PG8_SA(0, 0), a2, voffA);
;             PG8_WAIT_V(8); PG8_WAIT_L(0); PG8_BAR; PG8_MMA(1, 0, At, B0); PG8_MMA(1, 1, At, B1); PG8_BAR; PG8_SCHED;
;             PG8_LDB(B0, 1, 0); PG8_LDB(B1, 1, 1); PG8_SCHED; PG8_LDA(At, 1, 0); PG8_STAGE(PG8_SA(0, 1), a2 + hstep, voffA);
;             PG8_WAIT_V(8); PG8_WAIT_L(0); PG8_BAR; PG8_MMA(0, 0, At, B0); PG8_MMA(0, 1, At, B1); PG8_BAR; PG8_SCHED;
;             PG8_LDA(At, 1, 1); PG8_STAGE(PG8_SB(1, 0), b3, voffB); PG8_STAGE(PG8_SB(1, 1), b3 + hstep, voffB); PG8_STAGE(PG8_SA(1, 0), a3, voffA);
;             PG8_WAIT_V(8); PG8_WAIT_L(0); PG8_BAR; PG8_MMA(1, 0, At, B0); PG8_MMA(1, 1, At, B1); PG8_BAR; PG8_SCHED;
.LBB0_290:
	ds_read_b128 v[146:149], v162
	ds_read_b128 v[150:153], v162 offset:1024
	ds_read_b128 v[154:157], v162 offset:2048
	ds_read_b128 v[168:171], v162 offset:3072
	ds_read_b128 v[172:175], v163
	ds_read_b128 v[180:183], v163 offset:1024
	ds_read_b128 v[184:187], v163 offset:2048
	ds_read_b128 v[188:191], v163 offset:3072
	s_add_u32 s59, s72, 0x4000
	s_addc_u32 s62, s73, 0
	s_cmp_eq_u32 s58, 60
	s_cselect_b32 s78, s19, s59
	s_cselect_b32 s79, s5, s62
	s_cselect_b32 s76, s26, s33
	s_cselect_b32 s77, s17, s56
	s_add_u32 s74, s78, 0x8000
	s_addc_u32 s75, s79, 0
	s_sub_u32 s74, s72, 0x4000
	s_subb_u32 s75, s73, 0
	s_mov_b32 m0, s51
	s_nop 0
	global_load_lds_dwordx4 v130, s[74:75]
	s_mov_b32 m0, s57
	s_nop 0
	global_load_lds_dwordx4 v134, s[74:75]
	s_add_i32 m0, s15, 0xc000
	ds_read_b128 v[198:201], v164
	ds_read_b128 v[202:205], v164 offset:1024
	ds_read_b128 v[206:209], v164 offset:2048
	ds_read_b128 v[210:213], v164 offset:3072
	ds_read_b128 v[214:217], v164 offset:4096
	ds_read_b128 v[218:221], v164 offset:5120
	ds_read_b128 v[222:225], v164 offset:6144
	ds_read_b128 v[226:229], v164 offset:7168
	global_load_lds_dwordx4 v138, s[72:73]
	s_add_i32 m0, s15, 0xe000
	s_nop 0
	global_load_lds_dwordx4 v140, s[72:73]
	s_waitcnt vmcnt(8)
	s_waitcnt lgkmcnt(0)
	s_barrier
	s_setprio 0
	s_waitcnt lgkmcnt(0)
	v_mfma_f32_16x16x32_bf16 v[126:129], v[146:149], v[198:201], v[126:129]
	v_mfma_f32_16x16x32_bf16 v[126:129], v[150:153], v[202:205], v[126:129]
	v_mfma_f32_16x16x32_bf16 v[110:113], v[146:149], v[206:209], v[110:113]
	v_mfma_f32_16x16x32_bf16 v[110:113], v[150:153], v[210:213], v[110:113]
	v_mfma_f32_16x16x32_bf16 v[94:97], v[146:149], v[214:217], v[94:97]
	v_mfma_f32_16x16x32_bf16 v[94:97], v[150:153], v[218:221], v[94:97]
	v_mfma_f32_16x16x32_bf16 v[78:81], v[146:149], v[222:225], v[78:81]
	v_mfma_f32_16x16x32_bf16 v[78:81], v[150:153], v[226:229], v[78:81]
	v_mfma_f32_16x16x32_bf16 v[74:77], v[154:157], v[222:225], v[74:77]
	v_mfma_f32_16x16x32_bf16 v[74:77], v[168:171], v[226:229], v[74:77]
	v_mfma_f32_16x16x32_bf16 v[90:93], v[154:157], v[214:217], v[90:93]
	v_mfma_f32_16x16x32_bf16 v[90:93], v[168:171], v[218:221], v[90:93]
	v_mfma_f32_16x16x32_bf16 v[106:109], v[154:157], v[206:209], v[106:109]
	v_mfma_f32_16x16x32_bf16 v[106:109], v[168:171], v[210:213], v[106:109]
	v_mfma_f32_16x16x32_bf16 v[122:125], v[154:157], v[198:201], v[122:125]
	v_mfma_f32_16x16x32_bf16 v[122:125], v[168:171], v[202:205], v[122:125]
	v_mfma_f32_16x16x32_bf16 v[118:121], v[172:175], v[198:201], v[118:121]
	v_mfma_f32_16x16x32_bf16 v[118:121], v[180:183], v[202:205], v[118:121]
	v_mfma_f32_16x16x32_bf16 v[102:105], v[172:175], v[206:209], v[102:105]
	v_mfma_f32_16x16x32_bf16 v[102:105], v[180:183], v[210:213], v[102:105]
	v_mfma_f32_16x16x32_bf16 v[86:89], v[172:175], v[214:217], v[86:89]
	v_mfma_f32_16x16x32_bf16 v[86:89], v[180:183], v[218:221], v[86:89]
	v_mfma_f32_16x16x32_bf16 v[70:73], v[172:175], v[222:225], v[70:73]
	v_mfma_f32_16x16x32_bf16 v[70:73], v[180:183], v[226:229], v[70:73]
	v_mfma_f32_16x16x32_bf16 v[66:69], v[184:187], v[222:225], v[66:69]
	v_mfma_f32_16x16x32_bf16 v[66:69], v[188:191], v[226:229], v[66:69]
	v_mfma_f32_16x16x32_bf16 v[82:85], v[184:187], v[214:217], v[82:85]
	v_mfma_f32_16x16x32_bf16 v[82:85], v[188:191], v[218:221], v[82:85]
	v_mfma_f32_16x16x32_bf16 v[98:101], v[184:187], v[206:209], v[98:101]
	v_mfma_f32_16x16x32_bf16 v[98:101], v[188:191], v[210:213], v[98:101]
	v_mfma_f32_16x16x32_bf16 v[114:117], v[184:187], v[198:201], v[114:117]
	v_mfma_f32_16x16x32_bf16 v[114:117], v[188:191], v[202:205], v[114:117]
	s_setprio 1
	s_barrier
	s_add_i32 s59, s81, s3
	s_mov_b32 m0, s59
	ds_read_b128 v[198:201], v164 offset:16384
	ds_read_b128 v[202:205], v164 offset:17408
	ds_read_b128 v[206:209], v164 offset:18432
	ds_read_b128 v[210:213], v164 offset:19456
	ds_read_b128 v[214:217], v164 offset:20480
	ds_read_b128 v[218:221], v164 offset:21504
	ds_read_b128 v[222:225], v164 offset:22528
	ds_read_b128 v[226:229], v164 offset:23552
	global_load_lds_dwordx4 v132, s[76:77]
	s_add_i32 m0, s59, 0x2000
	s_add_u32 s62, s76, 0x4000
	s_addc_u32 s63, s77, 0
	s_add_i32 s59, s82, s3
	global_load_lds_dwordx4 v136, s[76:77]
	s_mov_b32 m0, s59
	s_nop 0
	global_load_lds_dwordx4 v132, s[62:63]
	s_add_i32 m0, s59, 0x2000
	s_nop 0
	global_load_lds_dwordx4 v136, s[62:63]
	s_waitcnt vmcnt(6)
	s_waitcnt lgkmcnt(0)
	s_barrier
	s_setprio 0
	s_waitcnt lgkmcnt(0)
	v_mfma_f32_16x16x32_bf16 v[62:65], v[146:149], v[198:201], v[62:65]
	v_mfma_f32_16x16x32_bf16 v[62:65], v[150:153], v[202:205], v[62:65]
	v_mfma_f32_16x16x32_bf16 v[46:49], v[146:149], v[206:209], v[46:49]
	v_mfma_f32_16x16x32_bf16 v[46:49], v[150:153], v[210:213], v[46:49]
	v_mfma_f32_16x16x32_bf16 v[30:33], v[146:149], v[214:217], v[30:33]
	v_mfma_f32_16x16x32_bf16 v[30:33], v[150:153], v[218:221], v[30:33]
	v_mfma_f32_16x16x32_bf16 v[14:17], v[146:149], v[222:225], v[14:17]
	v_mfma_f32_16x16x32_bf16 v[14:17], v[150:153], v[226:229], v[14:17]
	v_mfma_f32_16x16x32_bf16 v[10:13], v[154:157], v[222:225], v[10:13]
	v_mfma_f32_16x16x32_bf16 v[10:13], v[168:171], v[226:229], v[10:13]
	v_mfma_f32_16x16x32_bf16 v[26:29], v[154:157], v[214:217], v[26:29]
	v_mfma_f32_16x16x32_bf16 v[26:29], v[168:171], v[218:221], v[26:29]
	v_mfma_f32_16x16x32_bf16 v[42:45], v[154:157], v[206:209], v[42:45]
	v_mfma_f32_16x16x32_bf16 v[42:45], v[168:171], v[210:213], v[42:45]
	v_mfma_f32_16x16x32_bf16 v[58:61], v[154:157], v[198:201], v[58:61]
	v_mfma_f32_16x16x32_bf16 v[58:61], v[168:171], v[202:205], v[58:61]
	v_mfma_f32_16x16x32_bf16 v[54:57], v[172:175], v[198:201], v[54:57]
	v_mfma_f32_16x16x32_bf16 v[54:57], v[180:183], v[202:205], v[54:57]
	v_mfma_f32_16x16x32_bf16 v[38:41], v[172:175], v[206:209], v[38:41]
	v_mfma_f32_16x16x32_bf16 v[38:41], v[180:183], v[210:213], v[38:41]
	v_mfma_f32_16x16x32_bf16 v[22:25], v[172:175], v[214:217], v[22:25]
	v_mfma_f32_16x16x32_bf16 v[22:25], v[180:183], v[218:221], v[22:25]
	v_mfma_f32_16x16x32_bf16 v[6:9], v[172:175], v[222:225], v[6:9]
	v_mfma_f32_16x16x32_bf16 v[6:9], v[180:183], v[226:229], v[6:9]
	v_mfma_f32_16x16x32_bf16 v[2:5], v[184:187], v[222:225], v[2:5]
	v_mfma_f32_16x16x32_bf16 v[2:5], v[188:191], v[226:229], v[2:5]
	v_mfma_f32_16x16x32_bf16 v[18:21], v[184:187], v[214:217], v[18:21]
	v_mfma_f32_16x16x32_bf16 v[18:21], v[188:191], v[218:221], v[18:21]
	v_mfma_f32_16x16x32_bf16 v[34:37], v[184:187], v[206:209], v[34:37]
	v_mfma_f32_16x16x32_bf16 v[34:37], v[188:191], v[210:213], v[34:37]
	v_mfma_f32_16x16x32_bf16 v[50:53], v[184:187], v[198:201], v[50:53]
	v_mfma_f32_16x16x32_bf16 v[50:53], v[188:191], v[202:205], v[50:53]
	s_setprio 1
	s_barrier
; #define PG8_STAGE(bufoff, gbase, voff) do { _Pragma("unroll") for (int _i = 0; _i < 2; ++_i) \
;         __builtin_amdgcn_global_load_lds((const unsigned*)((const char*)(gbase) + (voff)[_i]), (PG8_LAS unsigned*)(lds + (bufoff) + ldsw + _i * 8192), 16, 0, 0); } while (0)
; #define PG8_LDA(dst, b, h) do { _Pragma("unroll") for (int m = 0; m < 4; ++m) _Pragma("unroll") for (int k = 0; k < 2; ++k) dst[m][k] = *(const PG8_LAS bf16x8*)(lds + PG8_SA(b, h) + aoff + m * 2048 + k * 1024); } while (0)
; #define PG8_LDB(dst, b, h) do { _Pragma("unroll") for (int n = 0; n < 2; ++n) _Pragma("unroll") for (int k = 0; k < 2; ++k) dst[n][k] = *(const PG8_LAS bf16x8*)(lds + PG8_SB(b, h) + boff + n * 2048 + k * 1024); } while (0)
; template <class Epi, class Sched, bool ALIGN_EPI = false, bool SP2 = false>
; __device__ __forceinline__ void gemm_phase(PG8_LAS unsigned char* lds, const Gemm g, const Sched& S, const Epi& E) {
;     ...
;         for (; t < tend; t += 2) {
;             const bool last = (t == nt - 2);
;             const char* a1 = cA + (size_t)(t + 1) * kstep;
;             const char* a2 = last ? nA : cA + (size_t)(t + 2) * kstep; const char* b2 = last ? nB : cB + (size_t)(t + 2) * kstep;
;             const char* a3 = a2 + kstep; const char* b3 = b2 + kstep;
;             if (last && has_next) S.a_ready(nxt);
;             if constexpr (SP2) {
;             PG8_LDB(B0, 0, 0); PG8_LDB(B1, 0, 1); PG8_SCHED; PG8_LDA(At, 0, 0); PG8_STAGE(PG8_SA(1, 1), a1 + hstep, voffA);
;             PG8_WAIT_V(8); PG8_WAIT_L(0); PG8_BAR; PG8_MMA(0, 0, At, B0); PG8_MMA(0, 1, At, B1); PG8_BAR; PG8_SCHED;
;             PG8_LDA(At, 0, 1); PG8_STAGE(PG8_SB(0, 0), b2, voffB); PG8_STAGE(PG8_SB(0, 1), b2 + hstep, voffB); PG8_STAGE(PG8_SA(0, 0), a2, voffA);
;             PG8_WAIT_V(8); PG8_WAIT_L(0); PG8_BAR; PG8_MMA(1, 0, At, B0); PG8_MMA(1, 1, At, B1); PG8_BAR; PG8_SCHED;
;             PG8_LDB(B0, 1, 0); PG8_LDB(B1, 1, 1); PG8_SCHED; PG8_LDA(At, 1, 0); PG8_STAGE(PG8_SA(0, 1), a2 + hstep, voffA);
;             PG8_WAIT_V(8); PG8_WAIT_L(0); PG8_BAR; PG8_MMA(0, 0, At, B0); PG8_MMA(0, 1, At, B1); PG8_BAR; PG8_SCHED;
;             PG8_LDA(At, 1, 1); PG8_STAGE(PG8_SB(1, 0), b3, voffB); PG8_STAGE(PG8_SB(1, 1), b3 + hstep, voffB); PG8_STAGE(PG8_SA(1, 0), a3, voffA);
;             PG8_WAIT_V(8); PG8_WAIT_L(0); PG8_BAR; PG8_MMA(1, 0, At, B0); PG8_MMA(1, 1, At, B1); PG8_BAR; PG8_SCHED;
	s_add_i32 s59, 0, 0x18000
	v_add_u32_e32 v158, s59, v160
	s_add_i32 s64, 0, 0x1c000
	ds_read_b128 v[146:149], v158
	ds_read_b128 v[150:153], v158 offset:1024
	ds_read_b128 v[154:157], v158 offset:2048
	ds_read_b128 v[168:171], v158 offset:3072
	v_add_u32_e32 v158, s64, v160
	ds_read_b128 v[172:175], v158
	ds_read_b128 v[180:183], v158 offset:1024
	ds_read_b128 v[184:187], v158 offset:2048
	ds_read_b128 v[188:191], v158 offset:3072
	s_mov_b32 m0, s15
	s_nop 0
	global_load_lds_dwordx4 v130, s[78:79]
	s_mov_b32 m0, s27
	s_nop 0
	global_load_lds_dwordx4 v134, s[78:79]
	s_add_u32 s62, s78, 0x4000
	s_addc_u32 s63, s79, 0
	s_mov_b32 m0, s28
	ds_read_b128 v[198:201], v164 offset:32768
	ds_read_b128 v[202:205], v164 offset:33792
	ds_read_b128 v[206:209], v164 offset:34816
	ds_read_b128 v[210:213], v164 offset:35840
	ds_read_b128 v[214:217], v164 offset:36864
	ds_read_b128 v[218:221], v164 offset:37888
	ds_read_b128 v[222:225], v164 offset:38912
	ds_read_b128 v[226:229], v164 offset:39936
	global_load_lds_dwordx4 v130, s[62:63]
	s_mov_b32 m0, s29
	s_nop 0
	global_load_lds_dwordx4 v134, s[62:63]
	s_waitcnt vmcnt(8)
	s_waitcnt lgkmcnt(0)
	s_barrier
	s_setprio 0
	s_waitcnt lgkmcnt(0)
	v_mfma_f32_16x16x32_bf16 v[126:129], v[146:149], v[198:201], v[126:129]
	v_mfma_f32_16x16x32_bf16 v[126:129], v[150:153], v[202:205], v[126:129]
	v_mfma_f32_16x16x32_bf16 v[110:113], v[146:149], v[206:209], v[110:113]
	v_mfma_f32_16x16x32_bf16 v[110:113], v[150:153], v[210:213], v[110:113]
	v_mfma_f32_16x16x32_bf16 v[94:97], v[146:149], v[214:217], v[94:97]
	v_mfma_f32_16x16x32_bf16 v[94:97], v[150:153], v[218:221], v[94:97]
	v_mfma_f32_16x16x32_bf16 v[78:81], v[146:149], v[222:225], v[78:81]
	v_mfma_f32_16x16x32_bf16 v[78:81], v[150:153], v[226:229], v[78:81]
	v_mfma_f32_16x16x32_bf16 v[74:77], v[154:157], v[222:225], v[74:77]
	v_mfma_f32_16x16x32_bf16 v[74:77], v[168:171], v[226:229], v[74:77]
	v_mfma_f32_16x16x32_bf16 v[90:93], v[154:157], v[214:217], v[90:93]
	v_mfma_f32_16x16x32_bf16 v[90:93], v[168:171], v[218:221], v[90:93]
	v_mfma_f32_16x16x32_bf16 v[106:109], v[154:157], v[206:209], v[106:109]
	v_mfma_f32_16x16x32_bf16 v[106:109], v[168:171], v[210:213], v[106:109]
	v_mfma_f32_16x16x32_bf16 v[122:125], v[154:157], v[198:201], v[122:125]
	v_mfma_f32_16x16x32_bf16 v[122:125], v[168:171], v[202:205], v[122:125]
	v_mfma_f32_16x16x32_bf16 v[118:121], v[172:175], v[198:201], v[118:121]
	v_mfma_f32_16x16x32_bf16 v[118:121], v[180:183], v[202:205], v[118:121]
	v_mfma_f32_16x16x32_bf16 v[102:105], v[172:175], v[206:209], v[102:105]
	v_mfma_f32_16x16x32_bf16 v[102:105], v[180:183], v[210:213], v[102:105]
	v_mfma_f32_16x16x32_bf16 v[86:89], v[172:175], v[214:217], v[86:89]
	v_mfma_f32_16x16x32_bf16 v[86:89], v[180:183], v[218:221], v[86:89]
	v_mfma_f32_16x16x32_bf16 v[70:73], v[172:175], v[222:225], v[70:73]
	v_mfma_f32_16x16x32_bf16 v[70:73], v[180:183], v[226:229], v[70:73]
	v_mfma_f32_16x16x32_bf16 v[66:69], v[184:187], v[222:225], v[66:69]
	v_mfma_f32_16x16x32_bf16 v[66:69], v[188:191], v[226:229], v[66:69]
	v_mfma_f32_16x16x32_bf16 v[82:85], v[184:187], v[214:217], v[82:85]
	v_mfma_f32_16x16x32_bf16 v[82:85], v[188:191], v[218:221], v[82:85]
	v_mfma_f32_16x16x32_bf16 v[98:101], v[184:187], v[206:209], v[98:101]
	v_mfma_f32_16x16x32_bf16 v[98:101], v[188:191], v[210:213], v[98:101]
	v_mfma_f32_16x16x32_bf16 v[114:117], v[184:187], v[198:201], v[114:117]
	v_mfma_f32_16x16x32_bf16 v[114:117], v[188:191], v[202:205], v[114:117]
	s_setprio 1
	s_barrier
	s_add_u32 s62, s76, 0x8000
	s_addc_u32 s63, s77, 0
	s_add_i32 s59, s59, s3
	s_mov_b32 m0, s59
	ds_read_b128 v[198:201], v164 offset:49152
	ds_read_b128 v[202:205], v164 offset:50176
	ds_read_b128 v[206:209], v164 offset:51200
	ds_read_b128 v[210:213], v164 offset:52224
	ds_read_b128 v[214:217], v164 offset:53248
	ds_read_b128 v[218:221], v164 offset:54272
	ds_read_b128 v[222:225], v164 offset:55296
	ds_read_b128 v[226:229], v164 offset:56320
	global_load_lds_dwordx4 v132, s[62:63]
	s_add_i32 m0, s59, 0x2000
	v_lshl_add_u64 v[158:159], s[62:63], 0, v[136:137]
	s_add_u32 s62, s76, 0xc000
	s_addc_u32 s63, s77, 0
	s_add_i32 s59, s64, s3
	global_load_lds_dwordx4 v[158:159], off
	s_mov_b32 m0, s59
	s_nop 0
	global_load_lds_dwordx4 v132, s[62:63]
	s_add_i32 m0, s59, 0x2000
	s_nop 0
	global_load_lds_dwordx4 v136, s[62:63]
	s_waitcnt vmcnt(6)
	s_waitcnt lgkmcnt(0)
	s_barrier
	s_setprio 0
	s_waitcnt lgkmcnt(0)
	v_mfma_f32_16x16x32_bf16 v[62:65], v[146:149], v[198:201], v[62:65]
	v_mfma_f32_16x16x32_bf16 v[62:65], v[150:153], v[202:205], v[62:65]
	v_mfma_f32_16x16x32_bf16 v[46:49], v[146:149], v[206:209], v[46:49]
	v_mfma_f32_16x16x32_bf16 v[46:49], v[150:153], v[210:213], v[46:49]
	v_mfma_f32_16x16x32_bf16 v[30:33], v[146:149], v[214:217], v[30:33]
	v_mfma_f32_16x16x32_bf16 v[30:33], v[150:153], v[218:221], v[30:33]
	v_mfma_f32_16x16x32_bf16 v[14:17], v[146:149], v[222:225], v[14:17]
	v_mfma_f32_16x16x32_bf16 v[14:17], v[150:153], v[226:229], v[14:17]
	v_mfma_f32_16x16x32_bf16 v[10:13], v[154:157], v[222:225], v[10:13]
	v_mfma_f32_16x16x32_bf16 v[10:13], v[168:171], v[226:229], v[10:13]
	v_mfma_f32_16x16x32_bf16 v[26:29], v[154:157], v[214:217], v[26:29]
	v_mfma_f32_16x16x32_bf16 v[26:29], v[168:171], v[218:221], v[26:29]
	v_mfma_f32_16x16x32_bf16 v[42:45], v[154:157], v[206:209], v[42:45]
	v_mfma_f32_16x16x32_bf16 v[42:45], v[168:171], v[210:213], v[42:45]
	v_mfma_f32_16x16x32_bf16 v[58:61], v[154:157], v[198:201], v[58:61]
	v_mfma_f32_16x16x32_bf16 v[58:61], v[168:171], v[202:205], v[58:61]
	v_mfma_f32_16x16x32_bf16 v[54:57], v[172:175], v[198:201], v[54:57]
	v_mfma_f32_16x16x32_bf16 v[54:57], v[180:183], v[202:205], v[54:57]
	v_mfma_f32_16x16x32_bf16 v[38:41], v[172:175], v[206:209], v[38:41]
	v_mfma_f32_16x16x32_bf16 v[38:41], v[180:183], v[210:213], v[38:41]
	v_mfma_f32_16x16x32_bf16 v[22:25], v[172:175], v[214:217], v[22:25]
	v_mfma_f32_16x16x32_bf16 v[22:25], v[180:183], v[218:221], v[22:25]
	v_mfma_f32_16x16x32_bf16 v[6:9], v[172:175], v[222:225], v[6:9]
	v_mfma_f32_16x16x32_bf16 v[6:9], v[180:183], v[226:229], v[6:9]
	v_mfma_f32_16x16x32_bf16 v[2:5], v[184:187], v[222:225], v[2:5]
	v_mfma_f32_16x16x32_bf16 v[2:5], v[188:191], v[226:229], v[2:5]
	v_mfma_f32_16x16x32_bf16 v[18:21], v[184:187], v[214:217], v[18:21]
	v_mfma_f32_16x16x32_bf16 v[18:21], v[188:191], v[218:221], v[18:21]
	v_mfma_f32_16x16x32_bf16 v[34:37], v[184:187], v[206:209], v[34:37]
	v_mfma_f32_16x16x32_bf16 v[34:37], v[188:191], v[210:213], v[34:37]
	v_mfma_f32_16x16x32_bf16 v[50:53], v[184:187], v[198:201], v[50:53]
	v_mfma_f32_16x16x32_bf16 v[50:53], v[188:191], v[202:205], v[50:53]
	s_setprio 1
	s_barrier
	s_add_i32 s58, s58, 2
	s_add_u32 s72, s72, 0x10000
	s_addc_u32 s73, s73, 0
	s_add_u32 s33, s33, 0x10000
	s_addc_u32 s56, s56, 0
	s_cmp_gt_u32 s58, 61
	s_cbranch_scc0 .LBB0_290
	s_setprio 0
	s_and_b64 vcc, exec, s[12:13]
	s_cbranch_vccz .LBB0_293
	s_barrier

; #define PG8_STAGE(bufoff, gbase, voff) do { _Pragma("unroll") for (int _i = 0; _i < 2; ++_i) \
;         __builtin_amdgcn_global_load_lds((const unsigned*)((const char*)(gbase) + (voff)[_i]), (PG8_LAS unsigned*)(lds + (bufoff) + ldsw + _i * 8192), 16, 0, 0); } while (0)
; #define PG8_LDA(dst, b, h) do { _Pragma("unroll") for (int m = 0; m < 4; ++m) _Pragma("unroll") for (int k = 0; k < 2; ++k) dst[m][k] = *(const PG8_LAS bf16x8*)(lds + PG8_SA(b, h) + aoff + m * 2048 + k * 1024); } while (0)
; #define PG8_LDB(dst, b, h) do { _Pragma("unroll") for (int n = 0; n < 2; ++n) _Pragma("unroll") for (int k = 0; k < 2; ++k) dst[n][k] = *(const PG8_LAS bf16x8*)(lds + PG8_SB(b, h) + boff + n * 2048 + k * 1024); } while (0)
; template <class Epi, class Sched, bool ALIGN_EPI = false, bool SP2 = false>
; __device__ __forceinline__ void gemm_phase(PG8_LAS unsigned char* lds, const Gemm g, const Sched& S, const Epi& E) {
;     ...
;         for (; t < tend; t += 2) {
;             const bool last = (t == nt - 2);
;             const char* a1 = cA + (size_t)(t + 1) * kstep;
;             const char* a2 = last ? nA : cA + (size_t)(t + 2) * kstep; const char* b2 = last ? nB : cB + (size_t)(t + 2) * kstep;
;             const char* a3 = a2 + kstep; const char* b3 = b2 + kstep;
;             if (last && has_next) S.a_ready(nxt);
;             if constexpr (SP2) {
;             PG8_LDB(B0, 0, 0); PG8_LDB(B1, 0, 1); PG8_SCHED; PG8_LDA(At, 0, 0); PG8_STAGE(PG8_SA(1, 1), a1 + hstep, voffA);
;             PG8_WAIT_V(8); PG8_WAIT_L(0); PG8_BAR; PG8_MMA(0, 0, At, B0); PG8_MMA(0, 1, At, B1); PG8_BAR; PG8_SCHED;
;             PG8_LDA(At, 0, 1); PG8_STAGE(PG8_SB(0, 0), b2, voffB); PG8_STAGE(PG8_SB(0, 1), b2 + hstep, voffB); PG8_STAGE(PG8_SA(0, 0), a2, voffA);
;             PG8_WAIT_V(8); PG8_WAIT_L(0); PG8_BAR; PG8_MMA(1, 0, At, B0); PG8_MMA(1, 1, At, B1); PG8_BAR; PG8_SCHED;
;             PG8_LDB(B0, 1, 0); PG8_LDB(B1, 1, 1); PG8_SCHED; PG8_LDA(At, 1, 0); PG8_STAGE(PG8_SA(0, 1), a2 + hstep, voffA);
;             PG8_WAIT_V(8); PG8_WAIT_L(0); PG8_BAR; PG8_MMA(0, 0, At, B0); PG8_MMA(0, 1, At, B1); PG8_BAR; PG8_SCHED;
;             PG8_LDA(At, 1, 1); PG8_STAGE(PG8_SB(1, 0), b3, voffB); PG8_STAGE(PG8_SB(1, 1), b3 + hstep, voffB); PG8_STAGE(PG8_SA(1, 0), a3, voffA);
;             PG8_WAIT_V(8); PG8_WAIT_L(0); PG8_BAR; PG8_MMA(1, 0, At, B0); PG8_MMA(1, 1, At, B1); PG8_BAR; PG8_SCHED;
.LBB0_682:
	ds_read_b128 v[166:169], v163
	ds_read_b128 v[170:173], v163 offset:1024
	ds_read_b128 v[174:177], v163 offset:2048
	ds_read_b128 v[180:183], v163 offset:3072
	ds_read_b128 v[184:187], v164
	ds_read_b128 v[188:191], v164 offset:1024
	ds_read_b128 v[198:201], v164 offset:2048
	ds_read_b128 v[202:205], v164 offset:3072
	v_lshl_add_u64 v[242:243], v[130:131], 0, s[44:45]
	s_add_i32 s83, s29, 0xc000
	v_lshl_add_u64 v[238:239], v[242:243], 0, s[10:11]
	s_mov_b32 m0, s83
	v_lshl_add_u64 v[244:245], v[132:133], 0, s[44:45]
	s_add_i32 s84, s29, 0xe000
	ds_read_b128 v[206:209], v165
	ds_read_b128 v[210:213], v165 offset:1024
	ds_read_b128 v[214:217], v165 offset:2048
	ds_read_b128 v[218:221], v165 offset:3072
	ds_read_b128 v[222:225], v165 offset:4096
	ds_read_b128 v[226:229], v165 offset:5120
	ds_read_b128 v[230:233], v165 offset:6144
	ds_read_b128 v[234:237], v165 offset:7168
	global_load_lds_dwordx4 v[238:239], off
	v_lshl_add_u64 v[238:239], v[244:245], 0, s[10:11]
	s_mov_b32 m0, s84
	s_nop 0
	global_load_lds_dwordx4 v[238:239], off
	s_waitcnt vmcnt(8)
	s_waitcnt lgkmcnt(0)
	s_barrier
	s_setprio 0
	s_waitcnt lgkmcnt(0)
	v_mfma_f32_16x16x32_bf16 v[14:17], v[166:169], v[206:209], v[14:17]
	v_mfma_f32_16x16x32_bf16 v[14:17], v[170:173], v[210:213], v[14:17]
	v_mfma_f32_16x16x32_bf16 v[38:41], v[166:169], v[214:217], v[38:41]
	v_mfma_f32_16x16x32_bf16 v[38:41], v[170:173], v[218:221], v[38:41]
	v_mfma_f32_16x16x32_bf16 v[70:73], v[166:169], v[222:225], v[70:73]
	v_mfma_f32_16x16x32_bf16 v[70:73], v[170:173], v[226:229], v[70:73]
	v_mfma_f32_16x16x32_bf16 v[94:97], v[166:169], v[230:233], v[94:97]
	v_mfma_f32_16x16x32_bf16 v[94:97], v[170:173], v[234:237], v[94:97]
	v_mfma_f32_16x16x32_bf16 v[90:93], v[174:177], v[230:233], v[90:93]
	v_mfma_f32_16x16x32_bf16 v[90:93], v[180:183], v[234:237], v[90:93]
	v_mfma_f32_16x16x32_bf16 v[66:69], v[174:177], v[222:225], v[66:69]
	v_mfma_f32_16x16x32_bf16 v[66:69], v[180:183], v[226:229], v[66:69]
	v_mfma_f32_16x16x32_bf16 v[34:37], v[174:177], v[214:217], v[34:37]
	v_mfma_f32_16x16x32_bf16 v[34:37], v[180:183], v[218:221], v[34:37]
	v_mfma_f32_16x16x32_bf16 v[10:13], v[174:177], v[206:209], v[10:13]
	v_mfma_f32_16x16x32_bf16 v[10:13], v[180:183], v[210:213], v[10:13]
	v_mfma_f32_16x16x32_bf16 v[30:33], v[184:187], v[206:209], v[30:33]
	v_mfma_f32_16x16x32_bf16 v[30:33], v[188:191], v[210:213], v[30:33]
	v_mfma_f32_16x16x32_bf16 v[54:57], v[184:187], v[214:217], v[54:57]
	v_mfma_f32_16x16x32_bf16 v[54:57], v[188:191], v[218:221], v[54:57]
	v_mfma_f32_16x16x32_bf16 v[86:89], v[184:187], v[222:225], v[86:89]
	v_mfma_f32_16x16x32_bf16 v[86:89], v[188:191], v[226:229], v[86:89]
	v_mfma_f32_16x16x32_bf16 v[110:113], v[184:187], v[230:233], v[110:113]
	v_mfma_f32_16x16x32_bf16 v[110:113], v[188:191], v[234:237], v[110:113]
	v_mfma_f32_16x16x32_bf16 v[106:109], v[198:201], v[230:233], v[106:109]
	v_mfma_f32_16x16x32_bf16 v[106:109], v[202:205], v[234:237], v[106:109]
	v_mfma_f32_16x16x32_bf16 v[82:85], v[198:201], v[222:225], v[82:85]
	v_mfma_f32_16x16x32_bf16 v[82:85], v[202:205], v[226:229], v[82:85]
	v_mfma_f32_16x16x32_bf16 v[50:53], v[198:201], v[214:217], v[50:53]
	v_mfma_f32_16x16x32_bf16 v[50:53], v[202:205], v[218:221], v[50:53]
	v_mfma_f32_16x16x32_bf16 v[26:29], v[198:201], v[206:209], v[26:29]
	v_mfma_f32_16x16x32_bf16 v[26:29], v[202:205], v[210:213], v[26:29]
	s_setprio 1
	s_barrier
	v_lshl_add_u64 v[246:247], v[156:157], 0, s[44:45]
	s_add_i32 s85, s80, s28
	v_lshl_add_u64 v[238:239], v[246:247], 0, s[14:15]
	s_mov_b32 m0, s85
	v_lshl_add_u64 v[248:249], v[158:159], 0, s[44:45]
	s_add_i32 s86, s85, 0x2000
	ds_read_b128 v[206:209], v165 offset:16384
	ds_read_b128 v[210:213], v165 offset:17408
	ds_read_b128 v[214:217], v165 offset:18432
	ds_read_b128 v[218:221], v165 offset:19456
	ds_read_b128 v[222:225], v165 offset:20480
	ds_read_b128 v[226:229], v165 offset:21504
	ds_read_b128 v[230:233], v165 offset:22528
	ds_read_b128 v[234:237], v165 offset:23552
	global_load_lds_dwordx4 v[238:239], off
	v_lshl_add_u64 v[238:239], v[248:249], 0, s[14:15]
	s_mov_b32 m0, s86
	s_add_i32 s87, s81, s28
	global_load_lds_dwordx4 v[238:239], off
	v_lshl_add_u64 v[238:239], v[246:247], 0, s[16:17]
	s_mov_b32 m0, s87
	s_add_i32 s88, s87, 0x2000
	global_load_lds_dwordx4 v[238:239], off
	v_lshl_add_u64 v[238:239], v[248:249], 0, s[16:17]
	s_mov_b32 m0, s88
	s_nop 0
	global_load_lds_dwordx4 v[238:239], off
	v_lshl_add_u64 v[238:239], v[242:243], 0, s[14:15]
	s_mov_b32 m0, s29
	s_nop 0
	global_load_lds_dwordx4 v[238:239], off
	v_lshl_add_u64 v[238:239], v[244:245], 0, s[14:15]
	s_mov_b32 m0, s30
	s_nop 0
	global_load_lds_dwordx4 v[238:239], off
	s_waitcnt vmcnt(8)
	s_waitcnt lgkmcnt(0)
	s_barrier
; #define PG8_STAGE(bufoff, gbase, voff) do { _Pragma("unroll") for (int _i = 0; _i < 2; ++_i) \
;         __builtin_amdgcn_global_load_lds((const unsigned*)((const char*)(gbase) + (voff)[_i]), (PG8_LAS unsigned*)(lds + (bufoff) + ldsw + _i * 8192), 16, 0, 0); } while (0)
; #define PG8_LDA(dst, b, h) do { _Pragma("unroll") for (int m = 0; m < 4; ++m) _Pragma("unroll") for (int k = 0; k < 2; ++k) dst[m][k] = *(const PG8_LAS bf16x8*)(lds + PG8_SA(b, h) + aoff + m * 2048 + k * 1024); } while (0)
; #define PG8_LDB(dst, b, h) do { _Pragma("unroll") for (int n = 0; n < 2; ++n) _Pragma("unroll") for (int k = 0; k < 2; ++k) dst[n][k] = *(const PG8_LAS bf16x8*)(lds + PG8_SB(b, h) + boff + n * 2048 + k * 1024); } while (0)
; template <class Epi, class Sched, bool ALIGN_EPI = false, bool SP2 = false>
; __device__ __forceinline__ void gemm_phase(PG8_LAS unsigned char* lds, const Gemm g, const Sched& S, const Epi& E) {
;     ...
;         for (; t < tend; t += 2) {
;             const bool last = (t == nt - 2);
;             const char* a1 = cA + (size_t)(t + 1) * kstep;
;             const char* a2 = last ? nA : cA + (size_t)(t + 2) * kstep; const char* b2 = last ? nB : cB + (size_t)(t + 2) * kstep;
;             const char* a3 = a2 + kstep; const char* b3 = b2 + kstep;
;             if (last && has_next) S.a_ready(nxt);
;             if constexpr (SP2) {
;             PG8_LDB(B0, 0, 0); PG8_LDB(B1, 0, 1); PG8_SCHED; PG8_LDA(At, 0, 0); PG8_STAGE(PG8_SA(1, 1), a1 + hstep, voffA);
;             PG8_WAIT_V(8); PG8_WAIT_L(0); PG8_BAR; PG8_MMA(0, 0, At, B0); PG8_MMA(0, 1, At, B1); PG8_BAR; PG8_SCHED;
;             PG8_LDA(At, 0, 1); PG8_STAGE(PG8_SB(0, 0), b2, voffB); PG8_STAGE(PG8_SB(0, 1), b2 + hstep, voffB); PG8_STAGE(PG8_SA(0, 0), a2, voffA);
;             PG8_WAIT_V(8); PG8_WAIT_L(0); PG8_BAR; PG8_MMA(1, 0, At, B0); PG8_MMA(1, 1, At, B1); PG8_BAR; PG8_SCHED;
;             PG8_LDB(B0, 1, 0); PG8_LDB(B1, 1, 1); PG8_SCHED; PG8_LDA(At, 1, 0); PG8_STAGE(PG8_SA(0, 1), a2 + hstep, voffA);
;             PG8_WAIT_V(8); PG8_WAIT_L(0); PG8_BAR; PG8_MMA(0, 0, At, B0); PG8_MMA(0, 1, At, B1); PG8_BAR; PG8_SCHED;
;             PG8_LDA(At, 1, 1); PG8_STAGE(PG8_SB(1, 0), b3, voffB); PG8_STAGE(PG8_SB(1, 1), b3 + hstep, voffB); PG8_STAGE(PG8_SA(1, 0), a3, voffA);
;             PG8_WAIT_V(8); PG8_WAIT_L(0); PG8_BAR; PG8_MMA(1, 0, At, B0); PG8_MMA(1, 1, At, B1); PG8_BAR; PG8_SCHED;
	s_setprio 0
	s_waitcnt lgkmcnt(0)
	v_mfma_f32_16x16x32_bf16 v[126:129], v[166:169], v[206:209], v[126:129]
	v_mfma_f32_16x16x32_bf16 v[126:129], v[170:173], v[210:213], v[126:129]
	v_mfma_f32_16x16x32_bf16 v[102:105], v[166:169], v[214:217], v[102:105]
	v_mfma_f32_16x16x32_bf16 v[102:105], v[170:173], v[218:221], v[102:105]
	v_mfma_f32_16x16x32_bf16 v[62:65], v[166:169], v[222:225], v[62:65]
	v_mfma_f32_16x16x32_bf16 v[62:65], v[170:173], v[226:229], v[62:65]
	v_mfma_f32_16x16x32_bf16 v[22:25], v[166:169], v[230:233], v[22:25]
	v_mfma_f32_16x16x32_bf16 v[22:25], v[170:173], v[234:237], v[22:25]
	v_mfma_f32_16x16x32_bf16 v[18:21], v[174:177], v[230:233], v[18:21]
	v_mfma_f32_16x16x32_bf16 v[18:21], v[180:183], v[234:237], v[18:21]
	v_mfma_f32_16x16x32_bf16 v[58:61], v[174:177], v[222:225], v[58:61]
	v_mfma_f32_16x16x32_bf16 v[58:61], v[180:183], v[226:229], v[58:61]
	v_mfma_f32_16x16x32_bf16 v[98:101], v[174:177], v[214:217], v[98:101]
	v_mfma_f32_16x16x32_bf16 v[98:101], v[180:183], v[218:221], v[98:101]
	v_mfma_f32_16x16x32_bf16 v[122:125], v[174:177], v[206:209], v[122:125]
	v_mfma_f32_16x16x32_bf16 v[122:125], v[180:183], v[210:213], v[122:125]
	v_mfma_f32_16x16x32_bf16 v[118:121], v[184:187], v[206:209], v[118:121]
	v_mfma_f32_16x16x32_bf16 v[118:121], v[188:191], v[210:213], v[118:121]
	v_mfma_f32_16x16x32_bf16 v[78:81], v[184:187], v[214:217], v[78:81]
	v_mfma_f32_16x16x32_bf16 v[78:81], v[188:191], v[218:221], v[78:81]
	v_mfma_f32_16x16x32_bf16 v[46:49], v[184:187], v[222:225], v[46:49]
	v_mfma_f32_16x16x32_bf16 v[46:49], v[188:191], v[226:229], v[46:49]
	v_mfma_f32_16x16x32_bf16 v[6:9], v[184:187], v[230:233], v[6:9]
	v_mfma_f32_16x16x32_bf16 v[6:9], v[188:191], v[234:237], v[6:9]
	v_mfma_f32_16x16x32_bf16 v[2:5], v[198:201], v[230:233], v[2:5]
	v_mfma_f32_16x16x32_bf16 v[2:5], v[202:205], v[234:237], v[2:5]
	v_mfma_f32_16x16x32_bf16 v[42:45], v[198:201], v[222:225], v[42:45]
	v_mfma_f32_16x16x32_bf16 v[42:45], v[202:205], v[226:229], v[42:45]
	v_mfma_f32_16x16x32_bf16 v[74:77], v[198:201], v[214:217], v[74:77]
	v_mfma_f32_16x16x32_bf16 v[74:77], v[202:205], v[218:221], v[74:77]
	v_mfma_f32_16x16x32_bf16 v[114:117], v[198:201], v[206:209], v[114:117]
	v_mfma_f32_16x16x32_bf16 v[114:117], v[202:205], v[210:213], v[114:117]
	s_setprio 1
	s_barrier
	s_add_i32 s89, 0, 0x18000
	s_add_i32 s91, 0, 0x1c000
	v_add_u32_e32 v142, s89, v161
	v_add_u32_e32 v167, s91, v161
	ds_read_b128 v[168:171], v142
	ds_read_b128 v[172:175], v142 offset:1024
	ds_read_b128 v[180:183], v142 offset:2048
	ds_read_b128 v[184:187], v142 offset:3072
	ds_read_b128 v[188:191], v167
	ds_read_b128 v[198:201], v167 offset:1024
	ds_read_b128 v[202:205], v167 offset:2048
	ds_read_b128 v[206:209], v167 offset:3072
	s_mov_b32 m0, s31
	v_lshl_add_u64 v[176:177], v[242:243], 0, s[16:17]
	ds_read_b128 v[210:213], v165 offset:32768
	ds_read_b128 v[214:217], v165 offset:33792
	ds_read_b128 v[218:221], v165 offset:34816
	ds_read_b128 v[222:225], v165 offset:35840
	ds_read_b128 v[226:229], v165 offset:36864
	ds_read_b128 v[230:233], v165 offset:37888
	ds_read_b128 v[234:237], v165 offset:38912
	ds_read_b128 v[238:241], v165 offset:39936
	global_load_lds_dwordx4 v[176:177], off
	v_lshl_add_u64 v[176:177], v[244:245], 0, s[16:17]
	s_mov_b32 m0, s35
	s_nop 0
	global_load_lds_dwordx4 v[176:177], off
	s_waitcnt vmcnt(8)
	s_waitcnt lgkmcnt(0)
	s_barrier
	s_setprio 0
	s_waitcnt lgkmcnt(0)
	v_mfma_f32_16x16x32_bf16 v[14:17], v[168:171], v[210:213], v[14:17]
	v_mfma_f32_16x16x32_bf16 v[14:17], v[172:175], v[214:217], v[14:17]
	v_mfma_f32_16x16x32_bf16 v[38:41], v[168:171], v[218:221], v[38:41]
	v_mfma_f32_16x16x32_bf16 v[38:41], v[172:175], v[222:225], v[38:41]
	v_mfma_f32_16x16x32_bf16 v[70:73], v[168:171], v[226:229], v[70:73]
	v_mfma_f32_16x16x32_bf16 v[70:73], v[172:175], v[230:233], v[70:73]
	v_mfma_f32_16x16x32_bf16 v[94:97], v[168:171], v[234:237], v[94:97]
	v_mfma_f32_16x16x32_bf16 v[94:97], v[172:175], v[238:241], v[94:97]
	v_mfma_f32_16x16x32_bf16 v[90:93], v[180:183], v[234:237], v[90:93]
	v_mfma_f32_16x16x32_bf16 v[90:93], v[184:187], v[238:241], v[90:93]
	v_mfma_f32_16x16x32_bf16 v[66:69], v[180:183], v[226:229], v[66:69]
	v_mfma_f32_16x16x32_bf16 v[66:69], v[184:187], v[230:233], v[66:69]
	v_mfma_f32_16x16x32_bf16 v[34:37], v[180:183], v[218:221], v[34:37]
	v_mfma_f32_16x16x32_bf16 v[34:37], v[184:187], v[222:225], v[34:37]
	v_mfma_f32_16x16x32_bf16 v[10:13], v[180:183], v[210:213], v[10:13]
	v_mfma_f32_16x16x32_bf16 v[10:13], v[184:187], v[214:217], v[10:13]
	v_mfma_f32_16x16x32_bf16 v[30:33], v[188:191], v[210:213], v[30:33]
	v_mfma_f32_16x16x32_bf16 v[30:33], v[198:201], v[214:217], v[30:33]
	v_mfma_f32_16x16x32_bf16 v[54:57], v[188:191], v[218:221], v[54:57]
	v_mfma_f32_16x16x32_bf16 v[54:57], v[198:201], v[222:225], v[54:57]
	v_mfma_f32_16x16x32_bf16 v[86:89], v[188:191], v[226:229], v[86:89]
	v_mfma_f32_16x16x32_bf16 v[86:89], v[198:201], v[230:233], v[86:89]
	v_mfma_f32_16x16x32_bf16 v[110:113], v[188:191], v[234:237], v[110:113]
	v_mfma_f32_16x16x32_bf16 v[110:113], v[198:201], v[238:241], v[110:113]
	v_mfma_f32_16x16x32_bf16 v[106:109], v[202:205], v[234:237], v[106:109]
	v_mfma_f32_16x16x32_bf16 v[106:109], v[206:209], v[238:241], v[106:109]
	v_mfma_f32_16x16x32_bf16 v[82:85], v[202:205], v[226:229], v[82:85]
	v_mfma_f32_16x16x32_bf16 v[82:85], v[206:209], v[230:233], v[82:85]
	v_mfma_f32_16x16x32_bf16 v[50:53], v[202:205], v[218:221], v[50:53]
	v_mfma_f32_16x16x32_bf16 v[50:53], v[206:209], v[222:225], v[50:53]
	v_mfma_f32_16x16x32_bf16 v[26:29], v[202:205], v[210:213], v[26:29]
	v_mfma_f32_16x16x32_bf16 v[26:29], v[206:209], v[214:217], v[26:29]
	s_setprio 1
	s_barrier
; #define PG8_STAGE(bufoff, gbase, voff) do { _Pragma("unroll") for (int _i = 0; _i < 2; ++_i) \
;         __builtin_amdgcn_global_load_lds((const unsigned*)((const char*)(gbase) + (voff)[_i]), (PG8_LAS unsigned*)(lds + (bufoff) + ldsw + _i * 8192), 16, 0, 0); } while (0)
; #define PG8_LDA(dst, b, h) do { _Pragma("unroll") for (int m = 0; m < 4; ++m) _Pragma("unroll") for (int k = 0; k < 2; ++k) dst[m][k] = *(const PG8_LAS bf16x8*)(lds + PG8_SA(b, h) + aoff + m * 2048 + k * 1024); } while (0)
; #define PG8_BAR __builtin_amdgcn_s_barrier()
;     __device__ __forceinline__ void mid(f32x4 (&acc)[2][2][4][2], const Unit& u, int wr, int wc, int fr, int fq) const {
;         int row0 = u.pm * BM + wr * 64 + fr; const int col0 = u.pn * BM + wc * 32 + 8 * fq;
;         asm volatile("" : "+v"(row0));
; #pragma unroll
;         for (int ai = 0; ai < 2; ++ai)
; #pragma unroll
;             for (int m = 0; m < 4; ++m) { const bf16_t* pr = P + (size_t)(row0 + ai * HALF + m * 16) * NP + col0;
; #pragma unroll
;                 for (int bj = 0; bj < 2; ++bj) { const u32x4 a = *(const u32x4*)(pr + PC_GA + bj * HALF), b = *(const u32x4*)(pr + PC_GB + bj * HALF);
; template <class Epi, class Sched, bool ALIGN_EPI = false, bool SP2 = false>
; __device__ __forceinline__ void gemm_phase(PG8_LAS unsigned char* lds, const Gemm g, const Sched& S, const Epi& E) {
;     ...
;             PG8_LDB(B0, 0, 0); PG8_LDB(B1, 0, 1); PG8_SCHED; PG8_LDA(At, 0, 0); PG8_STAGE(PG8_SA(1, 1), a1 + hstep, voffA);
;             PG8_WAIT_V(8); PG8_WAIT_L(0); PG8_BAR; PG8_MMA(0, 0, At, B0); PG8_MMA(0, 1, At, B1); PG8_BAR; PG8_SCHED;
;             PG8_LDA(At, 0, 1); PG8_STAGE(PG8_SB(0, 0), b2, voffB); PG8_STAGE(PG8_SB(0, 1), b2 + hstep, voffB); PG8_STAGE(PG8_SA(0, 0), a2, voffA);
;             PG8_WAIT_V(8); PG8_WAIT_L(0); PG8_BAR; PG8_MMA(1, 0, At, B0); PG8_MMA(1, 1, At, B1); PG8_BAR; PG8_SCHED;
;             PG8_LDB(B0, 1, 0); PG8_LDB(B1, 1, 1); PG8_SCHED; PG8_LDA(At, 1, 0); PG8_STAGE(PG8_SA(0, 1), a2 + hstep, voffA);
;             PG8_WAIT_V(8); PG8_WAIT_L(0); PG8_BAR; PG8_MMA(0, 0, At, B0); PG8_MMA(0, 1, At, B1); PG8_BAR; PG8_SCHED;
;             PG8_LDA(At, 1, 1); PG8_STAGE(PG8_SB(1, 0), b3, voffB); PG8_STAGE(PG8_SB(1, 1), b3 + hstep, voffB); PG8_STAGE(PG8_SA(1, 0), a3, voffA);
;             PG8_WAIT_V(8); PG8_WAIT_L(0); PG8_BAR; PG8_MMA(1, 0, At, B0); PG8_MMA(1, 1, At, B1); PG8_BAR; PG8_SCHED;
	s_add_i32 s89, s89, s28
	v_lshl_add_u64 v[176:177], v[246:247], 0, s[22:23]
	s_mov_b32 m0, s89
	s_add_i32 s90, s89, 0x2000
	ds_read_b128 v[210:213], v165 offset:49152
	ds_read_b128 v[214:217], v165 offset:50176
	ds_read_b128 v[218:221], v165 offset:51200
	ds_read_b128 v[222:225], v165 offset:52224
	ds_read_b128 v[226:229], v165 offset:53248
	ds_read_b128 v[230:233], v165 offset:54272
	ds_read_b128 v[234:237], v165 offset:55296
	ds_read_b128 v[238:241], v165 offset:56320
	global_load_lds_dwordx4 v[176:177], off
	v_lshl_add_u64 v[176:177], v[248:249], 0, s[22:23]
	s_mov_b32 m0, s90
	s_add_i32 s91, s91, s28
	global_load_lds_dwordx4 v[176:177], off
	v_lshl_add_u64 v[176:177], v[246:247], 0, s[36:37]
	s_mov_b32 m0, s91
	s_add_i32 s92, s91, 0x2000
	global_load_lds_dwordx4 v[176:177], off
	v_lshl_add_u64 v[176:177], v[248:249], 0, s[36:37]
	s_mov_b32 m0, s92
	s_nop 0
	global_load_lds_dwordx4 v[176:177], off
	v_lshl_add_u64 v[176:177], v[242:243], 0, s[22:23]
	s_mov_b32 m0, s75
	s_nop 0
	global_load_lds_dwordx4 v[176:177], off
	v_lshl_add_u64 v[176:177], v[244:245], 0, s[22:23]
	s_mov_b32 m0, s76
	s_nop 0
	global_load_lds_dwordx4 v[176:177], off
	s_waitcnt vmcnt(8)
	s_waitcnt lgkmcnt(0)
	s_barrier
	s_setprio 0
	s_waitcnt lgkmcnt(0)
	v_mfma_f32_16x16x32_bf16 v[126:129], v[168:171], v[210:213], v[126:129]
	v_mfma_f32_16x16x32_bf16 v[126:129], v[172:175], v[214:217], v[126:129]
	v_mfma_f32_16x16x32_bf16 v[102:105], v[168:171], v[218:221], v[102:105]
	v_mfma_f32_16x16x32_bf16 v[102:105], v[172:175], v[222:225], v[102:105]
	v_mfma_f32_16x16x32_bf16 v[62:65], v[168:171], v[226:229], v[62:65]
	v_mfma_f32_16x16x32_bf16 v[62:65], v[172:175], v[230:233], v[62:65]
	v_mfma_f32_16x16x32_bf16 v[22:25], v[168:171], v[234:237], v[22:25]
	v_mfma_f32_16x16x32_bf16 v[22:25], v[172:175], v[238:241], v[22:25]
	v_mfma_f32_16x16x32_bf16 v[18:21], v[180:183], v[234:237], v[18:21]
	v_mfma_f32_16x16x32_bf16 v[18:21], v[184:187], v[238:241], v[18:21]
	v_mfma_f32_16x16x32_bf16 v[58:61], v[180:183], v[226:229], v[58:61]
	v_mfma_f32_16x16x32_bf16 v[58:61], v[184:187], v[230:233], v[58:61]
	v_mfma_f32_16x16x32_bf16 v[98:101], v[180:183], v[218:221], v[98:101]
	v_mfma_f32_16x16x32_bf16 v[98:101], v[184:187], v[222:225], v[98:101]
	v_mfma_f32_16x16x32_bf16 v[122:125], v[180:183], v[210:213], v[122:125]
	v_mfma_f32_16x16x32_bf16 v[122:125], v[184:187], v[214:217], v[122:125]
	v_mfma_f32_16x16x32_bf16 v[118:121], v[188:191], v[210:213], v[118:121]
	v_mfma_f32_16x16x32_bf16 v[118:121], v[198:201], v[214:217], v[118:121]
	v_mfma_f32_16x16x32_bf16 v[78:81], v[188:191], v[218:221], v[78:81]
	v_mfma_f32_16x16x32_bf16 v[78:81], v[198:201], v[222:225], v[78:81]
	v_mfma_f32_16x16x32_bf16 v[46:49], v[188:191], v[226:229], v[46:49]
	v_mfma_f32_16x16x32_bf16 v[46:49], v[198:201], v[230:233], v[46:49]
	v_mfma_f32_16x16x32_bf16 v[6:9], v[188:191], v[234:237], v[6:9]
	v_mfma_f32_16x16x32_bf16 v[6:9], v[198:201], v[238:241], v[6:9]
	v_mfma_f32_16x16x32_bf16 v[2:5], v[202:205], v[234:237], v[2:5]
	v_mfma_f32_16x16x32_bf16 v[2:5], v[206:209], v[238:241], v[2:5]
	v_mfma_f32_16x16x32_bf16 v[42:45], v[202:205], v[226:229], v[42:45]
	v_mfma_f32_16x16x32_bf16 v[42:45], v[206:209], v[230:233], v[42:45]
	v_mfma_f32_16x16x32_bf16 v[74:77], v[202:205], v[218:221], v[74:77]
	v_mfma_f32_16x16x32_bf16 v[74:77], v[206:209], v[222:225], v[74:77]
	v_mfma_f32_16x16x32_bf16 v[114:117], v[202:205], v[210:213], v[114:117]
	v_mfma_f32_16x16x32_bf16 v[114:117], v[206:209], v[214:217], v[114:117]
	s_setprio 1
	s_barrier
	s_add_i32 s27, s27, 2
	s_add_u32 s44, s44, 0x10000
	s_addc_u32 s45, s45, 0
	s_cmp_lt_u32 s27, 30
	s_cbranch_scc1 .LBB0_682
	s_setprio 0
	s_ashr_i32 s41, s40, 31
	s_lshl_b64 s[44:45], s[40:41], 21
	s_add_u32 s44, s18, s44
	s_addc_u32 s45, s19, s45
	s_ashr_i32 s39, s38, 31
	s_lshl_b64 s[46:47], s[38:39], 21
	v_readlane_b32 s58, v255, 15
	v_readlane_b32 s59, v255, 16
	s_add_u32 s46, s58, s46
	s_addc_u32 s47, s59, s47
	s_lshl_b32 s39, s26, 8
	v_or_b32_e32 v130, s39, v162
	v_ashrrev_i32_e32 v131, 31, v130
	v_lshl_add_u32 v166, s70, 8, v160
	v_lshl_add_u64 v[156:157], v[130:131], 1, s[24:25]
	v_mov_b32_e32 v168, v166
	s_and_b64 s[26:27], s[0:1], exec
	v_mad_i64_i32 v[158:159], s[58:59], v168, s78, v[156:157]
	v_add_co_u32_e32 v174, vcc, s61, v158
	s_cselect_b32 s41, s45, s51
	s_nop 0
	v_addc_co_u32_e32 v175, vcc, 0, v159, vcc
	v_add_co_u32_e32 v158, vcc, s77, v158
	global_load_dwordx4 v[130:133], v[174:175], off
	s_nop 0
	v_addc_co_u32_e32 v159, vcc, 0, v159, vcc
	global_load_dwordx4 v[170:173], v[158:159], off
	s_cselect_b32 s93, s44, s50
	s_cselect_b32 s27, s47, s49
	s_cselect_b32 s97, s46, s48
	s_add_u32 s50, s50, 0x10c000
	s_addc_u32 s51, s51, 0
	s_add_u32 s26, s48, 0x110000
	s_addc_u32 s33, s49, 0
	s_mov_b32 s56, 30
	s_waitcnt vmcnt(0)
; __device__ __forceinline__ float bflo(unsigned w) { return __uint_as_float(w << 16); }
; __device__ __forceinline__ float bfhi(unsigned w) { return __uint_as_float(w & 0xffff0000u); }
;     __device__ __forceinline__ void mid(f32x4 (&acc)[2][2][4][2], const Unit& u, int wr, int wc, int fr, int fq) const {
;     ...
;             for (int m = 0; m < 4; ++m) { const bf16_t* pr = P + (size_t)(row0 + ai * HALF + m * 16) * NP + col0;
; #pragma unroll
;                 for (int bj = 0; bj < 2; ++bj) { const u32x4 a = *(const u32x4*)(pr + PC_GA + bj * HALF), b = *(const u32x4*)(pr + PC_GB + bj * HALF);
;                     const f32x4 b0 = {bflo(b.x), bfhi(b.x), bflo(b.y), bfhi(b.y)}, b1 = {bflo(b.z), bfhi(b.z), bflo(b.w), bfhi(b.w)};
;                     const f32x4 a0 = {bflo(a.x), bfhi(a.x), bflo(a.y), bfhi(a.y)}, a1 = {bflo(a.z), bfhi(a.z), bflo(a.w), bfhi(a.w)};
;                     f32x4 r0, r1;
; #pragma unroll
;                     for (int j = 0; j < 4; ++j) { r0[j] = a0[j] * __builtin_amdgcn_rcpf(fmaxf(b0[j], 1e-30f)); r1[j] = a1[j] * __builtin_amdgcn_rcpf(fmaxf(b1[j], 1e-30f)); }
;                     acc[ai][bj][m][0] *= r0; acc[ai][bj][m][1] *= r1; }
;                 asm volatile("" ::: "memory"); }
	v_and_b32_e32 v177, 0xffff0000, v130
	v_lshlrev_b32_e32 v169, 16, v170
	v_max_f32_e32 v169, v169, v169
	v_lshlrev_b32_e32 v178, 16, v171
	v_and_b32_e32 v179, 0xffff0000, v171
	v_lshlrev_b32_e32 v171, 16, v172
	v_max_f32_e32 v169, 0xda24260, v169
	v_and_b32_e32 v176, 0xffff0000, v170
	v_rcp_f32_e32 v170, v169
	v_max_f32_e32 v169, v171, v171
	v_max_f32_e32 v169, 0xda24260, v169
	v_and_b32_e32 v180, 0xffff0000, v172
	v_rcp_f32_e32 v172, v169
	v_max_f32_e32 v169, v176, v176
	v_max_f32_e32 v169, 0xda24260, v169
	v_lshlrev_b32_e32 v176, 16, v130
	v_max_f32_e32 v130, v180, v180
	v_rcp_f32_e32 v171, v169
	v_max_f32_e32 v130, 0xda24260, v130
	v_lshlrev_b32_e32 v181, 16, v173
	v_and_b32_e32 v182, 0xffff0000, v173
	v_rcp_f32_e32 v173, v130
	v_max_f32_e32 v130, v178, v178
	v_pk_mul_f32 v[170:171], v[170:171], v[176:177]
	v_lshlrev_b32_e32 v176, 16, v132
	v_and_b32_e32 v177, 0xffff0000, v132
	v_max_f32_e32 v130, 0xda24260, v130
	v_pk_mul_f32 v[172:173], v[172:173], v[176:177]
	v_rcp_f32_e32 v176, v130
	v_max_f32_e32 v130, v181, v181
	v_lshlrev_b32_e32 v180, 16, v131
	v_and_b32_e32 v181, 0xffff0000, v131
	v_max_f32_e32 v131, v182, v182
	v_max_f32_e32 v130, 0xda24260, v130
	v_max_f32_e32 v131, 0xda24260, v131
	v_rcp_f32_e32 v130, v130
	v_rcp_f32_e32 v131, v131
	v_max_f32_e32 v132, v179, v179
	v_max_f32_e32 v132, 0xda24260, v132
	v_rcp_f32_e32 v177, v132
	v_lshlrev_b32_e32 v132, 16, v133
	v_and_b32_e32 v133, 0xffff0000, v133
	v_pk_mul_f32 v[130:131], v[130:131], v[132:133]
	v_pk_mul_f32 v[14:15], v[14:15], v[170:171]
	v_pk_mul_f32 v[12:13], v[12:13], v[130:131]
	v_pk_mul_f32 v[10:11], v[10:11], v[172:173]
	global_load_dwordx4 v[130:133], v[174:175], off offset:256
	global_load_dwordx4 v[170:173], v[158:159], off offset:256
	v_pk_mul_f32 v[176:177], v[176:177], v[180:181]
	s_waitcnt vmcnt(0)
	v_lshlrev_b32_e32 v158, 16, v170
	v_and_b32_e32 v159, 0xffff0000, v170
	v_lshlrev_b32_e32 v169, 16, v171
	v_and_b32_e32 v174, 0xffff0000, v171
	v_lshlrev_b32_e32 v170, 16, v172
	v_and_b32_e32 v171, 0xffff0000, v172
	v_max_f32_e32 v158, v158, v158
	v_max_f32_e32 v159, v159, v159
	v_pk_mul_f32 v[16:17], v[16:17], v[176:177]
	v_lshlrev_b32_e32 v175, 16, v173
	v_and_b32_e32 v176, 0xffff0000, v173
	v_max_f32_e32 v158, 0xda24260, v158
	v_max_f32_e32 v170, v170, v170
	v_max_f32_e32 v159, 0xda24260, v159
	v_lshlrev_b32_e32 v172, 16, v130
	v_and_b32_e32 v173, 0xffff0000, v130
	v_max_f32_e32 v130, v171, v171
	v_rcp_f32_e32 v158, v158
	v_max_f32_e32 v170, 0xda24260, v170
	v_rcp_f32_e32 v159, v159
	v_max_f32_e32 v130, 0xda24260, v130
	v_rcp_f32_e32 v170, v170
	v_rcp_f32_e32 v171, v130
	v_max_f32_e32 v130, v169, v169
	v_pk_mul_f32 v[158:159], v[158:159], v[172:173]
	v_lshlrev_b32_e32 v172, 16, v132
	v_and_b32_e32 v173, 0xffff0000, v132
	v_max_f32_e32 v130, 0xda24260, v130
	v_pk_mul_f32 v[170:171], v[170:171], v[172:173]
	v_rcp_f32_e32 v172, v130
	v_max_f32_e32 v130, v175, v175
	v_max_f32_e32 v132, v174, v174
	v_lshlrev_b32_e32 v174, 16, v131
	v_and_b32_e32 v175, 0xffff0000, v131
	v_max_f32_e32 v131, v176, v176
	v_max_f32_e32 v130, 0xda24260, v130
	v_max_f32_e32 v131, 0xda24260, v131
	v_rcp_f32_e32 v130, v130
	v_rcp_f32_e32 v131, v131
	v_max_f32_e32 v132, 0xda24260, v132
	v_rcp_f32_e32 v173, v132
	v_lshlrev_b32_e32 v132, 16, v133
	v_and_b32_e32 v133, 0xffff0000, v133
	v_pk_mul_f32 v[130:131], v[130:131], v[132:133]
	v_pk_mul_f32 v[30:31], v[30:31], v[158:159]
	v_pk_mul_f32 v[28:29], v[28:29], v[130:131]
	v_add_u32_e32 v130, 16, v168
	v_mad_i64_i32 v[158:159], s[58:59], v130, s78, v[156:157]
	v_pk_mul_f32 v[172:173], v[172:173], v[174:175]
	v_add_co_u32_e32 v174, vcc, s61, v158
	v_pk_mul_f32 v[32:33], v[32:33], v[172:173]
	s_nop 0
	v_addc_co_u32_e32 v175, vcc, 0, v159, vcc
	v_add_co_u32_e32 v158, vcc, s77, v158
	v_pk_mul_f32 v[26:27], v[26:27], v[170:171]
	s_nop 0
	v_addc_co_u32_e32 v159, vcc, 0, v159, vcc
	global_load_dwordx4 v[130:133], v[174:175], off
	global_load_dwordx4 v[170:173], v[158:159], off
	s_waitcnt vmcnt(1)
	v_and_b32_e32 v177, 0xffff0000, v130
	s_waitcnt vmcnt(0)
	v_lshlrev_b32_e32 v169, 16, v170
	v_max_f32_e32 v169, v169, v169
	v_lshlrev_b32_e32 v178, 16, v171
	v_and_b32_e32 v179, 0xffff0000, v171
	v_lshlrev_b32_e32 v171, 16, v172
	v_max_f32_e32 v169, 0xda24260, v169
	v_and_b32_e32 v176, 0xffff0000, v170
	v_rcp_f32_e32 v170, v169
	v_max_f32_e32 v169, v171, v171
	v_max_f32_e32 v169, 0xda24260, v169
	v_and_b32_e32 v180, 0xffff0000, v172
	v_rcp_f32_e32 v172, v169
	v_max_f32_e32 v169, v176, v176
	v_max_f32_e32 v169, 0xda24260, v169
	v_lshlrev_b32_e32 v176, 16, v130
	v_max_f32_e32 v130, v180, v180
	v_rcp_f32_e32 v171, v169
	v_max_f32_e32 v130, 0xda24260, v130
	v_lshlrev_b32_e32 v181, 16, v173
	v_and_b32_e32 v182, 0xffff0000, v173
	v_rcp_f32_e32 v173, v130
	v_max_f32_e32 v130, v178, v178
	v_pk_mul_f32 v[170:171], v[170:171], v[176:177]
	v_lshlrev_b32_e32 v176, 16, v132
	v_and_b32_e32 v177, 0xffff0000, v132
	v_max_f32_e32 v130, 0xda24260, v130
	v_pk_mul_f32 v[172:173], v[172:173], v[176:177]
	v_rcp_f32_e32 v176, v130
	v_max_f32_e32 v130, v181, v181
	v_lshlrev_b32_e32 v180, 16, v131
	v_and_b32_e32 v181, 0xffff0000, v131
	v_max_f32_e32 v131, v182, v182
	v_max_f32_e32 v130, 0xda24260, v130
	v_max_f32_e32 v131, 0xda24260, v131
	v_rcp_f32_e32 v130, v130
	v_rcp_f32_e32 v131, v131
	v_max_f32_e32 v132, v179, v179
	v_max_f32_e32 v132, 0xda24260, v132
	v_rcp_f32_e32 v177, v132
	v_lshlrev_b32_e32 v132, 16, v133
	v_and_b32_e32 v133, 0xffff0000, v133
	v_pk_mul_f32 v[130:131], v[130:131], v[132:133]
	v_pk_mul_f32 v[38:39], v[38:39], v[170:171]
	v_pk_mul_f32 v[36:37], v[36:37], v[130:131]
	v_pk_mul_f32 v[34:35], v[34:35], v[172:173]
	global_load_dwordx4 v[130:133], v[174:175], off offset:256
	global_load_dwordx4 v[170:173], v[158:159], off offset:256
	v_pk_mul_f32 v[176:177], v[176:177], v[180:181]
	s_waitcnt vmcnt(0)
; __device__ __forceinline__ float bflo(unsigned w) { return __uint_as_float(w << 16); }
; __device__ __forceinline__ float bfhi(unsigned w) { return __uint_as_float(w & 0xffff0000u); }
;     __device__ __forceinline__ void mid(f32x4 (&acc)[2][2][4][2], const Unit& u, int wr, int wc, int fr, int fq) const {
;     ...
;             for (int m = 0; m < 4; ++m) { const bf16_t* pr = P + (size_t)(row0 + ai * HALF + m * 16) * NP + col0;
; #pragma unroll
;                 for (int bj = 0; bj < 2; ++bj) { const u32x4 a = *(const u32x4*)(pr + PC_GA + bj * HALF), b = *(const u32x4*)(pr + PC_GB + bj * HALF);
;                     const f32x4 b0 = {bflo(b.x), bfhi(b.x), bflo(b.y), bfhi(b.y)}, b1 = {bflo(b.z), bfhi(b.z), bflo(b.w), bfhi(b.w)};
;                     const f32x4 a0 = {bflo(a.x), bfhi(a.x), bflo(a.y), bfhi(a.y)}, a1 = {bflo(a.z), bfhi(a.z), bflo(a.w), bfhi(a.w)};
;                     f32x4 r0, r1;
; #pragma unroll
;                     for (int j = 0; j < 4; ++j) { r0[j] = a0[j] * __builtin_amdgcn_rcpf(fmaxf(b0[j], 1e-30f)); r1[j] = a1[j] * __builtin_amdgcn_rcpf(fmaxf(b1[j], 1e-30f)); }
;                     acc[ai][bj][m][0] *= r0; acc[ai][bj][m][1] *= r1; }
;                 asm volatile("" ::: "memory"); }
	v_lshlrev_b32_e32 v158, 16, v170
	v_and_b32_e32 v159, 0xffff0000, v170
	v_lshlrev_b32_e32 v169, 16, v171
	v_and_b32_e32 v174, 0xffff0000, v171
	v_lshlrev_b32_e32 v170, 16, v172
	v_and_b32_e32 v171, 0xffff0000, v172
	v_max_f32_e32 v158, v158, v158
	v_max_f32_e32 v159, v159, v159
	v_pk_mul_f32 v[40:41], v[40:41], v[176:177]
	v_lshlrev_b32_e32 v175, 16, v173
	v_and_b32_e32 v176, 0xffff0000, v173
	v_max_f32_e32 v158, 0xda24260, v158
	v_max_f32_e32 v170, v170, v170
	v_max_f32_e32 v159, 0xda24260, v159
	v_lshlrev_b32_e32 v172, 16, v130
	v_and_b32_e32 v173, 0xffff0000, v130
	v_max_f32_e32 v130, v171, v171
	v_rcp_f32_e32 v158, v158
	v_max_f32_e32 v170, 0xda24260, v170
	v_rcp_f32_e32 v159, v159
	v_max_f32_e32 v130, 0xda24260, v130
	v_rcp_f32_e32 v170, v170
	v_rcp_f32_e32 v171, v130
	v_max_f32_e32 v130, v169, v169
	v_pk_mul_f32 v[158:159], v[158:159], v[172:173]
	v_lshlrev_b32_e32 v172, 16, v132
	v_and_b32_e32 v173, 0xffff0000, v132
	v_max_f32_e32 v130, 0xda24260, v130
	v_pk_mul_f32 v[170:171], v[170:171], v[172:173]
	v_rcp_f32_e32 v172, v130
	v_max_f32_e32 v130, v175, v175
	v_max_f32_e32 v132, v174, v174
	v_lshlrev_b32_e32 v174, 16, v131
	v_and_b32_e32 v175, 0xffff0000, v131
	v_max_f32_e32 v131, v176, v176
	v_max_f32_e32 v130, 0xda24260, v130
	v_max_f32_e32 v131, 0xda24260, v131
	v_rcp_f32_e32 v130, v130
	v_rcp_f32_e32 v131, v131
	v_max_f32_e32 v132, 0xda24260, v132
	v_rcp_f32_e32 v173, v132
	v_lshlrev_b32_e32 v132, 16, v133
	v_and_b32_e32 v133, 0xffff0000, v133
	v_pk_mul_f32 v[130:131], v[130:131], v[132:133]
	v_pk_mul_f32 v[54:55], v[54:55], v[158:159]
	v_pk_mul_f32 v[52:53], v[52:53], v[130:131]
	v_add_u32_e32 v130, 32, v168
	v_mad_i64_i32 v[158:159], s[58:59], v130, s78, v[156:157]
	v_pk_mul_f32 v[172:173], v[172:173], v[174:175]
	v_add_co_u32_e32 v174, vcc, s61, v158
	v_pk_mul_f32 v[56:57], v[56:57], v[172:173]
	s_nop 0
	v_addc_co_u32_e32 v175, vcc, 0, v159, vcc
	v_add_co_u32_e32 v158, vcc, s77, v158
	v_pk_mul_f32 v[50:51], v[50:51], v[170:171]
	s_nop 0
	v_addc_co_u32_e32 v159, vcc, 0, v159, vcc
	global_load_dwordx4 v[130:133], v[174:175], off
	global_load_dwordx4 v[170:173], v[158:159], off
	s_waitcnt vmcnt(1)
	v_and_b32_e32 v177, 0xffff0000, v130
	s_waitcnt vmcnt(0)
	v_lshlrev_b32_e32 v169, 16, v170
	v_max_f32_e32 v169, v169, v169
	v_lshlrev_b32_e32 v178, 16, v171
	v_and_b32_e32 v179, 0xffff0000, v171
	v_lshlrev_b32_e32 v171, 16, v172
	v_max_f32_e32 v169, 0xda24260, v169
	v_and_b32_e32 v176, 0xffff0000, v170
	v_rcp_f32_e32 v170, v169
	v_max_f32_e32 v169, v171, v171
	v_max_f32_e32 v169, 0xda24260, v169
	v_and_b32_e32 v180, 0xffff0000, v172
	v_rcp_f32_e32 v172, v169
	v_max_f32_e32 v169, v176, v176
	v_max_f32_e32 v169, 0xda24260, v169
	v_lshlrev_b32_e32 v176, 16, v130
	v_max_f32_e32 v130, v180, v180
	v_rcp_f32_e32 v171, v169
	v_max_f32_e32 v130, 0xda24260, v130
	v_lshlrev_b32_e32 v181, 16, v173
	v_and_b32_e32 v182, 0xffff0000, v173
	v_rcp_f32_e32 v173, v130
	v_max_f32_e32 v130, v178, v178
	v_pk_mul_f32 v[170:171], v[170:171], v[176:177]
	v_lshlrev_b32_e32 v176, 16, v132
	v_and_b32_e32 v177, 0xffff0000, v132
	v_max_f32_e32 v130, 0xda24260, v130
	v_pk_mul_f32 v[172:173], v[172:173], v[176:177]
	v_rcp_f32_e32 v176, v130
	v_max_f32_e32 v130, v181, v181
	v_lshlrev_b32_e32 v180, 16, v131
	v_and_b32_e32 v181, 0xffff0000, v131
	v_max_f32_e32 v131, v182, v182
	v_max_f32_e32 v130, 0xda24260, v130
	v_max_f32_e32 v131, 0xda24260, v131
	v_rcp_f32_e32 v130, v130
	v_rcp_f32_e32 v131, v131
	v_max_f32_e32 v132, v179, v179
	v_max_f32_e32 v132, 0xda24260, v132
	v_rcp_f32_e32 v177, v132
	v_lshlrev_b32_e32 v132, 16, v133
	v_and_b32_e32 v133, 0xffff0000, v133
	v_pk_mul_f32 v[130:131], v[130:131], v[132:133]
	v_pk_mul_f32 v[70:71], v[70:71], v[170:171]
	v_pk_mul_f32 v[68:69], v[68:69], v[130:131]
	v_pk_mul_f32 v[66:67], v[66:67], v[172:173]
	global_load_dwordx4 v[130:133], v[174:175], off offset:256
	global_load_dwordx4 v[170:173], v[158:159], off offset:256
	v_pk_mul_f32 v[176:177], v[176:177], v[180:181]
	s_waitcnt vmcnt(0)
	v_lshlrev_b32_e32 v158, 16, v170
	v_and_b32_e32 v159, 0xffff0000, v170
	v_lshlrev_b32_e32 v169, 16, v171
	v_and_b32_e32 v174, 0xffff0000, v171
	v_lshlrev_b32_e32 v170, 16, v172
	v_and_b32_e32 v171, 0xffff0000, v172
	v_max_f32_e32 v158, v158, v158
	v_max_f32_e32 v159, v159, v159
	v_pk_mul_f32 v[72:73], v[72:73], v[176:177]
	v_lshlrev_b32_e32 v175, 16, v173
	v_and_b32_e32 v176, 0xffff0000, v173
	v_max_f32_e32 v158, 0xda24260, v158
	v_max_f32_e32 v170, v170, v170
	v_max_f32_e32 v159, 0xda24260, v159
	v_lshlrev_b32_e32 v172, 16, v130
	v_and_b32_e32 v173, 0xffff0000, v130
	v_max_f32_e32 v130, v171, v171
	v_rcp_f32_e32 v158, v158
	v_max_f32_e32 v170, 0xda24260, v170
	v_rcp_f32_e32 v159, v159
	v_max_f32_e32 v130, 0xda24260, v130
	v_rcp_f32_e32 v170, v170
	v_rcp_f32_e32 v171, v130
	v_max_f32_e32 v130, v169, v169
	v_pk_mul_f32 v[158:159], v[158:159], v[172:173]
	v_lshlrev_b32_e32 v172, 16, v132
	v_and_b32_e32 v173, 0xffff0000, v132
	v_max_f32_e32 v130, 0xda24260, v130
	v_pk_mul_f32 v[170:171], v[170:171], v[172:173]
	v_rcp_f32_e32 v172, v130
	v_max_f32_e32 v130, v175, v175
	v_max_f32_e32 v132, v174, v174
	v_lshlrev_b32_e32 v174, 16, v131
	v_and_b32_e32 v175, 0xffff0000, v131
	v_max_f32_e32 v131, v176, v176
	v_max_f32_e32 v130, 0xda24260, v130
	v_max_f32_e32 v131, 0xda24260, v131
	v_rcp_f32_e32 v130, v130
	v_rcp_f32_e32 v131, v131
	v_max_f32_e32 v132, 0xda24260, v132
	v_rcp_f32_e32 v173, v132
	v_lshlrev_b32_e32 v132, 16, v133
	v_and_b32_e32 v133, 0xffff0000, v133
	v_pk_mul_f32 v[130:131], v[130:131], v[132:133]
	v_pk_mul_f32 v[86:87], v[86:87], v[158:159]
	v_pk_mul_f32 v[84:85], v[84:85], v[130:131]
	v_add_u32_e32 v130, 48, v168
	v_mad_i64_i32 v[158:159], s[58:59], v130, s78, v[156:157]
	v_pk_mul_f32 v[172:173], v[172:173], v[174:175]
	v_add_co_u32_e32 v174, vcc, s61, v158
	v_pk_mul_f32 v[88:89], v[88:89], v[172:173]
	s_nop 0
	v_addc_co_u32_e32 v175, vcc, 0, v159, vcc
	v_add_co_u32_e32 v158, vcc, s77, v158
	v_pk_mul_f32 v[82:83], v[82:83], v[170:171]
	s_nop 0
	v_addc_co_u32_e32 v159, vcc, 0, v159, vcc
	global_load_dwordx4 v[130:133], v[174:175], off
	global_load_dwordx4 v[170:173], v[158:159], off
	s_waitcnt vmcnt(1)
; __device__ __forceinline__ float bflo(unsigned w) { return __uint_as_float(w << 16); }
; __device__ __forceinline__ float bfhi(unsigned w) { return __uint_as_float(w & 0xffff0000u); }
;     __device__ __forceinline__ void mid(f32x4 (&acc)[2][2][4][2], const Unit& u, int wr, int wc, int fr, int fq) const {
;     ...
;             for (int m = 0; m < 4; ++m) { const bf16_t* pr = P + (size_t)(row0 + ai * HALF + m * 16) * NP + col0;
; #pragma unroll
;                 for (int bj = 0; bj < 2; ++bj) { const u32x4 a = *(const u32x4*)(pr + PC_GA + bj * HALF), b = *(const u32x4*)(pr + PC_GB + bj * HALF);
;                     const f32x4 b0 = {bflo(b.x), bfhi(b.x), bflo(b.y), bfhi(b.y)}, b1 = {bflo(b.z), bfhi(b.z), bflo(b.w), bfhi(b.w)};
;                     const f32x4 a0 = {bflo(a.x), bfhi(a.x), bflo(a.y), bfhi(a.y)}, a1 = {bflo(a.z), bfhi(a.z), bflo(a.w), bfhi(a.w)};
;                     f32x4 r0, r1;
; #pragma unroll
;                     for (int j = 0; j < 4; ++j) { r0[j] = a0[j] * __builtin_amdgcn_rcpf(fmaxf(b0[j], 1e-30f)); r1[j] = a1[j] * __builtin_amdgcn_rcpf(fmaxf(b1[j], 1e-30f)); }
;                     acc[ai][bj][m][0] *= r0; acc[ai][bj][m][1] *= r1; }
;                 asm volatile("" ::: "memory"); }
	v_and_b32_e32 v177, 0xffff0000, v130
	s_waitcnt vmcnt(0)
	v_lshlrev_b32_e32 v169, 16, v170
	v_max_f32_e32 v169, v169, v169
	v_lshlrev_b32_e32 v178, 16, v171
	v_and_b32_e32 v179, 0xffff0000, v171
	v_lshlrev_b32_e32 v171, 16, v172
	v_max_f32_e32 v169, 0xda24260, v169
	v_and_b32_e32 v176, 0xffff0000, v170
	v_rcp_f32_e32 v170, v169
	v_max_f32_e32 v169, v171, v171
	v_max_f32_e32 v169, 0xda24260, v169
	v_and_b32_e32 v180, 0xffff0000, v172
	v_rcp_f32_e32 v172, v169
	v_max_f32_e32 v169, v176, v176
	v_max_f32_e32 v169, 0xda24260, v169
	v_lshlrev_b32_e32 v176, 16, v130
	v_max_f32_e32 v130, v180, v180
	v_rcp_f32_e32 v171, v169
	v_max_f32_e32 v130, 0xda24260, v130
	v_lshlrev_b32_e32 v181, 16, v173
	v_and_b32_e32 v182, 0xffff0000, v173
	v_rcp_f32_e32 v173, v130
	v_max_f32_e32 v130, v178, v178
	v_pk_mul_f32 v[170:171], v[170:171], v[176:177]
	v_lshlrev_b32_e32 v176, 16, v132
	v_and_b32_e32 v177, 0xffff0000, v132
	v_max_f32_e32 v130, 0xda24260, v130
	v_pk_mul_f32 v[172:173], v[172:173], v[176:177]
	v_rcp_f32_e32 v176, v130
	v_max_f32_e32 v130, v181, v181
	v_lshlrev_b32_e32 v180, 16, v131
	v_and_b32_e32 v181, 0xffff0000, v131
	v_max_f32_e32 v131, v182, v182
	v_max_f32_e32 v130, 0xda24260, v130
	v_max_f32_e32 v131, 0xda24260, v131
	v_rcp_f32_e32 v130, v130
	v_rcp_f32_e32 v131, v131
	v_max_f32_e32 v132, v179, v179
	v_max_f32_e32 v132, 0xda24260, v132
	v_rcp_f32_e32 v177, v132
	v_lshlrev_b32_e32 v132, 16, v133
	v_and_b32_e32 v133, 0xffff0000, v133
	v_pk_mul_f32 v[130:131], v[130:131], v[132:133]
	v_pk_mul_f32 v[94:95], v[94:95], v[170:171]
	v_pk_mul_f32 v[92:93], v[92:93], v[130:131]
	v_pk_mul_f32 v[90:91], v[90:91], v[172:173]
	global_load_dwordx4 v[130:133], v[174:175], off offset:256
	global_load_dwordx4 v[170:173], v[158:159], off offset:256
	v_pk_mul_f32 v[176:177], v[176:177], v[180:181]
	s_waitcnt vmcnt(0)
	v_lshlrev_b32_e32 v158, 16, v170
	v_and_b32_e32 v159, 0xffff0000, v170
	v_lshlrev_b32_e32 v169, 16, v171
	v_and_b32_e32 v174, 0xffff0000, v171
	v_lshlrev_b32_e32 v170, 16, v172
	v_and_b32_e32 v171, 0xffff0000, v172
	v_max_f32_e32 v158, v158, v158
	v_max_f32_e32 v159, v159, v159
	v_pk_mul_f32 v[96:97], v[96:97], v[176:177]
	v_lshlrev_b32_e32 v175, 16, v173
	v_and_b32_e32 v176, 0xffff0000, v173
	v_max_f32_e32 v158, 0xda24260, v158
	v_max_f32_e32 v170, v170, v170
	v_max_f32_e32 v159, 0xda24260, v159
	v_lshlrev_b32_e32 v172, 16, v130
	v_and_b32_e32 v173, 0xffff0000, v130
	v_max_f32_e32 v130, v171, v171
	v_rcp_f32_e32 v158, v158
	v_max_f32_e32 v170, 0xda24260, v170
	v_rcp_f32_e32 v159, v159
	v_max_f32_e32 v130, 0xda24260, v130
	v_rcp_f32_e32 v170, v170
	v_rcp_f32_e32 v171, v130
	v_max_f32_e32 v130, v169, v169
	v_pk_mul_f32 v[158:159], v[158:159], v[172:173]
	v_lshlrev_b32_e32 v172, 16, v132
	v_and_b32_e32 v173, 0xffff0000, v132
	v_max_f32_e32 v130, 0xda24260, v130
	v_pk_mul_f32 v[170:171], v[170:171], v[172:173]
	v_rcp_f32_e32 v172, v130
	v_max_f32_e32 v130, v175, v175
	v_max_f32_e32 v132, v174, v174
	v_lshlrev_b32_e32 v174, 16, v131
	v_and_b32_e32 v175, 0xffff0000, v131
	v_max_f32_e32 v131, v176, v176
	v_max_f32_e32 v130, 0xda24260, v130
	v_max_f32_e32 v131, 0xda24260, v131
	v_rcp_f32_e32 v130, v130
	v_rcp_f32_e32 v131, v131
	v_max_f32_e32 v132, 0xda24260, v132
	v_rcp_f32_e32 v173, v132
	v_lshlrev_b32_e32 v132, 16, v133
	v_and_b32_e32 v133, 0xffff0000, v133
	v_pk_mul_f32 v[130:131], v[130:131], v[132:133]
	v_pk_mul_f32 v[110:111], v[110:111], v[158:159]
	v_pk_mul_f32 v[108:109], v[108:109], v[130:131]
	v_add_u32_e32 v130, 0x80, v168
	v_mad_i64_i32 v[158:159], s[58:59], v130, s78, v[156:157]
	v_pk_mul_f32 v[172:173], v[172:173], v[174:175]
	v_add_co_u32_e32 v174, vcc, s61, v158
	v_pk_mul_f32 v[112:113], v[112:113], v[172:173]
	s_nop 0
	v_addc_co_u32_e32 v175, vcc, 0, v159, vcc
	v_add_co_u32_e32 v158, vcc, s77, v158
	v_pk_mul_f32 v[106:107], v[106:107], v[170:171]
	s_nop 0
	v_addc_co_u32_e32 v159, vcc, 0, v159, vcc
	global_load_dwordx4 v[130:133], v[174:175], off
	global_load_dwordx4 v[170:173], v[158:159], off
	s_waitcnt vmcnt(1)
	v_and_b32_e32 v177, 0xffff0000, v130
	s_waitcnt vmcnt(0)
	v_lshlrev_b32_e32 v169, 16, v170
	v_max_f32_e32 v169, v169, v169
	v_lshlrev_b32_e32 v178, 16, v171
	v_and_b32_e32 v179, 0xffff0000, v171
	v_lshlrev_b32_e32 v171, 16, v172
	v_max_f32_e32 v169, 0xda24260, v169
	v_and_b32_e32 v176, 0xffff0000, v170
	v_rcp_f32_e32 v170, v169
	v_max_f32_e32 v169, v171, v171
	v_max_f32_e32 v169, 0xda24260, v169
	v_and_b32_e32 v180, 0xffff0000, v172
	v_rcp_f32_e32 v172, v169
	v_max_f32_e32 v169, v176, v176
	v_max_f32_e32 v169, 0xda24260, v169
	v_lshlrev_b32_e32 v176, 16, v130
	v_max_f32_e32 v130, v180, v180
	v_rcp_f32_e32 v171, v169
	v_max_f32_e32 v130, 0xda24260, v130
	v_lshlrev_b32_e32 v181, 16, v173
	v_and_b32_e32 v182, 0xffff0000, v173
	v_rcp_f32_e32 v173, v130
	v_max_f32_e32 v130, v178, v178
	v_pk_mul_f32 v[170:171], v[170:171], v[176:177]
	v_lshlrev_b32_e32 v176, 16, v132
	v_and_b32_e32 v177, 0xffff0000, v132
	v_max_f32_e32 v130, 0xda24260, v130
	v_pk_mul_f32 v[172:173], v[172:173], v[176:177]
	v_rcp_f32_e32 v176, v130
	v_max_f32_e32 v130, v181, v181
	v_lshlrev_b32_e32 v180, 16, v131
	v_and_b32_e32 v181, 0xffff0000, v131
	v_max_f32_e32 v131, v182, v182
	v_max_f32_e32 v130, 0xda24260, v130
	v_max_f32_e32 v131, 0xda24260, v131
	v_rcp_f32_e32 v130, v130
	v_rcp_f32_e32 v131, v131
	v_max_f32_e32 v132, v179, v179
	v_max_f32_e32 v132, 0xda24260, v132
	v_rcp_f32_e32 v177, v132
	v_lshlrev_b32_e32 v132, 16, v133
	v_and_b32_e32 v133, 0xffff0000, v133
	v_pk_mul_f32 v[130:131], v[130:131], v[132:133]
	v_pk_mul_f32 v[126:127], v[126:127], v[170:171]
	v_pk_mul_f32 v[124:125], v[124:125], v[130:131]
	v_pk_mul_f32 v[122:123], v[122:123], v[172:173]
	global_load_dwordx4 v[130:133], v[174:175], off offset:256
	global_load_dwordx4 v[170:173], v[158:159], off offset:256
	v_pk_mul_f32 v[176:177], v[176:177], v[180:181]
	s_waitcnt vmcnt(0)
; __device__ __forceinline__ float bflo(unsigned w) { return __uint_as_float(w << 16); }
; __device__ __forceinline__ float bfhi(unsigned w) { return __uint_as_float(w & 0xffff0000u); }
;     __device__ __forceinline__ void mid(f32x4 (&acc)[2][2][4][2], const Unit& u, int wr, int wc, int fr, int fq) const {
;     ...
;             for (int m = 0; m < 4; ++m) { const bf16_t* pr = P + (size_t)(row0 + ai * HALF + m * 16) * NP + col0;
; #pragma unroll
;                 for (int bj = 0; bj < 2; ++bj) { const u32x4 a = *(const u32x4*)(pr + PC_GA + bj * HALF), b = *(const u32x4*)(pr + PC_GB + bj * HALF);
;                     const f32x4 b0 = {bflo(b.x), bfhi(b.x), bflo(b.y), bfhi(b.y)}, b1 = {bflo(b.z), bfhi(b.z), bflo(b.w), bfhi(b.w)};
;                     const f32x4 a0 = {bflo(a.x), bfhi(a.x), bflo(a.y), bfhi(a.y)}, a1 = {bflo(a.z), bfhi(a.z), bflo(a.w), bfhi(a.w)};
;                     f32x4 r0, r1;
; #pragma unroll
;                     for (int j = 0; j < 4; ++j) { r0[j] = a0[j] * __builtin_amdgcn_rcpf(fmaxf(b0[j], 1e-30f)); r1[j] = a1[j] * __builtin_amdgcn_rcpf(fmaxf(b1[j], 1e-30f)); }
;                     acc[ai][bj][m][0] *= r0; acc[ai][bj][m][1] *= r1; }
;                 asm volatile("" ::: "memory"); }
	v_lshlrev_b32_e32 v158, 16, v170
	v_and_b32_e32 v159, 0xffff0000, v170
	v_lshlrev_b32_e32 v169, 16, v171
	v_and_b32_e32 v174, 0xffff0000, v171
	v_lshlrev_b32_e32 v170, 16, v172
	v_and_b32_e32 v171, 0xffff0000, v172
	v_max_f32_e32 v158, v158, v158
	v_max_f32_e32 v159, v159, v159
	v_pk_mul_f32 v[128:129], v[128:129], v[176:177]
	v_lshlrev_b32_e32 v175, 16, v173
	v_and_b32_e32 v176, 0xffff0000, v173
	v_max_f32_e32 v158, 0xda24260, v158
	v_max_f32_e32 v170, v170, v170
	v_max_f32_e32 v159, 0xda24260, v159
	v_lshlrev_b32_e32 v172, 16, v130
	v_and_b32_e32 v173, 0xffff0000, v130
	v_max_f32_e32 v130, v171, v171
	v_rcp_f32_e32 v158, v158
	v_max_f32_e32 v170, 0xda24260, v170
	v_rcp_f32_e32 v159, v159
	v_max_f32_e32 v130, 0xda24260, v130
	v_rcp_f32_e32 v170, v170
	v_rcp_f32_e32 v171, v130
	v_max_f32_e32 v130, v169, v169
	v_pk_mul_f32 v[158:159], v[158:159], v[172:173]
	v_lshlrev_b32_e32 v172, 16, v132
	v_and_b32_e32 v173, 0xffff0000, v132
	v_max_f32_e32 v130, 0xda24260, v130
	v_pk_mul_f32 v[170:171], v[170:171], v[172:173]
	v_rcp_f32_e32 v172, v130
	v_max_f32_e32 v130, v175, v175
	v_max_f32_e32 v132, v174, v174
	v_lshlrev_b32_e32 v174, 16, v131
	v_and_b32_e32 v175, 0xffff0000, v131
	v_max_f32_e32 v131, v176, v176
	v_max_f32_e32 v130, 0xda24260, v130
	v_max_f32_e32 v131, 0xda24260, v131
	v_rcp_f32_e32 v130, v130
	v_rcp_f32_e32 v131, v131
	v_max_f32_e32 v132, 0xda24260, v132
	v_rcp_f32_e32 v173, v132
	v_lshlrev_b32_e32 v132, 16, v133
	v_and_b32_e32 v133, 0xffff0000, v133
	v_pk_mul_f32 v[130:131], v[130:131], v[132:133]
	v_pk_mul_f32 v[118:119], v[118:119], v[158:159]
	v_pk_mul_f32 v[116:117], v[116:117], v[130:131]
	v_add_u32_e32 v130, 0x90, v168
	v_mad_i64_i32 v[158:159], s[58:59], v130, s78, v[156:157]
	v_pk_mul_f32 v[172:173], v[172:173], v[174:175]
	v_add_co_u32_e32 v174, vcc, s61, v158
	v_pk_mul_f32 v[120:121], v[120:121], v[172:173]
	s_nop 0
	v_addc_co_u32_e32 v175, vcc, 0, v159, vcc
	v_add_co_u32_e32 v158, vcc, s77, v158
	v_pk_mul_f32 v[114:115], v[114:115], v[170:171]
	s_nop 0
	v_addc_co_u32_e32 v159, vcc, 0, v159, vcc
	global_load_dwordx4 v[130:133], v[174:175], off
	global_load_dwordx4 v[170:173], v[158:159], off
	s_waitcnt vmcnt(1)
	v_and_b32_e32 v177, 0xffff0000, v130
	s_waitcnt vmcnt(0)
	v_lshlrev_b32_e32 v169, 16, v170
	v_max_f32_e32 v169, v169, v169
	v_lshlrev_b32_e32 v178, 16, v171
	v_and_b32_e32 v179, 0xffff0000, v171
	v_lshlrev_b32_e32 v171, 16, v172
	v_max_f32_e32 v169, 0xda24260, v169
	v_and_b32_e32 v176, 0xffff0000, v170
	v_rcp_f32_e32 v170, v169
	v_max_f32_e32 v169, v171, v171
	v_max_f32_e32 v169, 0xda24260, v169
	v_and_b32_e32 v180, 0xffff0000, v172
	v_rcp_f32_e32 v172, v169
	v_max_f32_e32 v169, v176, v176
	v_max_f32_e32 v169, 0xda24260, v169
	v_lshlrev_b32_e32 v176, 16, v130
	v_max_f32_e32 v130, v180, v180
	v_rcp_f32_e32 v171, v169
	v_max_f32_e32 v130, 0xda24260, v130
	v_lshlrev_b32_e32 v181, 16, v173
	v_and_b32_e32 v182, 0xffff0000, v173
	v_rcp_f32_e32 v173, v130
	v_max_f32_e32 v130, v178, v178
	v_pk_mul_f32 v[170:171], v[170:171], v[176:177]
	v_lshlrev_b32_e32 v176, 16, v132
	v_and_b32_e32 v177, 0xffff0000, v132
	v_max_f32_e32 v130, 0xda24260, v130
	v_pk_mul_f32 v[172:173], v[172:173], v[176:177]
	v_rcp_f32_e32 v176, v130
	v_max_f32_e32 v130, v181, v181
	v_lshlrev_b32_e32 v180, 16, v131
	v_and_b32_e32 v181, 0xffff0000, v131
	v_max_f32_e32 v131, v182, v182
	v_max_f32_e32 v130, 0xda24260, v130
	v_max_f32_e32 v131, 0xda24260, v131
	v_rcp_f32_e32 v130, v130
	v_rcp_f32_e32 v131, v131
	v_max_f32_e32 v132, v179, v179
	v_max_f32_e32 v132, 0xda24260, v132
	v_rcp_f32_e32 v177, v132
	v_lshlrev_b32_e32 v132, 16, v133
	v_and_b32_e32 v133, 0xffff0000, v133
	v_pk_mul_f32 v[130:131], v[130:131], v[132:133]
	v_pk_mul_f32 v[102:103], v[102:103], v[170:171]
	v_pk_mul_f32 v[100:101], v[100:101], v[130:131]
	v_pk_mul_f32 v[98:99], v[98:99], v[172:173]
	global_load_dwordx4 v[130:133], v[174:175], off offset:256
	global_load_dwordx4 v[170:173], v[158:159], off offset:256
	v_pk_mul_f32 v[176:177], v[176:177], v[180:181]
	s_waitcnt vmcnt(0)
	v_lshlrev_b32_e32 v158, 16, v170
	v_and_b32_e32 v159, 0xffff0000, v170
	v_lshlrev_b32_e32 v169, 16, v171
	v_and_b32_e32 v174, 0xffff0000, v171
	v_lshlrev_b32_e32 v170, 16, v172
	v_and_b32_e32 v171, 0xffff0000, v172
	v_max_f32_e32 v158, v158, v158
	v_max_f32_e32 v159, v159, v159
	v_pk_mul_f32 v[104:105], v[104:105], v[176:177]
	v_lshlrev_b32_e32 v175, 16, v173
	v_and_b32_e32 v176, 0xffff0000, v173
	v_max_f32_e32 v158, 0xda24260, v158
	v_max_f32_e32 v170, v170, v170
	v_max_f32_e32 v159, 0xda24260, v159
	v_lshlrev_b32_e32 v172, 16, v130
	v_and_b32_e32 v173, 0xffff0000, v130
	v_max_f32_e32 v130, v171, v171
	v_rcp_f32_e32 v158, v158
	v_max_f32_e32 v170, 0xda24260, v170
	v_rcp_f32_e32 v159, v159
	v_max_f32_e32 v130, 0xda24260, v130
	v_rcp_f32_e32 v170, v170
	v_rcp_f32_e32 v171, v130
	v_max_f32_e32 v130, v169, v169
	v_pk_mul_f32 v[158:159], v[158:159], v[172:173]
	v_lshlrev_b32_e32 v172, 16, v132
	v_and_b32_e32 v173, 0xffff0000, v132
	v_max_f32_e32 v130, 0xda24260, v130
	v_pk_mul_f32 v[170:171], v[170:171], v[172:173]
	v_rcp_f32_e32 v172, v130
	v_max_f32_e32 v130, v175, v175
	v_max_f32_e32 v132, v174, v174
	v_lshlrev_b32_e32 v174, 16, v131
	v_and_b32_e32 v175, 0xffff0000, v131
	v_max_f32_e32 v131, v176, v176
	v_max_f32_e32 v130, 0xda24260, v130
	v_max_f32_e32 v131, 0xda24260, v131
	v_rcp_f32_e32 v130, v130
	v_rcp_f32_e32 v131, v131
	v_max_f32_e32 v132, 0xda24260, v132
	v_rcp_f32_e32 v173, v132
	v_lshlrev_b32_e32 v132, 16, v133
	v_and_b32_e32 v133, 0xffff0000, v133
	v_pk_mul_f32 v[130:131], v[130:131], v[132:133]
	v_pk_mul_f32 v[78:79], v[78:79], v[158:159]
	v_pk_mul_f32 v[76:77], v[76:77], v[130:131]
	v_add_u32_e32 v130, 0xa0, v168
	v_mad_i64_i32 v[158:159], s[58:59], v130, s78, v[156:157]
	v_pk_mul_f32 v[172:173], v[172:173], v[174:175]
	v_add_co_u32_e32 v174, vcc, s61, v158
	v_pk_mul_f32 v[80:81], v[80:81], v[172:173]
	s_nop 0
	v_addc_co_u32_e32 v175, vcc, 0, v159, vcc
	v_add_co_u32_e32 v158, vcc, s77, v158
	v_pk_mul_f32 v[74:75], v[74:75], v[170:171]
	s_nop 0
	v_addc_co_u32_e32 v159, vcc, 0, v159, vcc
	global_load_dwordx4 v[130:133], v[174:175], off
	global_load_dwordx4 v[170:173], v[158:159], off
	s_waitcnt vmcnt(1)
; __device__ __forceinline__ float bflo(unsigned w) { return __uint_as_float(w << 16); }
; __device__ __forceinline__ float bfhi(unsigned w) { return __uint_as_float(w & 0xffff0000u); }
;     __device__ __forceinline__ void mid(f32x4 (&acc)[2][2][4][2], const Unit& u, int wr, int wc, int fr, int fq) const {
;     ...
;             for (int m = 0; m < 4; ++m) { const bf16_t* pr = P + (size_t)(row0 + ai * HALF + m * 16) * NP + col0;
; #pragma unroll
;                 for (int bj = 0; bj < 2; ++bj) { const u32x4 a = *(const u32x4*)(pr + PC_GA + bj * HALF), b = *(const u32x4*)(pr + PC_GB + bj * HALF);
;                     const f32x4 b0 = {bflo(b.x), bfhi(b.x), bflo(b.y), bfhi(b.y)}, b1 = {bflo(b.z), bfhi(b.z), bflo(b.w), bfhi(b.w)};
;                     const f32x4 a0 = {bflo(a.x), bfhi(a.x), bflo(a.y), bfhi(a.y)}, a1 = {bflo(a.z), bfhi(a.z), bflo(a.w), bfhi(a.w)};
;                     f32x4 r0, r1;
; #pragma unroll
;                     for (int j = 0; j < 4; ++j) { r0[j] = a0[j] * __builtin_amdgcn_rcpf(fmaxf(b0[j], 1e-30f)); r1[j] = a1[j] * __builtin_amdgcn_rcpf(fmaxf(b1[j], 1e-30f)); }
;                     acc[ai][bj][m][0] *= r0; acc[ai][bj][m][1] *= r1; }
;                 asm volatile("" ::: "memory"); }
	v_and_b32_e32 v177, 0xffff0000, v130
	s_waitcnt vmcnt(0)
	v_lshlrev_b32_e32 v169, 16, v170
	v_max_f32_e32 v169, v169, v169
	v_lshlrev_b32_e32 v178, 16, v171
	v_and_b32_e32 v179, 0xffff0000, v171
	v_lshlrev_b32_e32 v171, 16, v172
	v_max_f32_e32 v169, 0xda24260, v169
	v_and_b32_e32 v176, 0xffff0000, v170
	v_rcp_f32_e32 v170, v169
	v_max_f32_e32 v169, v171, v171
	v_max_f32_e32 v169, 0xda24260, v169
	v_and_b32_e32 v180, 0xffff0000, v172
	v_rcp_f32_e32 v172, v169
	v_max_f32_e32 v169, v176, v176
	v_max_f32_e32 v169, 0xda24260, v169
	v_lshlrev_b32_e32 v176, 16, v130
	v_max_f32_e32 v130, v180, v180
	v_rcp_f32_e32 v171, v169
	v_max_f32_e32 v130, 0xda24260, v130
	v_lshlrev_b32_e32 v181, 16, v173
	v_and_b32_e32 v182, 0xffff0000, v173
	v_rcp_f32_e32 v173, v130
	v_max_f32_e32 v130, v178, v178
	v_pk_mul_f32 v[170:171], v[170:171], v[176:177]
	v_lshlrev_b32_e32 v176, 16, v132
	v_and_b32_e32 v177, 0xffff0000, v132
	v_max_f32_e32 v130, 0xda24260, v130
	v_pk_mul_f32 v[172:173], v[172:173], v[176:177]
	v_rcp_f32_e32 v176, v130
	v_max_f32_e32 v130, v181, v181
	v_lshlrev_b32_e32 v180, 16, v131
	v_and_b32_e32 v181, 0xffff0000, v131
	v_max_f32_e32 v131, v182, v182
	v_max_f32_e32 v130, 0xda24260, v130
	v_max_f32_e32 v131, 0xda24260, v131
	v_rcp_f32_e32 v130, v130
	v_rcp_f32_e32 v131, v131
	v_max_f32_e32 v132, v179, v179
	v_max_f32_e32 v132, 0xda24260, v132
	v_rcp_f32_e32 v177, v132
	v_lshlrev_b32_e32 v132, 16, v133
	v_and_b32_e32 v133, 0xffff0000, v133
	v_pk_mul_f32 v[130:131], v[130:131], v[132:133]
	v_pk_mul_f32 v[62:63], v[62:63], v[170:171]
	v_pk_mul_f32 v[60:61], v[60:61], v[130:131]
	v_pk_mul_f32 v[58:59], v[58:59], v[172:173]
	global_load_dwordx4 v[130:133], v[174:175], off offset:256
	global_load_dwordx4 v[170:173], v[158:159], off offset:256
	v_pk_mul_f32 v[176:177], v[176:177], v[180:181]
	s_waitcnt vmcnt(0)
	v_lshlrev_b32_e32 v158, 16, v170
	v_and_b32_e32 v159, 0xffff0000, v170
	v_lshlrev_b32_e32 v169, 16, v171
	v_and_b32_e32 v174, 0xffff0000, v171
	v_lshlrev_b32_e32 v170, 16, v172
	v_and_b32_e32 v171, 0xffff0000, v172
	v_max_f32_e32 v158, v158, v158
	v_max_f32_e32 v159, v159, v159
	v_pk_mul_f32 v[64:65], v[64:65], v[176:177]
	v_lshlrev_b32_e32 v175, 16, v173
	v_and_b32_e32 v176, 0xffff0000, v173
	v_max_f32_e32 v158, 0xda24260, v158
	v_max_f32_e32 v170, v170, v170
	v_max_f32_e32 v159, 0xda24260, v159
	v_lshlrev_b32_e32 v172, 16, v130
	v_and_b32_e32 v173, 0xffff0000, v130
	v_max_f32_e32 v130, v171, v171
	v_rcp_f32_e32 v158, v158
	v_max_f32_e32 v170, 0xda24260, v170
	v_rcp_f32_e32 v159, v159
	v_max_f32_e32 v130, 0xda24260, v130
	v_rcp_f32_e32 v170, v170
	v_rcp_f32_e32 v171, v130
	v_max_f32_e32 v130, v169, v169
	v_pk_mul_f32 v[158:159], v[158:159], v[172:173]
	v_lshlrev_b32_e32 v172, 16, v132
	v_and_b32_e32 v173, 0xffff0000, v132
	v_max_f32_e32 v130, 0xda24260, v130
	v_pk_mul_f32 v[170:171], v[170:171], v[172:173]
	v_rcp_f32_e32 v172, v130
	v_max_f32_e32 v130, v175, v175
	v_max_f32_e32 v132, v174, v174
	v_lshlrev_b32_e32 v174, 16, v131
	v_and_b32_e32 v175, 0xffff0000, v131
	v_max_f32_e32 v131, v176, v176
	v_max_f32_e32 v130, 0xda24260, v130
	v_max_f32_e32 v131, 0xda24260, v131
	v_rcp_f32_e32 v130, v130
	v_rcp_f32_e32 v131, v131
	v_max_f32_e32 v132, 0xda24260, v132
	v_rcp_f32_e32 v173, v132
	v_lshlrev_b32_e32 v132, 16, v133
	v_and_b32_e32 v133, 0xffff0000, v133
	v_pk_mul_f32 v[130:131], v[130:131], v[132:133]
	v_pk_mul_f32 v[46:47], v[46:47], v[158:159]
	v_pk_mul_f32 v[44:45], v[44:45], v[130:131]
	v_add_u32_e32 v130, 0xb0, v168
	v_mad_i64_i32 v[156:157], s[58:59], v130, s78, v[156:157]
	v_add_co_u32_e32 v158, vcc, s61, v156
	v_pk_mul_f32 v[42:43], v[42:43], v[170:171]
	s_nop 0
	v_addc_co_u32_e32 v159, vcc, 0, v157, vcc
	v_add_co_u32_e32 v156, vcc, s77, v156
	global_load_dwordx4 v[130:133], v[158:159], off
	s_nop 0
	v_addc_co_u32_e32 v157, vcc, 0, v157, vcc
	global_load_dwordx4 v[168:171], v[156:157], off
	v_pk_mul_f32 v[172:173], v[172:173], v[174:175]
	s_waitcnt vmcnt(0)
	v_lshlrev_b32_e32 v174, 16, v169
	v_and_b32_e32 v175, 0xffff0000, v169
	v_lshlrev_b32_e32 v169, 16, v170
	v_max_f32_e32 v169, v169, v169
	v_pk_mul_f32 v[48:49], v[48:49], v[172:173]
	v_lshlrev_b32_e32 v172, 16, v168
	v_and_b32_e32 v173, 0xffff0000, v168
	v_max_f32_e32 v169, 0xda24260, v169
	v_and_b32_e32 v176, 0xffff0000, v170
	v_max_f32_e32 v168, v172, v172
	v_rcp_f32_e32 v170, v169
	v_max_f32_e32 v169, v173, v173
	v_max_f32_e32 v168, 0xda24260, v168
	v_max_f32_e32 v169, 0xda24260, v169
	v_lshlrev_b32_e32 v172, 16, v130
	v_and_b32_e32 v173, 0xffff0000, v130
	v_max_f32_e32 v130, v176, v176
	v_rcp_f32_e32 v168, v168
	v_rcp_f32_e32 v169, v169
	v_max_f32_e32 v130, 0xda24260, v130
	v_lshlrev_b32_e32 v177, 16, v171
	v_and_b32_e32 v178, 0xffff0000, v171
	v_rcp_f32_e32 v171, v130
	v_max_f32_e32 v130, v174, v174
	v_pk_mul_f32 v[168:169], v[168:169], v[172:173]
	v_lshlrev_b32_e32 v172, 16, v132
	v_and_b32_e32 v173, 0xffff0000, v132
	v_max_f32_e32 v130, 0xda24260, v130
	v_pk_mul_f32 v[170:171], v[170:171], v[172:173]
	v_rcp_f32_e32 v172, v130
	v_max_f32_e32 v130, v177, v177
	v_max_f32_e32 v132, v175, v175
	v_lshlrev_b32_e32 v174, 16, v131
	v_and_b32_e32 v175, 0xffff0000, v131
	v_max_f32_e32 v131, v178, v178
	v_max_f32_e32 v130, 0xda24260, v130
	v_max_f32_e32 v131, 0xda24260, v131
	v_rcp_f32_e32 v130, v130
	v_rcp_f32_e32 v131, v131
	v_max_f32_e32 v132, 0xda24260, v132
	v_rcp_f32_e32 v173, v132
	v_lshlrev_b32_e32 v132, 16, v133
	v_and_b32_e32 v133, 0xffff0000, v133
	v_pk_mul_f32 v[130:131], v[130:131], v[132:133]
	v_pk_mul_f32 v[18:19], v[18:19], v[170:171]
	v_pk_mul_f32 v[20:21], v[20:21], v[130:131]
	global_load_dwordx4 v[130:133], v[158:159], off offset:256
	s_nop 0
	global_load_dwordx4 v[156:159], v[156:157], off offset:256
	v_pk_mul_f32 v[172:173], v[172:173], v[174:175]
	v_pk_mul_f32 v[22:23], v[22:23], v[168:169]
	v_pk_mul_f32 v[24:25], v[24:25], v[172:173]
	s_waitcnt vmcnt(0)
; __device__ __forceinline__ float bflo(unsigned w) { return __uint_as_float(w << 16); }
; __device__ __forceinline__ float bfhi(unsigned w) { return __uint_as_float(w & 0xffff0000u); }
; #define PG8_WAIT_V(n) asm volatile("s_waitcnt vmcnt(" #n ")" ::: "memory")
; #define PG8_BAR __builtin_amdgcn_s_barrier()
;     __device__ __forceinline__ void mid(f32x4 (&acc)[2][2][4][2], const Unit& u, int wr, int wc, int fr, int fq) const {
;     ...
;                 for (int bj = 0; bj < 2; ++bj) { const u32x4 a = *(const u32x4*)(pr + PC_GA + bj * HALF), b = *(const u32x4*)(pr + PC_GB + bj * HALF);
;                     const f32x4 b0 = {bflo(b.x), bfhi(b.x), bflo(b.y), bfhi(b.y)}, b1 = {bflo(b.z), bfhi(b.z), bflo(b.w), bfhi(b.w)};
;                     const f32x4 a0 = {bflo(a.x), bfhi(a.x), bflo(a.y), bfhi(a.y)}, a1 = {bflo(a.z), bfhi(a.z), bflo(a.w), bfhi(a.w)};
;                     f32x4 r0, r1;
; #pragma unroll
;                     for (int j = 0; j < 4; ++j) { r0[j] = a0[j] * __builtin_amdgcn_rcpf(fmaxf(b0[j], 1e-30f)); r1[j] = a1[j] * __builtin_amdgcn_rcpf(fmaxf(b1[j], 1e-30f)); }
;                     acc[ai][bj][m][0] *= r0; acc[ai][bj][m][1] *= r1; }
; template <class Epi, class Sched, bool ALIGN_EPI = false, bool SP2 = false>
; __device__ __forceinline__ void gemm_phase(PG8_LAS unsigned char* lds, const Gemm g, const Sched& S, const Epi& E) {
;     ...
;             PG8_LDB(B0, 0, 0); PG8_LDB(B1, 0, 1); PG8_SCHED; PG8_LDA(At, 0, 0); PG8_STAGE(PG8_SA(1, 1), a1 + hstep, voffA);
;             PG8_WAIT_V(8); PG8_WAIT_L(0); PG8_BAR; PG8_MMA(0, 0, At, B0); PG8_MMA(0, 1, At, B1); PG8_BAR; PG8_SCHED;
;             PG8_LDA(At, 0, 1); PG8_STAGE(PG8_SB(0, 0), b2, voffB); PG8_STAGE(PG8_SB(0, 1), b2 + hstep, voffB); PG8_STAGE(PG8_SA(0, 0), a2, voffA);
;             PG8_WAIT_V(8); PG8_WAIT_L(0); PG8_BAR; PG8_MMA(1, 0, At, B0); PG8_MMA(1, 1, At, B1); PG8_BAR; PG8_SCHED;
;             PG8_LDB(B0, 1, 0); PG8_LDB(B1, 1, 1); PG8_SCHED; PG8_LDA(At, 1, 0); PG8_STAGE(PG8_SA(0, 1), a2 + hstep, voffA);
;             PG8_WAIT_V(8); PG8_WAIT_L(0); PG8_BAR; PG8_MMA(0, 0, At, B0); PG8_MMA(0, 1, At, B1); PG8_BAR; PG8_SCHED;
;             PG8_LDA(At, 1, 1); PG8_STAGE(PG8_SB(1, 0), b3, voffB); PG8_STAGE(PG8_SB(1, 1), b3 + hstep, voffB); PG8_STAGE(PG8_SA(1, 0), a3, voffA);
;             PG8_WAIT_V(8); PG8_WAIT_L(0); PG8_BAR; PG8_MMA(1, 0, At, B0); PG8_MMA(1, 1, At, B1); PG8_BAR; PG8_SCHED;
	v_lshlrev_b32_e32 v170, 16, v157
	v_and_b32_e32 v171, 0xffff0000, v157
	v_lshlrev_b32_e32 v157, 16, v158
	v_max_f32_e32 v157, v157, v157
	v_lshlrev_b32_e32 v168, 16, v156
	v_and_b32_e32 v169, 0xffff0000, v156
	v_max_f32_e32 v157, 0xda24260, v157
	v_and_b32_e32 v172, 0xffff0000, v158
	v_max_f32_e32 v156, v168, v168
	v_rcp_f32_e32 v158, v157
	v_max_f32_e32 v157, v169, v169
	v_max_f32_e32 v156, 0xda24260, v156
	v_max_f32_e32 v157, 0xda24260, v157
	v_lshlrev_b32_e32 v168, 16, v130
	v_and_b32_e32 v169, 0xffff0000, v130
	v_max_f32_e32 v130, v172, v172
	v_rcp_f32_e32 v156, v156
	v_rcp_f32_e32 v157, v157
	v_max_f32_e32 v130, 0xda24260, v130
	v_lshlrev_b32_e32 v173, 16, v159
	v_and_b32_e32 v174, 0xffff0000, v159
	v_rcp_f32_e32 v159, v130
	v_max_f32_e32 v130, v170, v170
	v_pk_mul_f32 v[156:157], v[156:157], v[168:169]
	v_lshlrev_b32_e32 v168, 16, v132
	v_and_b32_e32 v169, 0xffff0000, v132
	v_max_f32_e32 v130, 0xda24260, v130
	v_pk_mul_f32 v[158:159], v[158:159], v[168:169]
	v_rcp_f32_e32 v168, v130
	v_max_f32_e32 v130, v173, v173
	v_max_f32_e32 v132, v171, v171
	v_lshlrev_b32_e32 v170, 16, v131
	v_and_b32_e32 v171, 0xffff0000, v131
	v_max_f32_e32 v131, v174, v174
	v_max_f32_e32 v130, 0xda24260, v130
	v_max_f32_e32 v132, 0xda24260, v132
	v_max_f32_e32 v131, 0xda24260, v131
	v_rcp_f32_e32 v130, v130
	v_rcp_f32_e32 v169, v132
	v_rcp_f32_e32 v131, v131
	v_lshlrev_b32_e32 v132, 16, v133
	v_and_b32_e32 v133, 0xffff0000, v133
	v_pk_mul_f32 v[168:169], v[168:169], v[170:171]
	v_pk_mul_f32 v[130:131], v[130:131], v[132:133]
	v_pk_mul_f32 v[8:9], v[8:9], v[168:169]
	v_pk_mul_f32 v[6:7], v[6:7], v[156:157]
	v_pk_mul_f32 v[4:5], v[4:5], v[130:131]
	v_pk_mul_f32 v[2:3], v[2:3], v[158:159]
.LBB0_684:
	ds_read_b128 v[130:133], v163
	ds_read_b128 v[156:159], v163 offset:1024
	ds_read_b128 v[168:171], v163 offset:2048
	ds_read_b128 v[172:175], v163 offset:3072
	ds_read_b128 v[180:183], v164
	ds_read_b128 v[184:187], v164 offset:1024
	ds_read_b128 v[188:191], v164 offset:2048
	ds_read_b128 v[198:201], v164 offset:3072
	s_add_u32 s48, s50, 0x4000
	s_addc_u32 s49, s51, 0
	s_cmp_eq_u32 s56, 60
	s_cselect_b32 s72, s93, s48
	s_cselect_b32 s73, s41, s49
	s_cselect_b32 s70, s97, s26
	s_cselect_b32 s71, s27, s33
	s_add_u32 s48, s72, 0x8000
	s_addc_u32 s49, s73, 0
	s_mov_b32 m0, s83
	ds_read_b128 v[202:205], v165
	ds_read_b128 v[206:209], v165 offset:1024
	ds_read_b128 v[210:213], v165 offset:2048
	ds_read_b128 v[214:217], v165 offset:3072
	ds_read_b128 v[218:221], v165 offset:4096
	ds_read_b128 v[222:225], v165 offset:5120
	ds_read_b128 v[226:229], v165 offset:6144
	ds_read_b128 v[230:233], v165 offset:7168
	global_load_lds_dwordx4 v144, s[50:51]
	s_mov_b32 m0, s84
	s_nop 0
	global_load_lds_dwordx4 v146, s[50:51]
	s_waitcnt vmcnt(8)
	s_waitcnt lgkmcnt(0)
	s_barrier
	s_setprio 0
	s_waitcnt lgkmcnt(0)
	v_mfma_f32_16x16x32_bf16 v[14:17], v[130:133], v[202:205], v[14:17]
	v_mfma_f32_16x16x32_bf16 v[14:17], v[156:159], v[206:209], v[14:17]
	v_mfma_f32_16x16x32_bf16 v[38:41], v[130:133], v[210:213], v[38:41]
	v_mfma_f32_16x16x32_bf16 v[38:41], v[156:159], v[214:217], v[38:41]
	v_mfma_f32_16x16x32_bf16 v[70:73], v[130:133], v[218:221], v[70:73]
	v_mfma_f32_16x16x32_bf16 v[70:73], v[156:159], v[222:225], v[70:73]
	v_mfma_f32_16x16x32_bf16 v[94:97], v[130:133], v[226:229], v[94:97]
	v_mfma_f32_16x16x32_bf16 v[94:97], v[156:159], v[230:233], v[94:97]
	v_mfma_f32_16x16x32_bf16 v[90:93], v[168:171], v[226:229], v[90:93]
	v_mfma_f32_16x16x32_bf16 v[90:93], v[172:175], v[230:233], v[90:93]
	v_mfma_f32_16x16x32_bf16 v[66:69], v[168:171], v[218:221], v[66:69]
	v_mfma_f32_16x16x32_bf16 v[66:69], v[172:175], v[222:225], v[66:69]
	v_mfma_f32_16x16x32_bf16 v[34:37], v[168:171], v[210:213], v[34:37]
	v_mfma_f32_16x16x32_bf16 v[34:37], v[172:175], v[214:217], v[34:37]
	v_mfma_f32_16x16x32_bf16 v[10:13], v[168:171], v[202:205], v[10:13]
	v_mfma_f32_16x16x32_bf16 v[10:13], v[172:175], v[206:209], v[10:13]
	v_mfma_f32_16x16x32_bf16 v[30:33], v[180:183], v[202:205], v[30:33]
	v_mfma_f32_16x16x32_bf16 v[30:33], v[184:187], v[206:209], v[30:33]
	v_mfma_f32_16x16x32_bf16 v[54:57], v[180:183], v[210:213], v[54:57]
	v_mfma_f32_16x16x32_bf16 v[54:57], v[184:187], v[214:217], v[54:57]
	v_mfma_f32_16x16x32_bf16 v[86:89], v[180:183], v[218:221], v[86:89]
	v_mfma_f32_16x16x32_bf16 v[86:89], v[184:187], v[222:225], v[86:89]
	v_mfma_f32_16x16x32_bf16 v[110:113], v[180:183], v[226:229], v[110:113]
	v_mfma_f32_16x16x32_bf16 v[110:113], v[184:187], v[230:233], v[110:113]
	v_mfma_f32_16x16x32_bf16 v[106:109], v[188:191], v[226:229], v[106:109]
	v_mfma_f32_16x16x32_bf16 v[106:109], v[198:201], v[230:233], v[106:109]
	v_mfma_f32_16x16x32_bf16 v[82:85], v[188:191], v[218:221], v[82:85]
	v_mfma_f32_16x16x32_bf16 v[82:85], v[198:201], v[222:225], v[82:85]
	v_mfma_f32_16x16x32_bf16 v[50:53], v[188:191], v[210:213], v[50:53]
	v_mfma_f32_16x16x32_bf16 v[50:53], v[198:201], v[214:217], v[50:53]
	v_mfma_f32_16x16x32_bf16 v[26:29], v[188:191], v[202:205], v[26:29]
	v_mfma_f32_16x16x32_bf16 v[26:29], v[198:201], v[206:209], v[26:29]
	s_setprio 1
	s_barrier
	s_mov_b32 m0, s85
	s_add_u32 s58, s70, 0x4000
	ds_read_b128 v[202:205], v165 offset:16384
	ds_read_b128 v[206:209], v165 offset:17408
	ds_read_b128 v[210:213], v165 offset:18432
	ds_read_b128 v[214:217], v165 offset:19456
	ds_read_b128 v[218:221], v165 offset:20480
	ds_read_b128 v[222:225], v165 offset:21504
	ds_read_b128 v[226:229], v165 offset:22528
	ds_read_b128 v[230:233], v165 offset:23552
	global_load_lds_dwordx4 v136, s[70:71]
	s_mov_b32 m0, s86
	s_addc_u32 s59, s71, 0
	global_load_lds_dwordx4 v140, s[70:71]
	s_mov_b32 m0, s87
	s_nop 0
	global_load_lds_dwordx4 v136, s[58:59]
	s_mov_b32 m0, s88
	s_nop 0
	global_load_lds_dwordx4 v140, s[58:59]
	s_mov_b32 m0, s29
	s_nop 0
	global_load_lds_dwordx4 v134, s[72:73]
	s_mov_b32 m0, s30
	s_nop 0
	global_load_lds_dwordx4 v138, s[72:73]
	s_waitcnt vmcnt(8)
	s_waitcnt lgkmcnt(0)
	s_barrier
; #define PG8_STAGE(bufoff, gbase, voff) do { _Pragma("unroll") for (int _i = 0; _i < 2; ++_i) \
;         __builtin_amdgcn_global_load_lds((const unsigned*)((const char*)(gbase) + (voff)[_i]), (PG8_LAS unsigned*)(lds + (bufoff) + ldsw + _i * 8192), 16, 0, 0); } while (0)
; #define PG8_LDA(dst, b, h) do { _Pragma("unroll") for (int m = 0; m < 4; ++m) _Pragma("unroll") for (int k = 0; k < 2; ++k) dst[m][k] = *(const PG8_LAS bf16x8*)(lds + PG8_SA(b, h) + aoff + m * 2048 + k * 1024); } while (0)
; #define PG8_LDB(dst, b, h) do { _Pragma("unroll") for (int n = 0; n < 2; ++n) _Pragma("unroll") for (int k = 0; k < 2; ++k) dst[n][k] = *(const PG8_LAS bf16x8*)(lds + PG8_SB(b, h) + boff + n * 2048 + k * 1024); } while (0)
; #define PG8_MMA(ai, bj, At, Bt) do { __builtin_amdgcn_s_setprio(1); _Pragma("unroll") for (int m = 0; m < 4; ++m) _Pragma("unroll") for (int n = 0; n < 2; ++n) _Pragma("unroll") for (int k = 0; k < 2; ++k) \
;         acc[ai][bj][m][n] = __builtin_amdgcn_mfma_f32_16x16x32_bf16(Bt[n][k], At[m][k], acc[ai][bj][m][n], 0, 0, 0); __builtin_amdgcn_s_setprio(0); } while (0)
; #define PG8_WAIT_V(n) asm volatile("s_waitcnt vmcnt(" #n ")" ::: "memory")
; template <class Epi, class Sched, bool ALIGN_EPI = false, bool SP2 = false>
; __device__ __forceinline__ void gemm_phase(PG8_LAS unsigned char* lds, const Gemm g, const Sched& S, const Epi& E) {
;     ...
;             PG8_LDB(B0, 0, 0); PG8_LDB(B1, 0, 1); PG8_SCHED; PG8_LDA(At, 0, 0); PG8_STAGE(PG8_SA(1, 1), a1 + hstep, voffA);
;             PG8_WAIT_V(8); PG8_WAIT_L(0); PG8_BAR; PG8_MMA(0, 0, At, B0); PG8_MMA(0, 1, At, B1); PG8_BAR; PG8_SCHED;
;             PG8_LDA(At, 0, 1); PG8_STAGE(PG8_SB(0, 0), b2, voffB); PG8_STAGE(PG8_SB(0, 1), b2 + hstep, voffB); PG8_STAGE(PG8_SA(0, 0), a2, voffA);
;             PG8_WAIT_V(8); PG8_WAIT_L(0); PG8_BAR; PG8_MMA(1, 0, At, B0); PG8_MMA(1, 1, At, B1); PG8_BAR; PG8_SCHED;
;             PG8_LDB(B0, 1, 0); PG8_LDB(B1, 1, 1); PG8_SCHED; PG8_LDA(At, 1, 0); PG8_STAGE(PG8_SA(0, 1), a2 + hstep, voffA);
;             PG8_WAIT_V(8); PG8_WAIT_L(0); PG8_BAR; PG8_MMA(0, 0, At, B0); PG8_MMA(0, 1, At, B1); PG8_BAR; PG8_SCHED;
;             PG8_LDA(At, 1, 1); PG8_STAGE(PG8_SB(1, 0), b3, voffB); PG8_STAGE(PG8_SB(1, 1), b3 + hstep, voffB); PG8_STAGE(PG8_SA(1, 0), a3, voffA);
;             PG8_WAIT_V(8); PG8_WAIT_L(0); PG8_BAR; PG8_MMA(1, 0, At, B0); PG8_MMA(1, 1, At, B1); PG8_BAR; PG8_SCHED;
	s_setprio 0
	s_waitcnt lgkmcnt(0)
	v_mfma_f32_16x16x32_bf16 v[126:129], v[130:133], v[202:205], v[126:129]
	v_mfma_f32_16x16x32_bf16 v[126:129], v[156:159], v[206:209], v[126:129]
	v_mfma_f32_16x16x32_bf16 v[102:105], v[130:133], v[210:213], v[102:105]
	v_mfma_f32_16x16x32_bf16 v[102:105], v[156:159], v[214:217], v[102:105]
	v_mfma_f32_16x16x32_bf16 v[62:65], v[130:133], v[218:221], v[62:65]
	v_mfma_f32_16x16x32_bf16 v[62:65], v[156:159], v[222:225], v[62:65]
	v_mfma_f32_16x16x32_bf16 v[22:25], v[130:133], v[226:229], v[22:25]
	v_mfma_f32_16x16x32_bf16 v[22:25], v[156:159], v[230:233], v[22:25]
	v_mfma_f32_16x16x32_bf16 v[18:21], v[168:171], v[226:229], v[18:21]
	v_mfma_f32_16x16x32_bf16 v[18:21], v[172:175], v[230:233], v[18:21]
	v_mfma_f32_16x16x32_bf16 v[58:61], v[168:171], v[218:221], v[58:61]
	v_mfma_f32_16x16x32_bf16 v[58:61], v[172:175], v[222:225], v[58:61]
	v_mfma_f32_16x16x32_bf16 v[98:101], v[168:171], v[210:213], v[98:101]
	v_mfma_f32_16x16x32_bf16 v[98:101], v[172:175], v[214:217], v[98:101]
	v_mfma_f32_16x16x32_bf16 v[122:125], v[168:171], v[202:205], v[122:125]
	v_mfma_f32_16x16x32_bf16 v[122:125], v[172:175], v[206:209], v[122:125]
	v_mfma_f32_16x16x32_bf16 v[118:121], v[180:183], v[202:205], v[118:121]
	v_mfma_f32_16x16x32_bf16 v[118:121], v[184:187], v[206:209], v[118:121]
	v_mfma_f32_16x16x32_bf16 v[78:81], v[180:183], v[210:213], v[78:81]
	v_mfma_f32_16x16x32_bf16 v[78:81], v[184:187], v[214:217], v[78:81]
	v_mfma_f32_16x16x32_bf16 v[46:49], v[180:183], v[218:221], v[46:49]
	v_mfma_f32_16x16x32_bf16 v[46:49], v[184:187], v[222:225], v[46:49]
	v_mfma_f32_16x16x32_bf16 v[6:9], v[180:183], v[226:229], v[6:9]
	v_mfma_f32_16x16x32_bf16 v[6:9], v[184:187], v[230:233], v[6:9]
	v_mfma_f32_16x16x32_bf16 v[2:5], v[188:191], v[226:229], v[2:5]
	v_mfma_f32_16x16x32_bf16 v[2:5], v[198:201], v[230:233], v[2:5]
	v_mfma_f32_16x16x32_bf16 v[42:45], v[188:191], v[218:221], v[42:45]
	v_mfma_f32_16x16x32_bf16 v[42:45], v[198:201], v[222:225], v[42:45]
	v_mfma_f32_16x16x32_bf16 v[74:77], v[188:191], v[210:213], v[74:77]
	v_mfma_f32_16x16x32_bf16 v[74:77], v[198:201], v[214:217], v[74:77]
	v_mfma_f32_16x16x32_bf16 v[114:117], v[188:191], v[202:205], v[114:117]
	v_mfma_f32_16x16x32_bf16 v[114:117], v[198:201], v[206:209], v[114:117]
	s_setprio 1
	s_barrier
	ds_read_b128 v[130:133], v142
	ds_read_b128 v[156:159], v142 offset:1024
	ds_read_b128 v[168:171], v142 offset:2048
	ds_read_b128 v[172:175], v142 offset:3072
	ds_read_b128 v[180:183], v167
	ds_read_b128 v[184:187], v167 offset:1024
	ds_read_b128 v[188:191], v167 offset:2048
	ds_read_b128 v[198:201], v167 offset:3072
	s_add_u32 s58, s72, 0x4000
	s_addc_u32 s59, s73, 0
	s_mov_b32 m0, s31
	ds_read_b128 v[202:205], v165 offset:32768
	ds_read_b128 v[206:209], v165 offset:33792
	ds_read_b128 v[210:213], v165 offset:34816
	ds_read_b128 v[214:217], v165 offset:35840
	ds_read_b128 v[218:221], v165 offset:36864
	ds_read_b128 v[222:225], v165 offset:37888
	ds_read_b128 v[226:229], v165 offset:38912
	ds_read_b128 v[230:233], v165 offset:39936
	global_load_lds_dwordx4 v134, s[58:59]
	s_mov_b32 m0, s35
	s_nop 0
	global_load_lds_dwordx4 v138, s[58:59]
	s_waitcnt vmcnt(8)
	s_waitcnt lgkmcnt(0)
	s_barrier
	s_setprio 0
	s_waitcnt lgkmcnt(0)
	v_mfma_f32_16x16x32_bf16 v[14:17], v[130:133], v[202:205], v[14:17]
	v_mfma_f32_16x16x32_bf16 v[14:17], v[156:159], v[206:209], v[14:17]
	v_mfma_f32_16x16x32_bf16 v[38:41], v[130:133], v[210:213], v[38:41]
	v_mfma_f32_16x16x32_bf16 v[38:41], v[156:159], v[214:217], v[38:41]
	v_mfma_f32_16x16x32_bf16 v[70:73], v[130:133], v[218:221], v[70:73]
	v_mfma_f32_16x16x32_bf16 v[70:73], v[156:159], v[222:225], v[70:73]
	v_mfma_f32_16x16x32_bf16 v[94:97], v[130:133], v[226:229], v[94:97]
	v_mfma_f32_16x16x32_bf16 v[94:97], v[156:159], v[230:233], v[94:97]
	v_mfma_f32_16x16x32_bf16 v[90:93], v[168:171], v[226:229], v[90:93]
	v_mfma_f32_16x16x32_bf16 v[90:93], v[172:175], v[230:233], v[90:93]
	v_mfma_f32_16x16x32_bf16 v[66:69], v[168:171], v[218:221], v[66:69]
	v_mfma_f32_16x16x32_bf16 v[66:69], v[172:175], v[222:225], v[66:69]
	v_mfma_f32_16x16x32_bf16 v[34:37], v[168:171], v[210:213], v[34:37]
	v_mfma_f32_16x16x32_bf16 v[34:37], v[172:175], v[214:217], v[34:37]
	v_mfma_f32_16x16x32_bf16 v[10:13], v[168:171], v[202:205], v[10:13]
	v_mfma_f32_16x16x32_bf16 v[10:13], v[172:175], v[206:209], v[10:13]
	v_mfma_f32_16x16x32_bf16 v[30:33], v[180:183], v[202:205], v[30:33]
	v_mfma_f32_16x16x32_bf16 v[30:33], v[184:187], v[206:209], v[30:33]
	v_mfma_f32_16x16x32_bf16 v[54:57], v[180:183], v[210:213], v[54:57]
	v_mfma_f32_16x16x32_bf16 v[54:57], v[184:187], v[214:217], v[54:57]
	v_mfma_f32_16x16x32_bf16 v[86:89], v[180:183], v[218:221], v[86:89]
	v_mfma_f32_16x16x32_bf16 v[86:89], v[184:187], v[222:225], v[86:89]
	v_mfma_f32_16x16x32_bf16 v[110:113], v[180:183], v[226:229], v[110:113]
	v_mfma_f32_16x16x32_bf16 v[110:113], v[184:187], v[230:233], v[110:113]
	v_mfma_f32_16x16x32_bf16 v[106:109], v[188:191], v[226:229], v[106:109]
	v_mfma_f32_16x16x32_bf16 v[106:109], v[198:201], v[230:233], v[106:109]
	v_mfma_f32_16x16x32_bf16 v[82:85], v[188:191], v[218:221], v[82:85]
	v_mfma_f32_16x16x32_bf16 v[82:85], v[198:201], v[222:225], v[82:85]
	v_mfma_f32_16x16x32_bf16 v[50:53], v[188:191], v[210:213], v[50:53]
	v_mfma_f32_16x16x32_bf16 v[50:53], v[198:201], v[214:217], v[50:53]
	v_mfma_f32_16x16x32_bf16 v[26:29], v[188:191], v[202:205], v[26:29]
	v_mfma_f32_16x16x32_bf16 v[26:29], v[198:201], v[206:209], v[26:29]
	s_setprio 1
	s_barrier
; #define PG8_STAGE(bufoff, gbase, voff) do { _Pragma("unroll") for (int _i = 0; _i < 2; ++_i) \
;         __builtin_amdgcn_global_load_lds((const unsigned*)((const char*)(gbase) + (voff)[_i]), (PG8_LAS unsigned*)(lds + (bufoff) + ldsw + _i * 8192), 16, 0, 0); } while (0)
; #define PG8_LDA(dst, b, h) do { _Pragma("unroll") for (int m = 0; m < 4; ++m) _Pragma("unroll") for (int k = 0; k < 2; ++k) dst[m][k] = *(const PG8_LAS bf16x8*)(lds + PG8_SA(b, h) + aoff + m * 2048 + k * 1024); } while (0)
; #define PG8_LDB(dst, b, h) do { _Pragma("unroll") for (int n = 0; n < 2; ++n) _Pragma("unroll") for (int k = 0; k < 2; ++k) dst[n][k] = *(const PG8_LAS bf16x8*)(lds + PG8_SB(b, h) + boff + n * 2048 + k * 1024); } while (0)
; #define PG8_MMA(ai, bj, At, Bt) do { __builtin_amdgcn_s_setprio(1); _Pragma("unroll") for (int m = 0; m < 4; ++m) _Pragma("unroll") for (int n = 0; n < 2; ++n) _Pragma("unroll") for (int k = 0; k < 2; ++k) \
;         acc[ai][bj][m][n] = __builtin_amdgcn_mfma_f32_16x16x32_bf16(Bt[n][k], At[m][k], acc[ai][bj][m][n], 0, 0, 0); __builtin_amdgcn_s_setprio(0); } while (0)
; #define PG8_WAIT_V(n) asm volatile("s_waitcnt vmcnt(" #n ")" ::: "memory")
; template <class Epi, class Sched, bool ALIGN_EPI = false, bool SP2 = false>
; __device__ __forceinline__ void gemm_phase(PG8_LAS unsigned char* lds, const Gemm g, const Sched& S, const Epi& E) {
;     ...
;             PG8_LDB(B0, 0, 0); PG8_LDB(B1, 0, 1); PG8_SCHED; PG8_LDA(At, 0, 0); PG8_STAGE(PG8_SA(1, 1), a1 + hstep, voffA);
;             PG8_WAIT_V(8); PG8_WAIT_L(0); PG8_BAR; PG8_MMA(0, 0, At, B0); PG8_MMA(0, 1, At, B1); PG8_BAR; PG8_SCHED;
;             PG8_LDA(At, 0, 1); PG8_STAGE(PG8_SB(0, 0), b2, voffB); PG8_STAGE(PG8_SB(0, 1), b2 + hstep, voffB); PG8_STAGE(PG8_SA(0, 0), a2, voffA);
;             PG8_WAIT_V(8); PG8_WAIT_L(0); PG8_BAR; PG8_MMA(1, 0, At, B0); PG8_MMA(1, 1, At, B1); PG8_BAR; PG8_SCHED;
;             PG8_LDB(B0, 1, 0); PG8_LDB(B1, 1, 1); PG8_SCHED; PG8_LDA(At, 1, 0); PG8_STAGE(PG8_SA(0, 1), a2 + hstep, voffA);
;             PG8_WAIT_V(8); PG8_WAIT_L(0); PG8_BAR; PG8_MMA(0, 0, At, B0); PG8_MMA(0, 1, At, B1); PG8_BAR; PG8_SCHED;
;             PG8_LDA(At, 1, 1); PG8_STAGE(PG8_SB(1, 0), b3, voffB); PG8_STAGE(PG8_SB(1, 1), b3 + hstep, voffB); PG8_STAGE(PG8_SA(1, 0), a3, voffA);
;             PG8_WAIT_V(8); PG8_WAIT_L(0); PG8_BAR; PG8_MMA(1, 0, At, B0); PG8_MMA(1, 1, At, B1); PG8_BAR; PG8_SCHED;
	s_add_u32 s58, s70, 0x8000
	s_addc_u32 s59, s71, 0
	s_mov_b32 m0, s89
	ds_read_b128 v[202:205], v165 offset:49152
	ds_read_b128 v[206:209], v165 offset:50176
	ds_read_b128 v[210:213], v165 offset:51200
	ds_read_b128 v[214:217], v165 offset:52224
	ds_read_b128 v[218:221], v165 offset:53248
	ds_read_b128 v[222:225], v165 offset:54272
	ds_read_b128 v[226:229], v165 offset:55296
	ds_read_b128 v[230:233], v165 offset:56320
	global_load_lds_dwordx4 v136, s[58:59]
	v_lshl_add_u64 v[176:177], s[58:59], 0, v[140:141]
	s_add_u32 s58, s70, 0xc000
	s_mov_b32 m0, s90
	s_addc_u32 s59, s71, 0
	global_load_lds_dwordx4 v[176:177], off
	s_mov_b32 m0, s91
	s_nop 0
	global_load_lds_dwordx4 v136, s[58:59]
	s_mov_b32 m0, s92
	s_nop 0
	global_load_lds_dwordx4 v140, s[58:59]
	s_mov_b32 m0, s75
	s_nop 0
	global_load_lds_dwordx4 v134, s[48:49]
	s_mov_b32 m0, s76
	s_nop 0
	global_load_lds_dwordx4 v138, s[48:49]
	s_waitcnt vmcnt(8)
	s_waitcnt lgkmcnt(0)
	s_barrier
	s_setprio 0
	s_waitcnt lgkmcnt(0)
	v_mfma_f32_16x16x32_bf16 v[126:129], v[130:133], v[202:205], v[126:129]
	v_mfma_f32_16x16x32_bf16 v[126:129], v[156:159], v[206:209], v[126:129]
	v_mfma_f32_16x16x32_bf16 v[102:105], v[130:133], v[210:213], v[102:105]
	v_mfma_f32_16x16x32_bf16 v[102:105], v[156:159], v[214:217], v[102:105]
	v_mfma_f32_16x16x32_bf16 v[62:65], v[130:133], v[218:221], v[62:65]
	v_mfma_f32_16x16x32_bf16 v[62:65], v[156:159], v[222:225], v[62:65]
	v_mfma_f32_16x16x32_bf16 v[22:25], v[130:133], v[226:229], v[22:25]
	v_mfma_f32_16x16x32_bf16 v[22:25], v[156:159], v[230:233], v[22:25]
	v_mfma_f32_16x16x32_bf16 v[18:21], v[168:171], v[226:229], v[18:21]
	v_mfma_f32_16x16x32_bf16 v[18:21], v[172:175], v[230:233], v[18:21]
	v_mfma_f32_16x16x32_bf16 v[58:61], v[168:171], v[218:221], v[58:61]
	v_mfma_f32_16x16x32_bf16 v[58:61], v[172:175], v[222:225], v[58:61]
	v_mfma_f32_16x16x32_bf16 v[98:101], v[168:171], v[210:213], v[98:101]
	v_mfma_f32_16x16x32_bf16 v[98:101], v[172:175], v[214:217], v[98:101]
	v_mfma_f32_16x16x32_bf16 v[122:125], v[168:171], v[202:205], v[122:125]
	v_mfma_f32_16x16x32_bf16 v[122:125], v[172:175], v[206:209], v[122:125]
	v_mfma_f32_16x16x32_bf16 v[118:121], v[180:183], v[202:205], v[118:121]
	v_mfma_f32_16x16x32_bf16 v[118:121], v[184:187], v[206:209], v[118:121]
	v_mfma_f32_16x16x32_bf16 v[78:81], v[180:183], v[210:213], v[78:81]
	v_mfma_f32_16x16x32_bf16 v[78:81], v[184:187], v[214:217], v[78:81]
	v_mfma_f32_16x16x32_bf16 v[46:49], v[180:183], v[218:221], v[46:49]
	v_mfma_f32_16x16x32_bf16 v[46:49], v[184:187], v[222:225], v[46:49]
	v_mfma_f32_16x16x32_bf16 v[6:9], v[180:183], v[226:229], v[6:9]
	v_mfma_f32_16x16x32_bf16 v[6:9], v[184:187], v[230:233], v[6:9]
	v_mfma_f32_16x16x32_bf16 v[2:5], v[188:191], v[226:229], v[2:5]
	v_mfma_f32_16x16x32_bf16 v[2:5], v[198:201], v[230:233], v[2:5]
	v_mfma_f32_16x16x32_bf16 v[42:45], v[188:191], v[218:221], v[42:45]
	v_mfma_f32_16x16x32_bf16 v[42:45], v[198:201], v[222:225], v[42:45]
	v_mfma_f32_16x16x32_bf16 v[74:77], v[188:191], v[210:213], v[74:77]
	v_mfma_f32_16x16x32_bf16 v[74:77], v[198:201], v[214:217], v[74:77]
	v_mfma_f32_16x16x32_bf16 v[114:117], v[188:191], v[202:205], v[114:117]
	v_mfma_f32_16x16x32_bf16 v[114:117], v[198:201], v[206:209], v[114:117]
	s_setprio 1
	s_barrier
	s_add_i32 s56, s56, 2
	s_add_u32 s50, s50, 0x10000
	s_addc_u32 s51, s51, 0
	s_add_u32 s26, s26, 0x10000
	s_addc_u32 s33, s33, 0
	s_cmp_lt_u32 s56, 62
	s_cbranch_scc1 .LBB0_684
	s_setprio 0
	s_andn2_b64 vcc, exec, s[12:13]
	s_cbranch_vccnz .LBB0_687
	s_barrier

; #define PG8_STAGE(bufoff, gbase, voff) do { _Pragma("unroll") for (int _i = 0; _i < 2; ++_i) \
;         __builtin_amdgcn_global_load_lds((const unsigned*)((const char*)(gbase) + (voff)[_i]), (PG8_LAS unsigned*)(lds + (bufoff) + ldsw + _i * 8192), 16, 0, 0); } while (0)
; #define PG8_LDA(dst, b, h) do { _Pragma("unroll") for (int m = 0; m < 4; ++m) _Pragma("unroll") for (int k = 0; k < 2; ++k) dst[m][k] = *(const PG8_LAS bf16x8*)(lds + PG8_SA(b, h) + aoff + m * 2048 + k * 1024); } while (0)
; #define PG8_LDB(dst, b, h) do { _Pragma("unroll") for (int n = 0; n < 2; ++n) _Pragma("unroll") for (int k = 0; k < 2; ++k) dst[n][k] = *(const PG8_LAS bf16x8*)(lds + PG8_SB(b, h) + boff + n * 2048 + k * 1024); } while (0)
; template <class Epi, class Sched, bool ALIGN_EPI = false, bool SP2 = false>
; __device__ __forceinline__ void gemm_phase(PG8_LAS unsigned char* lds, const Gemm g, const Sched& S, const Epi& E) {
;     ...
;         for (; t < tend; t += 2) {
;             const bool last = (t == nt - 2);
;             const char* a1 = cA + (size_t)(t + 1) * kstep;
;             const char* a2 = last ? nA : cA + (size_t)(t + 2) * kstep; const char* b2 = last ? nB : cB + (size_t)(t + 2) * kstep;
;             const char* a3 = a2 + kstep; const char* b3 = b2 + kstep;
;             if (last && has_next) S.a_ready(nxt);
;             if constexpr (SP2) {
;             PG8_LDB(B0, 0, 0); PG8_LDB(B1, 0, 1); PG8_SCHED; PG8_LDA(At, 0, 0); PG8_STAGE(PG8_SA(1, 1), a1 + hstep, voffA);
;             PG8_WAIT_V(8); PG8_WAIT_L(0); PG8_BAR; PG8_MMA(0, 0, At, B0); PG8_MMA(0, 1, At, B1); PG8_BAR; PG8_SCHED;
;             PG8_LDA(At, 0, 1); PG8_STAGE(PG8_SB(0, 0), b2, voffB); PG8_STAGE(PG8_SB(0, 1), b2 + hstep, voffB); PG8_STAGE(PG8_SA(0, 0), a2, voffA);
;             PG8_WAIT_V(8); PG8_WAIT_L(0); PG8_BAR; PG8_MMA(1, 0, At, B0); PG8_MMA(1, 1, At, B1); PG8_BAR; PG8_SCHED;
;             PG8_LDB(B0, 1, 0); PG8_LDB(B1, 1, 1); PG8_SCHED; PG8_LDA(At, 1, 0); PG8_STAGE(PG8_SA(0, 1), a2 + hstep, voffA);
;             PG8_WAIT_V(8); PG8_WAIT_L(0); PG8_BAR; PG8_MMA(0, 0, At, B0); PG8_MMA(0, 1, At, B1); PG8_BAR; PG8_SCHED;
;             PG8_LDA(At, 1, 1); PG8_STAGE(PG8_SB(1, 0), b3, voffB); PG8_STAGE(PG8_SB(1, 1), b3 + hstep, voffB); PG8_STAGE(PG8_SA(1, 0), a3, voffA);
;             PG8_WAIT_V(8); PG8_WAIT_L(0); PG8_BAR; PG8_MMA(1, 0, At, B0); PG8_MMA(1, 1, At, B1); PG8_BAR; PG8_SCHED;
.LBB0_757:
	ds_read_b128 v[154:157], v149
	ds_read_b128 v[158:161], v149 offset:1024
	ds_read_b128 v[162:165], v149 offset:2048
	ds_read_b128 v[166:169], v149 offset:3072
	ds_read_b128 v[170:173], v150
	ds_read_b128 v[174:177], v150 offset:1024
	ds_read_b128 v[180:183], v150 offset:2048
	ds_read_b128 v[184:187], v150 offset:3072
	s_add_u32 s46, s44, 0x4000
	s_addc_u32 s47, s45, 0
	s_cmp_eq_u32 s70, 60
	s_cselect_b32 s50, s39, s46
	s_cselect_b32 s51, s17, s47
	s_cselect_b32 s48, s41, s68
	s_cselect_b32 s49, s15, s69
	s_add_u32 s46, s50, 0x8000
	s_addc_u32 s47, s51, 0
	s_sub_u32 s46, s44, 0x4000
	s_subb_u32 s47, s45, 0
	s_mov_b32 m0, s57
	s_nop 0
	global_load_lds_dwordx4 v130, s[46:47]
	s_mov_b32 m0, s58
	s_nop 0
	global_load_lds_dwordx4 v134, s[46:47]
	s_add_i32 m0, s26, 0xc000
	ds_read_b128 v[188:191], v151
	ds_read_b128 v[198:201], v151 offset:1024
	ds_read_b128 v[202:205], v151 offset:2048
	ds_read_b128 v[206:209], v151 offset:3072
	ds_read_b128 v[210:213], v151 offset:4096
	ds_read_b128 v[214:217], v151 offset:5120
	ds_read_b128 v[218:221], v151 offset:6144
	ds_read_b128 v[222:225], v151 offset:7168
	global_load_lds_dwordx4 v138, s[44:45]
	s_add_i32 m0, s26, 0xe000
	s_nop 0
	global_load_lds_dwordx4 v140, s[44:45]
	s_waitcnt vmcnt(8)
	s_waitcnt lgkmcnt(0)
	s_barrier
	s_setprio 0
	s_waitcnt lgkmcnt(0)
	v_mfma_f32_16x16x32_bf16 v[126:129], v[154:157], v[188:191], v[126:129]
	v_mfma_f32_16x16x32_bf16 v[126:129], v[158:161], v[198:201], v[126:129]
	v_mfma_f32_16x16x32_bf16 v[110:113], v[154:157], v[202:205], v[110:113]
	v_mfma_f32_16x16x32_bf16 v[110:113], v[158:161], v[206:209], v[110:113]
	v_mfma_f32_16x16x32_bf16 v[94:97], v[154:157], v[210:213], v[94:97]
	v_mfma_f32_16x16x32_bf16 v[94:97], v[158:161], v[214:217], v[94:97]
	v_mfma_f32_16x16x32_bf16 v[78:81], v[154:157], v[218:221], v[78:81]
	v_mfma_f32_16x16x32_bf16 v[78:81], v[158:161], v[222:225], v[78:81]
	v_mfma_f32_16x16x32_bf16 v[74:77], v[162:165], v[218:221], v[74:77]
	v_mfma_f32_16x16x32_bf16 v[74:77], v[166:169], v[222:225], v[74:77]
	v_mfma_f32_16x16x32_bf16 v[90:93], v[162:165], v[210:213], v[90:93]
	v_mfma_f32_16x16x32_bf16 v[90:93], v[166:169], v[214:217], v[90:93]
	v_mfma_f32_16x16x32_bf16 v[106:109], v[162:165], v[202:205], v[106:109]
	v_mfma_f32_16x16x32_bf16 v[106:109], v[166:169], v[206:209], v[106:109]
	v_mfma_f32_16x16x32_bf16 v[122:125], v[162:165], v[188:191], v[122:125]
	v_mfma_f32_16x16x32_bf16 v[122:125], v[166:169], v[198:201], v[122:125]
	v_mfma_f32_16x16x32_bf16 v[118:121], v[170:173], v[188:191], v[118:121]
	v_mfma_f32_16x16x32_bf16 v[118:121], v[174:177], v[198:201], v[118:121]
	v_mfma_f32_16x16x32_bf16 v[102:105], v[170:173], v[202:205], v[102:105]
	v_mfma_f32_16x16x32_bf16 v[102:105], v[174:177], v[206:209], v[102:105]
	v_mfma_f32_16x16x32_bf16 v[86:89], v[170:173], v[210:213], v[86:89]
	v_mfma_f32_16x16x32_bf16 v[86:89], v[174:177], v[214:217], v[86:89]
	v_mfma_f32_16x16x32_bf16 v[70:73], v[170:173], v[218:221], v[70:73]
	v_mfma_f32_16x16x32_bf16 v[70:73], v[174:177], v[222:225], v[70:73]
	v_mfma_f32_16x16x32_bf16 v[66:69], v[180:183], v[218:221], v[66:69]
	v_mfma_f32_16x16x32_bf16 v[66:69], v[184:187], v[222:225], v[66:69]
	v_mfma_f32_16x16x32_bf16 v[82:85], v[180:183], v[210:213], v[82:85]
	v_mfma_f32_16x16x32_bf16 v[82:85], v[184:187], v[214:217], v[82:85]
	v_mfma_f32_16x16x32_bf16 v[98:101], v[180:183], v[202:205], v[98:101]
	v_mfma_f32_16x16x32_bf16 v[98:101], v[184:187], v[206:209], v[98:101]
	v_mfma_f32_16x16x32_bf16 v[114:117], v[180:183], v[188:191], v[114:117]
	v_mfma_f32_16x16x32_bf16 v[114:117], v[184:187], v[198:201], v[114:117]
	s_setprio 1
	s_barrier
	s_add_i32 s71, s59, s3
	s_mov_b32 m0, s71
	ds_read_b128 v[188:191], v151 offset:16384
	ds_read_b128 v[198:201], v151 offset:17408
	ds_read_b128 v[202:205], v151 offset:18432
	ds_read_b128 v[206:209], v151 offset:19456
	ds_read_b128 v[210:213], v151 offset:20480
	ds_read_b128 v[214:217], v151 offset:21504
	ds_read_b128 v[218:221], v151 offset:22528
	ds_read_b128 v[222:225], v151 offset:23552
	global_load_lds_dwordx4 v132, s[48:49]
	s_add_i32 m0, s71, 0x2000
	s_add_u32 s72, s48, 0x4000
	s_addc_u32 s73, s49, 0
	s_add_i32 s71, s61, s3
	global_load_lds_dwordx4 v136, s[48:49]
	s_mov_b32 m0, s71
	s_nop 0
	global_load_lds_dwordx4 v132, s[72:73]
	s_add_i32 m0, s71, 0x2000
	s_nop 0
	global_load_lds_dwordx4 v136, s[72:73]
	s_waitcnt vmcnt(6)
	s_waitcnt lgkmcnt(0)
	s_barrier
	s_setprio 0
	s_waitcnt lgkmcnt(0)
	v_mfma_f32_16x16x32_bf16 v[62:65], v[154:157], v[188:191], v[62:65]
	v_mfma_f32_16x16x32_bf16 v[62:65], v[158:161], v[198:201], v[62:65]
	v_mfma_f32_16x16x32_bf16 v[46:49], v[154:157], v[202:205], v[46:49]
	v_mfma_f32_16x16x32_bf16 v[46:49], v[158:161], v[206:209], v[46:49]
	v_mfma_f32_16x16x32_bf16 v[30:33], v[154:157], v[210:213], v[30:33]
	v_mfma_f32_16x16x32_bf16 v[30:33], v[158:161], v[214:217], v[30:33]
	v_mfma_f32_16x16x32_bf16 v[14:17], v[154:157], v[218:221], v[14:17]
	v_mfma_f32_16x16x32_bf16 v[14:17], v[158:161], v[222:225], v[14:17]
	v_mfma_f32_16x16x32_bf16 v[10:13], v[162:165], v[218:221], v[10:13]
	v_mfma_f32_16x16x32_bf16 v[10:13], v[166:169], v[222:225], v[10:13]
	v_mfma_f32_16x16x32_bf16 v[26:29], v[162:165], v[210:213], v[26:29]
	v_mfma_f32_16x16x32_bf16 v[26:29], v[166:169], v[214:217], v[26:29]
	v_mfma_f32_16x16x32_bf16 v[42:45], v[162:165], v[202:205], v[42:45]
	v_mfma_f32_16x16x32_bf16 v[42:45], v[166:169], v[206:209], v[42:45]
	v_mfma_f32_16x16x32_bf16 v[58:61], v[162:165], v[188:191], v[58:61]
	v_mfma_f32_16x16x32_bf16 v[58:61], v[166:169], v[198:201], v[58:61]
	v_mfma_f32_16x16x32_bf16 v[54:57], v[170:173], v[188:191], v[54:57]
	v_mfma_f32_16x16x32_bf16 v[54:57], v[174:177], v[198:201], v[54:57]
	v_mfma_f32_16x16x32_bf16 v[38:41], v[170:173], v[202:205], v[38:41]
	v_mfma_f32_16x16x32_bf16 v[38:41], v[174:177], v[206:209], v[38:41]
	v_mfma_f32_16x16x32_bf16 v[22:25], v[170:173], v[210:213], v[22:25]
	v_mfma_f32_16x16x32_bf16 v[22:25], v[174:177], v[214:217], v[22:25]
	v_mfma_f32_16x16x32_bf16 v[6:9], v[170:173], v[218:221], v[6:9]
	v_mfma_f32_16x16x32_bf16 v[6:9], v[174:177], v[222:225], v[6:9]
	v_mfma_f32_16x16x32_bf16 v[2:5], v[180:183], v[218:221], v[2:5]
	v_mfma_f32_16x16x32_bf16 v[2:5], v[184:187], v[222:225], v[2:5]
	v_mfma_f32_16x16x32_bf16 v[18:21], v[180:183], v[210:213], v[18:21]
	v_mfma_f32_16x16x32_bf16 v[18:21], v[184:187], v[214:217], v[18:21]
	v_mfma_f32_16x16x32_bf16 v[34:37], v[180:183], v[202:205], v[34:37]
	v_mfma_f32_16x16x32_bf16 v[34:37], v[184:187], v[206:209], v[34:37]
	v_mfma_f32_16x16x32_bf16 v[50:53], v[180:183], v[188:191], v[50:53]
	v_mfma_f32_16x16x32_bf16 v[50:53], v[184:187], v[198:201], v[50:53]
	s_setprio 1
	s_barrier
; #define PG8_STAGE(bufoff, gbase, voff) do { _Pragma("unroll") for (int _i = 0; _i < 2; ++_i) \
;         __builtin_amdgcn_global_load_lds((const unsigned*)((const char*)(gbase) + (voff)[_i]), (PG8_LAS unsigned*)(lds + (bufoff) + ldsw + _i * 8192), 16, 0, 0); } while (0)
; #define PG8_LDA(dst, b, h) do { _Pragma("unroll") for (int m = 0; m < 4; ++m) _Pragma("unroll") for (int k = 0; k < 2; ++k) dst[m][k] = *(const PG8_LAS bf16x8*)(lds + PG8_SA(b, h) + aoff + m * 2048 + k * 1024); } while (0)
; #define PG8_LDB(dst, b, h) do { _Pragma("unroll") for (int n = 0; n < 2; ++n) _Pragma("unroll") for (int k = 0; k < 2; ++k) dst[n][k] = *(const PG8_LAS bf16x8*)(lds + PG8_SB(b, h) + boff + n * 2048 + k * 1024); } while (0)
; template <class Epi, class Sched, bool ALIGN_EPI = false, bool SP2 = false>
; __device__ __forceinline__ void gemm_phase(PG8_LAS unsigned char* lds, const Gemm g, const Sched& S, const Epi& E) {
;     ...
;         for (; t < tend; t += 2) {
;             const bool last = (t == nt - 2);
;             const char* a1 = cA + (size_t)(t + 1) * kstep;
;             const char* a2 = last ? nA : cA + (size_t)(t + 2) * kstep; const char* b2 = last ? nB : cB + (size_t)(t + 2) * kstep;
;             const char* a3 = a2 + kstep; const char* b3 = b2 + kstep;
;             if (last && has_next) S.a_ready(nxt);
;             if constexpr (SP2) {
;             PG8_LDB(B0, 0, 0); PG8_LDB(B1, 0, 1); PG8_SCHED; PG8_LDA(At, 0, 0); PG8_STAGE(PG8_SA(1, 1), a1 + hstep, voffA);
;             PG8_WAIT_V(8); PG8_WAIT_L(0); PG8_BAR; PG8_MMA(0, 0, At, B0); PG8_MMA(0, 1, At, B1); PG8_BAR; PG8_SCHED;
;             PG8_LDA(At, 0, 1); PG8_STAGE(PG8_SB(0, 0), b2, voffB); PG8_STAGE(PG8_SB(0, 1), b2 + hstep, voffB); PG8_STAGE(PG8_SA(0, 0), a2, voffA);
;             PG8_WAIT_V(8); PG8_WAIT_L(0); PG8_BAR; PG8_MMA(1, 0, At, B0); PG8_MMA(1, 1, At, B1); PG8_BAR; PG8_SCHED;
;             PG8_LDB(B0, 1, 0); PG8_LDB(B1, 1, 1); PG8_SCHED; PG8_LDA(At, 1, 0); PG8_STAGE(PG8_SA(0, 1), a2 + hstep, voffA);
;             PG8_WAIT_V(8); PG8_WAIT_L(0); PG8_BAR; PG8_MMA(0, 0, At, B0); PG8_MMA(0, 1, At, B1); PG8_BAR; PG8_SCHED;
;             PG8_LDA(At, 1, 1); PG8_STAGE(PG8_SB(1, 0), b3, voffB); PG8_STAGE(PG8_SB(1, 1), b3 + hstep, voffB); PG8_STAGE(PG8_SA(1, 0), a3, voffA);
;             PG8_WAIT_V(8); PG8_WAIT_L(0); PG8_BAR; PG8_MMA(1, 0, At, B0); PG8_MMA(1, 1, At, B1); PG8_BAR; PG8_SCHED;
	s_add_i32 s71, 0, 0x18000
	v_add_u32_e32 v146, s71, v1
	s_add_i32 s72, 0, 0x1c000
	ds_read_b128 v[154:157], v146
	ds_read_b128 v[158:161], v146 offset:1024
	ds_read_b128 v[162:165], v146 offset:2048
	ds_read_b128 v[166:169], v146 offset:3072
	v_add_u32_e32 v146, s72, v1
	ds_read_b128 v[170:173], v146
	ds_read_b128 v[174:177], v146 offset:1024
	ds_read_b128 v[180:183], v146 offset:2048
	ds_read_b128 v[184:187], v146 offset:3072
	s_mov_b32 m0, s26
	s_nop 0
	global_load_lds_dwordx4 v130, s[50:51]
	s_mov_b32 m0, s27
	s_nop 0
	global_load_lds_dwordx4 v134, s[50:51]
	s_add_u32 s50, s50, 0x4000
	s_addc_u32 s51, s51, 0
	s_mov_b32 m0, s28
	ds_read_b128 v[188:191], v151 offset:32768
	ds_read_b128 v[198:201], v151 offset:33792
	ds_read_b128 v[202:205], v151 offset:34816
	ds_read_b128 v[206:209], v151 offset:35840
	ds_read_b128 v[210:213], v151 offset:36864
	ds_read_b128 v[214:217], v151 offset:37888
	ds_read_b128 v[218:221], v151 offset:38912
	ds_read_b128 v[222:225], v151 offset:39936
	global_load_lds_dwordx4 v130, s[50:51]
	s_mov_b32 m0, s29
	s_nop 0
	global_load_lds_dwordx4 v134, s[50:51]
	s_waitcnt vmcnt(8)
	s_waitcnt lgkmcnt(0)
	s_barrier
	s_setprio 0
	s_waitcnt lgkmcnt(0)
	v_mfma_f32_16x16x32_bf16 v[126:129], v[154:157], v[188:191], v[126:129]
	v_mfma_f32_16x16x32_bf16 v[126:129], v[158:161], v[198:201], v[126:129]
	v_mfma_f32_16x16x32_bf16 v[110:113], v[154:157], v[202:205], v[110:113]
	v_mfma_f32_16x16x32_bf16 v[110:113], v[158:161], v[206:209], v[110:113]
	v_mfma_f32_16x16x32_bf16 v[94:97], v[154:157], v[210:213], v[94:97]
	v_mfma_f32_16x16x32_bf16 v[94:97], v[158:161], v[214:217], v[94:97]
	v_mfma_f32_16x16x32_bf16 v[78:81], v[154:157], v[218:221], v[78:81]
	v_mfma_f32_16x16x32_bf16 v[78:81], v[158:161], v[222:225], v[78:81]
	v_mfma_f32_16x16x32_bf16 v[74:77], v[162:165], v[218:221], v[74:77]
	v_mfma_f32_16x16x32_bf16 v[74:77], v[166:169], v[222:225], v[74:77]
	v_mfma_f32_16x16x32_bf16 v[90:93], v[162:165], v[210:213], v[90:93]
	v_mfma_f32_16x16x32_bf16 v[90:93], v[166:169], v[214:217], v[90:93]
	v_mfma_f32_16x16x32_bf16 v[106:109], v[162:165], v[202:205], v[106:109]
	v_mfma_f32_16x16x32_bf16 v[106:109], v[166:169], v[206:209], v[106:109]
	v_mfma_f32_16x16x32_bf16 v[122:125], v[162:165], v[188:191], v[122:125]
	v_mfma_f32_16x16x32_bf16 v[122:125], v[166:169], v[198:201], v[122:125]
	v_mfma_f32_16x16x32_bf16 v[118:121], v[170:173], v[188:191], v[118:121]
	v_mfma_f32_16x16x32_bf16 v[118:121], v[174:177], v[198:201], v[118:121]
	v_mfma_f32_16x16x32_bf16 v[102:105], v[170:173], v[202:205], v[102:105]
	v_mfma_f32_16x16x32_bf16 v[102:105], v[174:177], v[206:209], v[102:105]
	v_mfma_f32_16x16x32_bf16 v[86:89], v[170:173], v[210:213], v[86:89]
	v_mfma_f32_16x16x32_bf16 v[86:89], v[174:177], v[214:217], v[86:89]
	v_mfma_f32_16x16x32_bf16 v[70:73], v[170:173], v[218:221], v[70:73]
	v_mfma_f32_16x16x32_bf16 v[70:73], v[174:177], v[222:225], v[70:73]
	v_mfma_f32_16x16x32_bf16 v[66:69], v[180:183], v[218:221], v[66:69]
	v_mfma_f32_16x16x32_bf16 v[66:69], v[184:187], v[222:225], v[66:69]
	v_mfma_f32_16x16x32_bf16 v[82:85], v[180:183], v[210:213], v[82:85]
	v_mfma_f32_16x16x32_bf16 v[82:85], v[184:187], v[214:217], v[82:85]
	v_mfma_f32_16x16x32_bf16 v[98:101], v[180:183], v[202:205], v[98:101]
	v_mfma_f32_16x16x32_bf16 v[98:101], v[184:187], v[206:209], v[98:101]
	v_mfma_f32_16x16x32_bf16 v[114:117], v[180:183], v[188:191], v[114:117]
	v_mfma_f32_16x16x32_bf16 v[114:117], v[184:187], v[198:201], v[114:117]
	s_setprio 1
	s_barrier
	s_add_u32 s50, s48, 0x8000
	s_addc_u32 s51, s49, 0
	s_add_i32 s71, s71, s3
	s_mov_b32 m0, s71
	ds_read_b128 v[188:191], v151 offset:49152
	ds_read_b128 v[198:201], v151 offset:50176
	ds_read_b128 v[202:205], v151 offset:51200
	ds_read_b128 v[206:209], v151 offset:52224
	ds_read_b128 v[210:213], v151 offset:53248
	ds_read_b128 v[214:217], v151 offset:54272
	ds_read_b128 v[218:221], v151 offset:55296
	ds_read_b128 v[222:225], v151 offset:56320
	global_load_lds_dwordx4 v132, s[50:51]
	s_add_i32 m0, s71, 0x2000
	s_add_u32 s48, s48, 0xc000
	v_lshl_add_u64 v[146:147], s[50:51], 0, v[136:137]
	s_addc_u32 s49, s49, 0
	s_add_i32 s50, s72, s3
	global_load_lds_dwordx4 v[146:147], off
	s_mov_b32 m0, s50
	s_nop 0
	global_load_lds_dwordx4 v132, s[48:49]
	s_add_i32 m0, s50, 0x2000
	s_nop 0
	global_load_lds_dwordx4 v136, s[48:49]
	s_waitcnt vmcnt(6)
	s_waitcnt lgkmcnt(0)
	s_barrier
	s_setprio 0
	s_waitcnt lgkmcnt(0)
	v_mfma_f32_16x16x32_bf16 v[62:65], v[154:157], v[188:191], v[62:65]
	v_mfma_f32_16x16x32_bf16 v[62:65], v[158:161], v[198:201], v[62:65]
	v_mfma_f32_16x16x32_bf16 v[46:49], v[154:157], v[202:205], v[46:49]
	v_mfma_f32_16x16x32_bf16 v[46:49], v[158:161], v[206:209], v[46:49]
	v_mfma_f32_16x16x32_bf16 v[30:33], v[154:157], v[210:213], v[30:33]
	v_mfma_f32_16x16x32_bf16 v[30:33], v[158:161], v[214:217], v[30:33]
	v_mfma_f32_16x16x32_bf16 v[14:17], v[154:157], v[218:221], v[14:17]
	v_mfma_f32_16x16x32_bf16 v[14:17], v[158:161], v[222:225], v[14:17]
	v_mfma_f32_16x16x32_bf16 v[10:13], v[162:165], v[218:221], v[10:13]
	v_mfma_f32_16x16x32_bf16 v[10:13], v[166:169], v[222:225], v[10:13]
	v_mfma_f32_16x16x32_bf16 v[26:29], v[162:165], v[210:213], v[26:29]
	v_mfma_f32_16x16x32_bf16 v[26:29], v[166:169], v[214:217], v[26:29]
	v_mfma_f32_16x16x32_bf16 v[42:45], v[162:165], v[202:205], v[42:45]
	v_mfma_f32_16x16x32_bf16 v[42:45], v[166:169], v[206:209], v[42:45]
	v_mfma_f32_16x16x32_bf16 v[58:61], v[162:165], v[188:191], v[58:61]
	v_mfma_f32_16x16x32_bf16 v[58:61], v[166:169], v[198:201], v[58:61]
	v_mfma_f32_16x16x32_bf16 v[54:57], v[170:173], v[188:191], v[54:57]
	v_mfma_f32_16x16x32_bf16 v[54:57], v[174:177], v[198:201], v[54:57]
	v_mfma_f32_16x16x32_bf16 v[38:41], v[170:173], v[202:205], v[38:41]
	v_mfma_f32_16x16x32_bf16 v[38:41], v[174:177], v[206:209], v[38:41]
	v_mfma_f32_16x16x32_bf16 v[22:25], v[170:173], v[210:213], v[22:25]
	v_mfma_f32_16x16x32_bf16 v[22:25], v[174:177], v[214:217], v[22:25]
	v_mfma_f32_16x16x32_bf16 v[6:9], v[170:173], v[218:221], v[6:9]
	v_mfma_f32_16x16x32_bf16 v[6:9], v[174:177], v[222:225], v[6:9]
	v_mfma_f32_16x16x32_bf16 v[2:5], v[180:183], v[218:221], v[2:5]
	v_mfma_f32_16x16x32_bf16 v[2:5], v[184:187], v[222:225], v[2:5]
	v_mfma_f32_16x16x32_bf16 v[18:21], v[180:183], v[210:213], v[18:21]
	v_mfma_f32_16x16x32_bf16 v[18:21], v[184:187], v[214:217], v[18:21]
	v_mfma_f32_16x16x32_bf16 v[34:37], v[180:183], v[202:205], v[34:37]
	v_mfma_f32_16x16x32_bf16 v[34:37], v[184:187], v[206:209], v[34:37]
	v_mfma_f32_16x16x32_bf16 v[50:53], v[180:183], v[188:191], v[50:53]
	v_mfma_f32_16x16x32_bf16 v[50:53], v[184:187], v[198:201], v[50:53]
	s_setprio 1
	s_barrier
	s_add_i32 s70, s70, 2
	s_add_u32 s44, s44, 0x10000
	s_addc_u32 s45, s45, 0
	s_add_u32 s68, s68, 0x10000
	s_addc_u32 s69, s69, 0
	s_cmp_gt_u32 s70, 61
	s_cbranch_scc0 .LBB0_757
	s_setprio 0
	s_and_b64 vcc, exec, s[12:13]
	s_cbranch_vccz .LBB0_760
	s_barrier

; #define PG8_STAGE(bufoff, gbase, voff) do { _Pragma("unroll") for (int _i = 0; _i < 2; ++_i) \
;         __builtin_amdgcn_global_load_lds((const unsigned*)((const char*)(gbase) + (voff)[_i]), (PG8_LAS unsigned*)(lds + (bufoff) + ldsw + _i * 8192), 16, 0, 0); } while (0)
; #define PG8_LDA(dst, b, h) do { _Pragma("unroll") for (int m = 0; m < 4; ++m) _Pragma("unroll") for (int k = 0; k < 2; ++k) dst[m][k] = *(const PG8_LAS bf16x8*)(lds + PG8_SA(b, h) + aoff + m * 2048 + k * 1024); } while (0)
; #define PG8_LDB(dst, b, h) do { _Pragma("unroll") for (int n = 0; n < 2; ++n) _Pragma("unroll") for (int k = 0; k < 2; ++k) dst[n][k] = *(const PG8_LAS bf16x8*)(lds + PG8_SB(b, h) + boff + n * 2048 + k * 1024); } while (0)
; template <class Epi, class Sched, bool ALIGN_EPI = false, bool SP2 = false>
; __device__ __forceinline__ void gemm_phase(PG8_LAS unsigned char* lds, const Gemm g, const Sched& S, const Epi& E) {
;     ...
;         for (; t < tend; t += 2) {
;             const bool last = (t == nt - 2);
;             const char* a1 = cA + (size_t)(t + 1) * kstep;
;             const char* a2 = last ? nA : cA + (size_t)(t + 2) * kstep; const char* b2 = last ? nB : cB + (size_t)(t + 2) * kstep;
;             const char* a3 = a2 + kstep; const char* b3 = b2 + kstep;
;             if (last && has_next) S.a_ready(nxt);
;             if constexpr (SP2) {
;             PG8_LDB(B0, 0, 0); PG8_LDB(B1, 0, 1); PG8_SCHED; PG8_LDA(At, 0, 0); PG8_STAGE(PG8_SA(1, 1), a1 + hstep, voffA);
;             PG8_WAIT_V(8); PG8_WAIT_L(0); PG8_BAR; PG8_MMA(0, 0, At, B0); PG8_MMA(0, 1, At, B1); PG8_BAR; PG8_SCHED;
;             PG8_LDA(At, 0, 1); PG8_STAGE(PG8_SB(0, 0), b2, voffB); PG8_STAGE(PG8_SB(0, 1), b2 + hstep, voffB); PG8_STAGE(PG8_SA(0, 0), a2, voffA);
;             PG8_WAIT_V(8); PG8_WAIT_L(0); PG8_BAR; PG8_MMA(1, 0, At, B0); PG8_MMA(1, 1, At, B1); PG8_BAR; PG8_SCHED;
;             PG8_LDB(B0, 1, 0); PG8_LDB(B1, 1, 1); PG8_SCHED; PG8_LDA(At, 1, 0); PG8_STAGE(PG8_SA(0, 1), a2 + hstep, voffA);
;             PG8_WAIT_V(8); PG8_WAIT_L(0); PG8_BAR; PG8_MMA(0, 0, At, B0); PG8_MMA(0, 1, At, B1); PG8_BAR; PG8_SCHED;
;             PG8_LDA(At, 1, 1); PG8_STAGE(PG8_SB(1, 0), b3, voffB); PG8_STAGE(PG8_SB(1, 1), b3 + hstep, voffB); PG8_STAGE(PG8_SA(1, 0), a3, voffA);
;             PG8_WAIT_V(8); PG8_WAIT_L(0); PG8_BAR; PG8_MMA(1, 0, At, B0); PG8_MMA(1, 1, At, B1); PG8_BAR; PG8_SCHED;
.LBB0_840:
	ds_read_b128 v[148:151], v153
	ds_read_b128 v[158:161], v153 offset:1024
	ds_read_b128 v[162:165], v153 offset:2048
	ds_read_b128 v[166:169], v153 offset:3072
	ds_read_b128 v[170:173], v154
	ds_read_b128 v[174:177], v154 offset:1024
	ds_read_b128 v[180:183], v154 offset:2048
	ds_read_b128 v[184:187], v154 offset:3072
	s_add_u32 s42, s40, 0x4000
	s_addc_u32 s43, s41, 0
	s_cmp_eq_u32 s69, 60
	s_cselect_b32 s46, s65, s42
	s_cselect_b32 s47, s23, s43
	s_cselect_b32 s44, s66, s67
	s_cselect_b32 s45, s17, s68
	s_add_u32 s42, s46, 0x8000
	s_addc_u32 s43, s47, 0
	s_sub_u32 s42, s40, 0x4000
	s_subb_u32 s43, s41, 0
	s_mov_b32 m0, s50
	s_nop 0
	global_load_lds_dwordx4 v130, s[42:43]
	s_mov_b32 m0, s51
	s_nop 0
	global_load_lds_dwordx4 v134, s[42:43]
	s_add_i32 m0, s28, 0xc000
	ds_read_b128 v[188:191], v155
	ds_read_b128 v[198:201], v155 offset:1024
	ds_read_b128 v[202:205], v155 offset:2048
	ds_read_b128 v[206:209], v155 offset:3072
	ds_read_b128 v[210:213], v155 offset:4096
	ds_read_b128 v[214:217], v155 offset:5120
	ds_read_b128 v[218:221], v155 offset:6144
	ds_read_b128 v[222:225], v155 offset:7168
	global_load_lds_dwordx4 v140, s[40:41]
	s_add_i32 m0, s28, 0xe000
	s_nop 0
	global_load_lds_dwordx4 v142, s[40:41]
	s_waitcnt vmcnt(8)
	s_waitcnt lgkmcnt(0)
	s_barrier
	s_setprio 0
	s_waitcnt lgkmcnt(0)
	v_mfma_f32_16x16x32_bf16 v[126:129], v[148:151], v[188:191], v[126:129]
	v_mfma_f32_16x16x32_bf16 v[126:129], v[158:161], v[198:201], v[126:129]
	v_mfma_f32_16x16x32_bf16 v[110:113], v[148:151], v[202:205], v[110:113]
	v_mfma_f32_16x16x32_bf16 v[110:113], v[158:161], v[206:209], v[110:113]
	v_mfma_f32_16x16x32_bf16 v[94:97], v[148:151], v[210:213], v[94:97]
	v_mfma_f32_16x16x32_bf16 v[94:97], v[158:161], v[214:217], v[94:97]
	v_mfma_f32_16x16x32_bf16 v[78:81], v[148:151], v[218:221], v[78:81]
	v_mfma_f32_16x16x32_bf16 v[78:81], v[158:161], v[222:225], v[78:81]
	v_mfma_f32_16x16x32_bf16 v[74:77], v[162:165], v[218:221], v[74:77]
	v_mfma_f32_16x16x32_bf16 v[74:77], v[166:169], v[222:225], v[74:77]
	v_mfma_f32_16x16x32_bf16 v[90:93], v[162:165], v[210:213], v[90:93]
	v_mfma_f32_16x16x32_bf16 v[90:93], v[166:169], v[214:217], v[90:93]
	v_mfma_f32_16x16x32_bf16 v[106:109], v[162:165], v[202:205], v[106:109]
	v_mfma_f32_16x16x32_bf16 v[106:109], v[166:169], v[206:209], v[106:109]
	v_mfma_f32_16x16x32_bf16 v[122:125], v[162:165], v[188:191], v[122:125]
	v_mfma_f32_16x16x32_bf16 v[122:125], v[166:169], v[198:201], v[122:125]
	v_mfma_f32_16x16x32_bf16 v[118:121], v[170:173], v[188:191], v[118:121]
	v_mfma_f32_16x16x32_bf16 v[118:121], v[174:177], v[198:201], v[118:121]
	v_mfma_f32_16x16x32_bf16 v[102:105], v[170:173], v[202:205], v[102:105]
	v_mfma_f32_16x16x32_bf16 v[102:105], v[174:177], v[206:209], v[102:105]
	v_mfma_f32_16x16x32_bf16 v[86:89], v[170:173], v[210:213], v[86:89]
	v_mfma_f32_16x16x32_bf16 v[86:89], v[174:177], v[214:217], v[86:89]
	v_mfma_f32_16x16x32_bf16 v[70:73], v[170:173], v[218:221], v[70:73]
	v_mfma_f32_16x16x32_bf16 v[70:73], v[174:177], v[222:225], v[70:73]
	v_mfma_f32_16x16x32_bf16 v[66:69], v[180:183], v[218:221], v[66:69]
	v_mfma_f32_16x16x32_bf16 v[66:69], v[184:187], v[222:225], v[66:69]
	v_mfma_f32_16x16x32_bf16 v[82:85], v[180:183], v[210:213], v[82:85]
	v_mfma_f32_16x16x32_bf16 v[82:85], v[184:187], v[214:217], v[82:85]
	v_mfma_f32_16x16x32_bf16 v[98:101], v[180:183], v[202:205], v[98:101]
	v_mfma_f32_16x16x32_bf16 v[98:101], v[184:187], v[206:209], v[98:101]
	v_mfma_f32_16x16x32_bf16 v[114:117], v[180:183], v[188:191], v[114:117]
	v_mfma_f32_16x16x32_bf16 v[114:117], v[184:187], v[198:201], v[114:117]
	s_setprio 1
	s_barrier
	s_add_i32 s70, s56, s3
	s_mov_b32 m0, s70
	ds_read_b128 v[188:191], v155 offset:16384
	ds_read_b128 v[198:201], v155 offset:17408
	ds_read_b128 v[202:205], v155 offset:18432
	ds_read_b128 v[206:209], v155 offset:19456
	ds_read_b128 v[210:213], v155 offset:20480
	ds_read_b128 v[214:217], v155 offset:21504
	ds_read_b128 v[218:221], v155 offset:22528
	ds_read_b128 v[222:225], v155 offset:23552
	global_load_lds_dwordx4 v132, s[44:45]
	s_add_i32 m0, s70, 0x2000
	s_add_u32 s70, s44, 0x4000
	s_addc_u32 s71, s45, 0
	s_add_i32 s72, s57, s3
	global_load_lds_dwordx4 v136, s[44:45]
	s_mov_b32 m0, s72
	s_nop 0
	global_load_lds_dwordx4 v132, s[70:71]
	s_add_i32 m0, s72, 0x2000
	s_nop 0
	global_load_lds_dwordx4 v136, s[70:71]
	s_waitcnt vmcnt(6)
	s_waitcnt lgkmcnt(0)
	s_barrier
	s_setprio 0
	s_waitcnt lgkmcnt(0)
	v_mfma_f32_16x16x32_bf16 v[62:65], v[148:151], v[188:191], v[62:65]
	v_mfma_f32_16x16x32_bf16 v[62:65], v[158:161], v[198:201], v[62:65]
	v_mfma_f32_16x16x32_bf16 v[46:49], v[148:151], v[202:205], v[46:49]
	v_mfma_f32_16x16x32_bf16 v[46:49], v[158:161], v[206:209], v[46:49]
	v_mfma_f32_16x16x32_bf16 v[30:33], v[148:151], v[210:213], v[30:33]
	v_mfma_f32_16x16x32_bf16 v[30:33], v[158:161], v[214:217], v[30:33]
	v_mfma_f32_16x16x32_bf16 v[14:17], v[148:151], v[218:221], v[14:17]
	v_mfma_f32_16x16x32_bf16 v[14:17], v[158:161], v[222:225], v[14:17]
	v_mfma_f32_16x16x32_bf16 v[10:13], v[162:165], v[218:221], v[10:13]
	v_mfma_f32_16x16x32_bf16 v[10:13], v[166:169], v[222:225], v[10:13]
	v_mfma_f32_16x16x32_bf16 v[26:29], v[162:165], v[210:213], v[26:29]
	v_mfma_f32_16x16x32_bf16 v[26:29], v[166:169], v[214:217], v[26:29]
	v_mfma_f32_16x16x32_bf16 v[42:45], v[162:165], v[202:205], v[42:45]
	v_mfma_f32_16x16x32_bf16 v[42:45], v[166:169], v[206:209], v[42:45]
	v_mfma_f32_16x16x32_bf16 v[58:61], v[162:165], v[188:191], v[58:61]
	v_mfma_f32_16x16x32_bf16 v[58:61], v[166:169], v[198:201], v[58:61]
	v_mfma_f32_16x16x32_bf16 v[54:57], v[170:173], v[188:191], v[54:57]
	v_mfma_f32_16x16x32_bf16 v[54:57], v[174:177], v[198:201], v[54:57]
	v_mfma_f32_16x16x32_bf16 v[38:41], v[170:173], v[202:205], v[38:41]
	v_mfma_f32_16x16x32_bf16 v[38:41], v[174:177], v[206:209], v[38:41]
	v_mfma_f32_16x16x32_bf16 v[22:25], v[170:173], v[210:213], v[22:25]
	v_mfma_f32_16x16x32_bf16 v[22:25], v[174:177], v[214:217], v[22:25]
	v_mfma_f32_16x16x32_bf16 v[6:9], v[170:173], v[218:221], v[6:9]
	v_mfma_f32_16x16x32_bf16 v[6:9], v[174:177], v[222:225], v[6:9]
	v_mfma_f32_16x16x32_bf16 v[2:5], v[180:183], v[218:221], v[2:5]
	v_mfma_f32_16x16x32_bf16 v[2:5], v[184:187], v[222:225], v[2:5]
	v_mfma_f32_16x16x32_bf16 v[18:21], v[180:183], v[210:213], v[18:21]
	v_mfma_f32_16x16x32_bf16 v[18:21], v[184:187], v[214:217], v[18:21]
	v_mfma_f32_16x16x32_bf16 v[34:37], v[180:183], v[202:205], v[34:37]
	v_mfma_f32_16x16x32_bf16 v[34:37], v[184:187], v[206:209], v[34:37]
	v_mfma_f32_16x16x32_bf16 v[50:53], v[180:183], v[188:191], v[50:53]
	v_mfma_f32_16x16x32_bf16 v[50:53], v[184:187], v[198:201], v[50:53]
	s_setprio 1
	s_barrier
; #define PG8_STAGE(bufoff, gbase, voff) do { _Pragma("unroll") for (int _i = 0; _i < 2; ++_i) \
;         __builtin_amdgcn_global_load_lds((const unsigned*)((const char*)(gbase) + (voff)[_i]), (PG8_LAS unsigned*)(lds + (bufoff) + ldsw + _i * 8192), 16, 0, 0); } while (0)
; #define PG8_LDA(dst, b, h) do { _Pragma("unroll") for (int m = 0; m < 4; ++m) _Pragma("unroll") for (int k = 0; k < 2; ++k) dst[m][k] = *(const PG8_LAS bf16x8*)(lds + PG8_SA(b, h) + aoff + m * 2048 + k * 1024); } while (0)
; #define PG8_LDB(dst, b, h) do { _Pragma("unroll") for (int n = 0; n < 2; ++n) _Pragma("unroll") for (int k = 0; k < 2; ++k) dst[n][k] = *(const PG8_LAS bf16x8*)(lds + PG8_SB(b, h) + boff + n * 2048 + k * 1024); } while (0)
; template <class Epi, class Sched, bool ALIGN_EPI = false, bool SP2 = false>
; __device__ __forceinline__ void gemm_phase(PG8_LAS unsigned char* lds, const Gemm g, const Sched& S, const Epi& E) {
;     ...
;         for (; t < tend; t += 2) {
;             const bool last = (t == nt - 2);
;             const char* a1 = cA + (size_t)(t + 1) * kstep;
;             const char* a2 = last ? nA : cA + (size_t)(t + 2) * kstep; const char* b2 = last ? nB : cB + (size_t)(t + 2) * kstep;
;             const char* a3 = a2 + kstep; const char* b3 = b2 + kstep;
;             if (last && has_next) S.a_ready(nxt);
;             if constexpr (SP2) {
;             PG8_LDB(B0, 0, 0); PG8_LDB(B1, 0, 1); PG8_SCHED; PG8_LDA(At, 0, 0); PG8_STAGE(PG8_SA(1, 1), a1 + hstep, voffA);
;             PG8_WAIT_V(8); PG8_WAIT_L(0); PG8_BAR; PG8_MMA(0, 0, At, B0); PG8_MMA(0, 1, At, B1); PG8_BAR; PG8_SCHED;
;             PG8_LDA(At, 0, 1); PG8_STAGE(PG8_SB(0, 0), b2, voffB); PG8_STAGE(PG8_SB(0, 1), b2 + hstep, voffB); PG8_STAGE(PG8_SA(0, 0), a2, voffA);
;             PG8_WAIT_V(8); PG8_WAIT_L(0); PG8_BAR; PG8_MMA(1, 0, At, B0); PG8_MMA(1, 1, At, B1); PG8_BAR; PG8_SCHED;
;             PG8_LDB(B0, 1, 0); PG8_LDB(B1, 1, 1); PG8_SCHED; PG8_LDA(At, 1, 0); PG8_STAGE(PG8_SA(0, 1), a2 + hstep, voffA);
;             PG8_WAIT_V(8); PG8_WAIT_L(0); PG8_BAR; PG8_MMA(0, 0, At, B0); PG8_MMA(0, 1, At, B1); PG8_BAR; PG8_SCHED;
;             PG8_LDA(At, 1, 1); PG8_STAGE(PG8_SB(1, 0), b3, voffB); PG8_STAGE(PG8_SB(1, 1), b3 + hstep, voffB); PG8_STAGE(PG8_SA(1, 0), a3, voffA);
;             PG8_WAIT_V(8); PG8_WAIT_L(0); PG8_BAR; PG8_MMA(1, 0, At, B0); PG8_MMA(1, 1, At, B1); PG8_BAR; PG8_SCHED;
	s_add_i32 s70, 0, 0x18000
	v_add_u32_e32 v138, s70, v1
	s_add_i32 s71, 0, 0x1c000
	ds_read_b128 v[148:151], v138
	ds_read_b128 v[158:161], v138 offset:1024
	ds_read_b128 v[162:165], v138 offset:2048
	ds_read_b128 v[166:169], v138 offset:3072
	v_add_u32_e32 v138, s71, v1
	ds_read_b128 v[170:173], v138
	ds_read_b128 v[174:177], v138 offset:1024
	ds_read_b128 v[180:183], v138 offset:2048
	ds_read_b128 v[184:187], v138 offset:3072
	s_mov_b32 m0, s28
	s_nop 0
	global_load_lds_dwordx4 v130, s[46:47]
	s_mov_b32 m0, s29
	s_nop 0
	global_load_lds_dwordx4 v134, s[46:47]
	s_add_u32 s46, s46, 0x4000
	s_addc_u32 s47, s47, 0
	s_mov_b32 m0, s30
	ds_read_b128 v[188:191], v155 offset:32768
	ds_read_b128 v[198:201], v155 offset:33792
	ds_read_b128 v[202:205], v155 offset:34816
	ds_read_b128 v[206:209], v155 offset:35840
	ds_read_b128 v[210:213], v155 offset:36864
	ds_read_b128 v[214:217], v155 offset:37888
	ds_read_b128 v[218:221], v155 offset:38912
	ds_read_b128 v[222:225], v155 offset:39936
	global_load_lds_dwordx4 v130, s[46:47]
	s_mov_b32 m0, s31
	s_nop 0
	global_load_lds_dwordx4 v134, s[46:47]
	s_waitcnt vmcnt(8)
	s_waitcnt lgkmcnt(0)
	s_barrier
	s_setprio 0
	s_waitcnt lgkmcnt(0)
	v_mfma_f32_16x16x32_bf16 v[126:129], v[148:151], v[188:191], v[126:129]
	v_mfma_f32_16x16x32_bf16 v[126:129], v[158:161], v[198:201], v[126:129]
	v_mfma_f32_16x16x32_bf16 v[110:113], v[148:151], v[202:205], v[110:113]
	v_mfma_f32_16x16x32_bf16 v[110:113], v[158:161], v[206:209], v[110:113]
	v_mfma_f32_16x16x32_bf16 v[94:97], v[148:151], v[210:213], v[94:97]
	v_mfma_f32_16x16x32_bf16 v[94:97], v[158:161], v[214:217], v[94:97]
	v_mfma_f32_16x16x32_bf16 v[78:81], v[148:151], v[218:221], v[78:81]
	v_mfma_f32_16x16x32_bf16 v[78:81], v[158:161], v[222:225], v[78:81]
	v_mfma_f32_16x16x32_bf16 v[74:77], v[162:165], v[218:221], v[74:77]
	v_mfma_f32_16x16x32_bf16 v[74:77], v[166:169], v[222:225], v[74:77]
	v_mfma_f32_16x16x32_bf16 v[90:93], v[162:165], v[210:213], v[90:93]
	v_mfma_f32_16x16x32_bf16 v[90:93], v[166:169], v[214:217], v[90:93]
	v_mfma_f32_16x16x32_bf16 v[106:109], v[162:165], v[202:205], v[106:109]
	v_mfma_f32_16x16x32_bf16 v[106:109], v[166:169], v[206:209], v[106:109]
	v_mfma_f32_16x16x32_bf16 v[122:125], v[162:165], v[188:191], v[122:125]
	v_mfma_f32_16x16x32_bf16 v[122:125], v[166:169], v[198:201], v[122:125]
	v_mfma_f32_16x16x32_bf16 v[118:121], v[170:173], v[188:191], v[118:121]
	v_mfma_f32_16x16x32_bf16 v[118:121], v[174:177], v[198:201], v[118:121]
	v_mfma_f32_16x16x32_bf16 v[102:105], v[170:173], v[202:205], v[102:105]
	v_mfma_f32_16x16x32_bf16 v[102:105], v[174:177], v[206:209], v[102:105]
	v_mfma_f32_16x16x32_bf16 v[86:89], v[170:173], v[210:213], v[86:89]
	v_mfma_f32_16x16x32_bf16 v[86:89], v[174:177], v[214:217], v[86:89]
	v_mfma_f32_16x16x32_bf16 v[70:73], v[170:173], v[218:221], v[70:73]
	v_mfma_f32_16x16x32_bf16 v[70:73], v[174:177], v[222:225], v[70:73]
	v_mfma_f32_16x16x32_bf16 v[66:69], v[180:183], v[218:221], v[66:69]
	v_mfma_f32_16x16x32_bf16 v[66:69], v[184:187], v[222:225], v[66:69]
	v_mfma_f32_16x16x32_bf16 v[82:85], v[180:183], v[210:213], v[82:85]
	v_mfma_f32_16x16x32_bf16 v[82:85], v[184:187], v[214:217], v[82:85]
	v_mfma_f32_16x16x32_bf16 v[98:101], v[180:183], v[202:205], v[98:101]
	v_mfma_f32_16x16x32_bf16 v[98:101], v[184:187], v[206:209], v[98:101]
	v_mfma_f32_16x16x32_bf16 v[114:117], v[180:183], v[188:191], v[114:117]
	v_mfma_f32_16x16x32_bf16 v[114:117], v[184:187], v[198:201], v[114:117]
	s_setprio 1
	s_barrier
	s_add_u32 s46, s44, 0x8000
	s_addc_u32 s47, s45, 0
	s_add_i32 s70, s70, s3
	s_mov_b32 m0, s70
	ds_read_b128 v[188:191], v155 offset:49152
	ds_read_b128 v[198:201], v155 offset:50176
	ds_read_b128 v[202:205], v155 offset:51200
	ds_read_b128 v[206:209], v155 offset:52224
	ds_read_b128 v[210:213], v155 offset:53248
	ds_read_b128 v[214:217], v155 offset:54272
	ds_read_b128 v[218:221], v155 offset:55296
	ds_read_b128 v[222:225], v155 offset:56320
	global_load_lds_dwordx4 v132, s[46:47]
	s_add_i32 m0, s70, 0x2000
	s_add_u32 s44, s44, 0xc000
	v_lshl_add_u64 v[226:227], s[46:47], 0, v[136:137]
	s_addc_u32 s45, s45, 0
	s_add_i32 s46, s71, s3
	global_load_lds_dwordx4 v[226:227], off
	s_mov_b32 m0, s46
	s_nop 0
	global_load_lds_dwordx4 v132, s[44:45]
	s_add_i32 m0, s46, 0x2000
	s_nop 0
	global_load_lds_dwordx4 v136, s[44:45]
	s_waitcnt vmcnt(6)
	s_waitcnt lgkmcnt(0)
	s_barrier
	s_setprio 0
	s_waitcnt lgkmcnt(0)
	v_mfma_f32_16x16x32_bf16 v[62:65], v[148:151], v[188:191], v[62:65]
	v_mfma_f32_16x16x32_bf16 v[62:65], v[158:161], v[198:201], v[62:65]
	v_mfma_f32_16x16x32_bf16 v[46:49], v[148:151], v[202:205], v[46:49]
	v_mfma_f32_16x16x32_bf16 v[46:49], v[158:161], v[206:209], v[46:49]
	v_mfma_f32_16x16x32_bf16 v[30:33], v[148:151], v[210:213], v[30:33]
	v_mfma_f32_16x16x32_bf16 v[30:33], v[158:161], v[214:217], v[30:33]
	v_mfma_f32_16x16x32_bf16 v[14:17], v[148:151], v[218:221], v[14:17]
	v_mfma_f32_16x16x32_bf16 v[14:17], v[158:161], v[222:225], v[14:17]
	v_mfma_f32_16x16x32_bf16 v[10:13], v[162:165], v[218:221], v[10:13]
	v_mfma_f32_16x16x32_bf16 v[10:13], v[166:169], v[222:225], v[10:13]
	v_mfma_f32_16x16x32_bf16 v[26:29], v[162:165], v[210:213], v[26:29]
	v_mfma_f32_16x16x32_bf16 v[26:29], v[166:169], v[214:217], v[26:29]
	v_mfma_f32_16x16x32_bf16 v[42:45], v[162:165], v[202:205], v[42:45]
	v_mfma_f32_16x16x32_bf16 v[42:45], v[166:169], v[206:209], v[42:45]
	v_mfma_f32_16x16x32_bf16 v[58:61], v[162:165], v[188:191], v[58:61]
	v_mfma_f32_16x16x32_bf16 v[58:61], v[166:169], v[198:201], v[58:61]
	v_mfma_f32_16x16x32_bf16 v[54:57], v[170:173], v[188:191], v[54:57]
	v_mfma_f32_16x16x32_bf16 v[54:57], v[174:177], v[198:201], v[54:57]
	v_mfma_f32_16x16x32_bf16 v[38:41], v[170:173], v[202:205], v[38:41]
	v_mfma_f32_16x16x32_bf16 v[38:41], v[174:177], v[206:209], v[38:41]
	v_mfma_f32_16x16x32_bf16 v[22:25], v[170:173], v[210:213], v[22:25]
	v_mfma_f32_16x16x32_bf16 v[22:25], v[174:177], v[214:217], v[22:25]
	v_mfma_f32_16x16x32_bf16 v[6:9], v[170:173], v[218:221], v[6:9]
	v_mfma_f32_16x16x32_bf16 v[6:9], v[174:177], v[222:225], v[6:9]
	v_mfma_f32_16x16x32_bf16 v[2:5], v[180:183], v[218:221], v[2:5]
	v_mfma_f32_16x16x32_bf16 v[2:5], v[184:187], v[222:225], v[2:5]
	v_mfma_f32_16x16x32_bf16 v[18:21], v[180:183], v[210:213], v[18:21]
	v_mfma_f32_16x16x32_bf16 v[18:21], v[184:187], v[214:217], v[18:21]
	v_mfma_f32_16x16x32_bf16 v[34:37], v[180:183], v[202:205], v[34:37]
	v_mfma_f32_16x16x32_bf16 v[34:37], v[184:187], v[206:209], v[34:37]
	v_mfma_f32_16x16x32_bf16 v[50:53], v[180:183], v[188:191], v[50:53]
	v_mfma_f32_16x16x32_bf16 v[50:53], v[184:187], v[198:201], v[50:53]
	s_setprio 1
	s_barrier
	s_add_i32 s69, s69, 2
	s_add_u32 s40, s40, 0x10000
	s_addc_u32 s41, s41, 0
	s_add_u32 s67, s67, 0x10000
	s_addc_u32 s68, s68, 0
	s_cmp_gt_u32 s69, 61
	s_cbranch_scc0 .LBB0_840
	s_setprio 0
	s_and_b64 vcc, exec, s[14:15]
	s_cbranch_vccz .LBB0_843
	s_barrier

; #define PG8_STAGE(bufoff, gbase, voff) do { _Pragma("unroll") for (int _i = 0; _i < 2; ++_i) \
;         __builtin_amdgcn_global_load_lds((const unsigned*)((const char*)(gbase) + (voff)[_i]), (PG8_LAS unsigned*)(lds + (bufoff) + ldsw + _i * 8192), 16, 0, 0); } while (0)
; #define PG8_LDA(dst, b, h) do { _Pragma("unroll") for (int m = 0; m < 4; ++m) _Pragma("unroll") for (int k = 0; k < 2; ++k) dst[m][k] = *(const PG8_LAS bf16x8*)(lds + PG8_SA(b, h) + aoff + m * 2048 + k * 1024); } while (0)
; #define PG8_LDB(dst, b, h) do { _Pragma("unroll") for (int n = 0; n < 2; ++n) _Pragma("unroll") for (int k = 0; k < 2; ++k) dst[n][k] = *(const PG8_LAS bf16x8*)(lds + PG8_SB(b, h) + boff + n * 2048 + k * 1024); } while (0)
; #define PG8_MMA(ai, bj, At, Bt) do { __builtin_amdgcn_s_setprio(1); _Pragma("unroll") for (int m = 0; m < 4; ++m) _Pragma("unroll") for (int n = 0; n < 2; ++n) _Pragma("unroll") for (int k = 0; k < 2; ++k) \
;         acc[ai][bj][m][n] = __builtin_amdgcn_mfma_f32_16x16x32_bf16(Bt[n][k], At[m][k], acc[ai][bj][m][n], 0, 0, 0); __builtin_amdgcn_s_setprio(0); } while (0)
; #define PG8_WAIT_V(n) asm volatile("s_waitcnt vmcnt(" #n ")" ::: "memory")
; #define PG8_WAIT_L(n) asm volatile("s_waitcnt lgkmcnt(" #n ")" ::: "memory")
; #define PG8_BAR __builtin_amdgcn_s_barrier()
; #define PG8_SCHED __builtin_amdgcn_sched_barrier(0)
; template <class Epi, class Sched, bool ALIGN_EPI = false, bool SP2 = false>
; __device__ __forceinline__ void gemm_phase(PG8_LAS unsigned char* lds, const Gemm g, const Sched& S, const Epi& E) {
;     ...
;         for (; t < tend; t += 2) {
;             const bool last = (t == nt - 2);
;             const char* a1 = cA + (size_t)(t + 1) * kstep;
;             const char* a2 = last ? nA : cA + (size_t)(t + 2) * kstep; const char* b2 = last ? nB : cB + (size_t)(t + 2) * kstep;
;             const char* a3 = a2 + kstep; const char* b3 = b2 + kstep;
;             if (last && has_next) S.a_ready(nxt);
;             if constexpr (SP2) {
;             PG8_LDB(B0, 0, 0); PG8_LDB(B1, 0, 1); PG8_SCHED; PG8_LDA(At, 0, 0); PG8_STAGE(PG8_SA(1, 1), a1 + hstep, voffA);
;             PG8_WAIT_V(8); PG8_WAIT_L(0); PG8_BAR; PG8_MMA(0, 0, At, B0); PG8_MMA(0, 1, At, B1); PG8_BAR; PG8_SCHED;
;             PG8_LDA(At, 0, 1); PG8_STAGE(PG8_SB(0, 0), b2, voffB); PG8_STAGE(PG8_SB(0, 1), b2 + hstep, voffB); PG8_STAGE(PG8_SA(0, 0), a2, voffA);
.LBB0_939:
	s_or_b32 s24, s59, 1
	s_lshl_b64 s[62:63], s[24:25], 15
	s_add_i32 s24, s59, 2
	ds_read_b128 v[156:159], v193
	ds_read_b128 v[160:163], v193 offset:1024
	ds_read_b128 v[196:199], v193 offset:2048
	ds_read_b128 v[200:203], v193 offset:3072
	ds_read_b128 v[204:207], v194
	ds_read_b128 v[208:211], v194 offset:1024
	ds_read_b128 v[212:215], v194 offset:2048
	ds_read_b128 v[216:219], v194 offset:3072
	s_lshl_b64 s[8:9], s[24:25], 15
	s_add_u32 s44, s6, s8
	s_addc_u32 s45, s7, s9
	s_cmpk_eq_i32 s59, 0xaa
	s_cselect_b32 s46, s58, s44
	s_cselect_b32 s47, s56, s45
	s_cselect_b32 s44, 0, s8
	s_cselect_b32 s45, 0, s9
	s_add_u32 s8, s46, 0x8000
	s_addc_u32 s9, s47, 0
	s_add_u32 s44, s14, s44
	s_addc_u32 s45, s15, s45
	s_add_u32 s62, s6, s62
	s_addc_u32 s63, s7, s63
	s_add_u32 s62, s62, 0x4000
	s_addc_u32 s63, s63, 0
	s_sub_u32 s8, s62, 0x4000
	s_subb_u32 s9, s63, 0
	s_mov_b32 m0, s51
	s_nop 0
	global_load_lds_dwordx4 v130, s[8:9]
	s_mov_b32 m0, s57
	s_nop 0
	global_load_lds_dwordx4 v134, s[8:9]
	s_add_i32 m0, s30, 0xc000
	ds_read_b128 v[220:223], v186
	ds_read_b128 v[224:227], v186 offset:1024
	ds_read_b128 v[228:231], v186 offset:2048
	ds_read_b128 v[232:235], v186 offset:3072
	ds_read_b128 v[236:239], v186 offset:4096
	ds_read_b128 v[240:243], v186 offset:5120
	ds_read_b128 v[244:247], v186 offset:6144
	ds_read_b128 v[248:251], v186 offset:7168
	global_load_lds_dwordx4 v130, s[62:63]
	s_add_i32 m0, s30, 0xe000
	s_nop 0
	global_load_lds_dwordx4 v134, s[62:63]
	s_waitcnt vmcnt(8)
	s_waitcnt lgkmcnt(0)
	s_barrier
	s_setprio 0
	s_waitcnt lgkmcnt(0)
	v_mfma_f32_16x16x32_bf16 v[126:129], v[156:159], v[220:223], v[126:129]
	v_mfma_f32_16x16x32_bf16 v[126:129], v[160:163], v[224:227], v[126:129]
	v_mfma_f32_16x16x32_bf16 v[110:113], v[156:159], v[228:231], v[110:113]
	v_mfma_f32_16x16x32_bf16 v[110:113], v[160:163], v[232:235], v[110:113]
	v_mfma_f32_16x16x32_bf16 v[94:97], v[156:159], v[236:239], v[94:97]
	v_mfma_f32_16x16x32_bf16 v[94:97], v[160:163], v[240:243], v[94:97]
	v_mfma_f32_16x16x32_bf16 v[78:81], v[156:159], v[244:247], v[78:81]
	v_mfma_f32_16x16x32_bf16 v[78:81], v[160:163], v[248:251], v[78:81]
	v_mfma_f32_16x16x32_bf16 v[74:77], v[196:199], v[244:247], v[74:77]
	v_mfma_f32_16x16x32_bf16 v[74:77], v[200:203], v[248:251], v[74:77]
	v_mfma_f32_16x16x32_bf16 v[90:93], v[196:199], v[236:239], v[90:93]
	v_mfma_f32_16x16x32_bf16 v[90:93], v[200:203], v[240:243], v[90:93]
	v_mfma_f32_16x16x32_bf16 v[106:109], v[196:199], v[228:231], v[106:109]
	v_mfma_f32_16x16x32_bf16 v[106:109], v[200:203], v[232:235], v[106:109]
	v_mfma_f32_16x16x32_bf16 v[122:125], v[196:199], v[220:223], v[122:125]
	v_mfma_f32_16x16x32_bf16 v[122:125], v[200:203], v[224:227], v[122:125]
	v_mfma_f32_16x16x32_bf16 v[118:121], v[204:207], v[220:223], v[118:121]
	v_mfma_f32_16x16x32_bf16 v[118:121], v[208:211], v[224:227], v[118:121]
	v_mfma_f32_16x16x32_bf16 v[102:105], v[204:207], v[228:231], v[102:105]
	v_mfma_f32_16x16x32_bf16 v[102:105], v[208:211], v[232:235], v[102:105]
	v_mfma_f32_16x16x32_bf16 v[86:89], v[204:207], v[236:239], v[86:89]
	v_mfma_f32_16x16x32_bf16 v[86:89], v[208:211], v[240:243], v[86:89]
	v_mfma_f32_16x16x32_bf16 v[70:73], v[204:207], v[244:247], v[70:73]
	v_mfma_f32_16x16x32_bf16 v[70:73], v[208:211], v[248:251], v[70:73]
	v_mfma_f32_16x16x32_bf16 v[66:69], v[212:215], v[244:247], v[66:69]
	v_mfma_f32_16x16x32_bf16 v[66:69], v[216:219], v[248:251], v[66:69]
	v_mfma_f32_16x16x32_bf16 v[82:85], v[212:215], v[236:239], v[82:85]
	v_mfma_f32_16x16x32_bf16 v[82:85], v[216:219], v[240:243], v[82:85]
	v_mfma_f32_16x16x32_bf16 v[98:101], v[212:215], v[228:231], v[98:101]
	v_mfma_f32_16x16x32_bf16 v[98:101], v[216:219], v[232:235], v[98:101]
	v_mfma_f32_16x16x32_bf16 v[114:117], v[212:215], v[220:223], v[114:117]
	v_mfma_f32_16x16x32_bf16 v[114:117], v[216:219], v[224:227], v[114:117]
	s_setprio 1
	s_barrier
	s_add_i32 s62, s67, s29
	s_mov_b32 m0, s62
	ds_read_b128 v[220:223], v186 offset:16384
	ds_read_b128 v[224:227], v186 offset:17408
	ds_read_b128 v[228:231], v186 offset:18432
	ds_read_b128 v[232:235], v186 offset:19456
	ds_read_b128 v[236:239], v186 offset:20480
	ds_read_b128 v[240:243], v186 offset:21504
	ds_read_b128 v[244:247], v186 offset:22528
	ds_read_b128 v[248:251], v186 offset:23552
	global_load_lds_dwordx4 v132, s[44:45]
	s_add_i32 m0, s62, 0x2000
	s_add_u32 s62, s44, 0x4000
	s_addc_u32 s63, s45, 0
	s_add_i32 s72, s68, s29
	global_load_lds_dwordx4 v136, s[44:45]
	s_mov_b32 m0, s72
	s_nop 0
	global_load_lds_dwordx4 v132, s[62:63]
	s_add_i32 m0, s72, 0x2000
	s_nop 0
	global_load_lds_dwordx4 v136, s[62:63]
	s_waitcnt vmcnt(6)
	s_waitcnt lgkmcnt(0)
	s_barrier
; #define PG8_STAGE(bufoff, gbase, voff) do { _Pragma("unroll") for (int _i = 0; _i < 2; ++_i) \
;         __builtin_amdgcn_global_load_lds((const unsigned*)((const char*)(gbase) + (voff)[_i]), (PG8_LAS unsigned*)(lds + (bufoff) + ldsw + _i * 8192), 16, 0, 0); } while (0)
; #define PG8_LDA(dst, b, h) do { _Pragma("unroll") for (int m = 0; m < 4; ++m) _Pragma("unroll") for (int k = 0; k < 2; ++k) dst[m][k] = *(const PG8_LAS bf16x8*)(lds + PG8_SA(b, h) + aoff + m * 2048 + k * 1024); } while (0)
; #define PG8_LDB(dst, b, h) do { _Pragma("unroll") for (int n = 0; n < 2; ++n) _Pragma("unroll") for (int k = 0; k < 2; ++k) dst[n][k] = *(const PG8_LAS bf16x8*)(lds + PG8_SB(b, h) + boff + n * 2048 + k * 1024); } while (0)
; #define PG8_MMA(ai, bj, At, Bt) do { __builtin_amdgcn_s_setprio(1); _Pragma("unroll") for (int m = 0; m < 4; ++m) _Pragma("unroll") for (int n = 0; n < 2; ++n) _Pragma("unroll") for (int k = 0; k < 2; ++k) \
;         acc[ai][bj][m][n] = __builtin_amdgcn_mfma_f32_16x16x32_bf16(Bt[n][k], At[m][k], acc[ai][bj][m][n], 0, 0, 0); __builtin_amdgcn_s_setprio(0); } while (0)
; #define PG8_WAIT_V(n) asm volatile("s_waitcnt vmcnt(" #n ")" ::: "memory")
; #define PG8_WAIT_L(n) asm volatile("s_waitcnt lgkmcnt(" #n ")" ::: "memory")
; #define PG8_BAR __builtin_amdgcn_s_barrier()
; #define PG8_SCHED __builtin_amdgcn_sched_barrier(0)
; template <class Epi, class Sched, bool ALIGN_EPI = false, bool SP2 = false>
; __device__ __forceinline__ void gemm_phase(PG8_LAS unsigned char* lds, const Gemm g, const Sched& S, const Epi& E) {
;     ...
;             PG8_LDA(At, 0, 1); PG8_STAGE(PG8_SB(0, 0), b2, voffB); PG8_STAGE(PG8_SB(0, 1), b2 + hstep, voffB); PG8_STAGE(PG8_SA(0, 0), a2, voffA);
;             PG8_WAIT_V(8); PG8_WAIT_L(0); PG8_BAR; PG8_MMA(1, 0, At, B0); PG8_MMA(1, 1, At, B1); PG8_BAR; PG8_SCHED;
;             PG8_LDB(B0, 1, 0); PG8_LDB(B1, 1, 1); PG8_SCHED; PG8_LDA(At, 1, 0); PG8_STAGE(PG8_SA(0, 1), a2 + hstep, voffA);
;             PG8_WAIT_V(8); PG8_WAIT_L(0); PG8_BAR; PG8_MMA(0, 0, At, B0); PG8_MMA(0, 1, At, B1); PG8_BAR; PG8_SCHED;
;             PG8_LDA(At, 1, 1); PG8_STAGE(PG8_SB(1, 0), b3, voffB); PG8_STAGE(PG8_SB(1, 1), b3 + hstep, voffB); PG8_STAGE(PG8_SA(1, 0), a3, voffA);
	s_setprio 0
	s_waitcnt lgkmcnt(0)
	v_mfma_f32_16x16x32_bf16 v[62:65], v[156:159], v[220:223], v[62:65]
	v_mfma_f32_16x16x32_bf16 v[62:65], v[160:163], v[224:227], v[62:65]
	v_mfma_f32_16x16x32_bf16 v[46:49], v[156:159], v[228:231], v[46:49]
	v_mfma_f32_16x16x32_bf16 v[46:49], v[160:163], v[232:235], v[46:49]
	v_mfma_f32_16x16x32_bf16 v[30:33], v[156:159], v[236:239], v[30:33]
	v_mfma_f32_16x16x32_bf16 v[30:33], v[160:163], v[240:243], v[30:33]
	v_mfma_f32_16x16x32_bf16 v[14:17], v[156:159], v[244:247], v[14:17]
	v_mfma_f32_16x16x32_bf16 v[14:17], v[160:163], v[248:251], v[14:17]
	v_mfma_f32_16x16x32_bf16 v[10:13], v[196:199], v[244:247], v[10:13]
	v_mfma_f32_16x16x32_bf16 v[10:13], v[200:203], v[248:251], v[10:13]
	v_mfma_f32_16x16x32_bf16 v[26:29], v[196:199], v[236:239], v[26:29]
	v_mfma_f32_16x16x32_bf16 v[26:29], v[200:203], v[240:243], v[26:29]
	v_mfma_f32_16x16x32_bf16 v[42:45], v[196:199], v[228:231], v[42:45]
	v_mfma_f32_16x16x32_bf16 v[42:45], v[200:203], v[232:235], v[42:45]
	v_mfma_f32_16x16x32_bf16 v[58:61], v[196:199], v[220:223], v[58:61]
	v_mfma_f32_16x16x32_bf16 v[58:61], v[200:203], v[224:227], v[58:61]
	v_mfma_f32_16x16x32_bf16 v[54:57], v[204:207], v[220:223], v[54:57]
	v_mfma_f32_16x16x32_bf16 v[54:57], v[208:211], v[224:227], v[54:57]
	v_mfma_f32_16x16x32_bf16 v[38:41], v[204:207], v[228:231], v[38:41]
	v_mfma_f32_16x16x32_bf16 v[38:41], v[208:211], v[232:235], v[38:41]
	v_mfma_f32_16x16x32_bf16 v[22:25], v[204:207], v[236:239], v[22:25]
	v_mfma_f32_16x16x32_bf16 v[22:25], v[208:211], v[240:243], v[22:25]
	v_mfma_f32_16x16x32_bf16 v[6:9], v[204:207], v[244:247], v[6:9]
	v_mfma_f32_16x16x32_bf16 v[6:9], v[208:211], v[248:251], v[6:9]
	v_mfma_f32_16x16x32_bf16 v[2:5], v[212:215], v[244:247], v[2:5]
	v_mfma_f32_16x16x32_bf16 v[2:5], v[216:219], v[248:251], v[2:5]
	v_mfma_f32_16x16x32_bf16 v[18:21], v[212:215], v[236:239], v[18:21]
	v_mfma_f32_16x16x32_bf16 v[18:21], v[216:219], v[240:243], v[18:21]
	v_mfma_f32_16x16x32_bf16 v[34:37], v[212:215], v[228:231], v[34:37]
	v_mfma_f32_16x16x32_bf16 v[34:37], v[216:219], v[232:235], v[34:37]
	v_mfma_f32_16x16x32_bf16 v[50:53], v[212:215], v[220:223], v[50:53]
	v_mfma_f32_16x16x32_bf16 v[50:53], v[216:219], v[224:227], v[50:53]
	s_setprio 1
	s_barrier
	s_add_i32 s62, 0, 0x18000
	v_add_u32_e32 v145, s62, v166
	s_add_i32 s63, 0, 0x1c000
	ds_read_b128 v[156:159], v145
	ds_read_b128 v[160:163], v145 offset:1024
	ds_read_b128 v[196:199], v145 offset:2048
	ds_read_b128 v[200:203], v145 offset:3072
	v_add_u32_e32 v145, s63, v166
	ds_read_b128 v[204:207], v145
	ds_read_b128 v[208:211], v145 offset:1024
	ds_read_b128 v[212:215], v145 offset:2048
	ds_read_b128 v[216:219], v145 offset:3072
	s_mov_b32 m0, s30
	s_nop 0
	global_load_lds_dwordx4 v130, s[46:47]
	s_mov_b32 m0, s31
	s_nop 0
	global_load_lds_dwordx4 v134, s[46:47]
	s_add_u32 s46, s46, 0x4000
	s_addc_u32 s47, s47, 0
	s_mov_b32 m0, s35
	ds_read_b128 v[220:223], v186 offset:32768
	ds_read_b128 v[224:227], v186 offset:33792
	ds_read_b128 v[228:231], v186 offset:34816
	ds_read_b128 v[232:235], v186 offset:35840
	ds_read_b128 v[236:239], v186 offset:36864
	ds_read_b128 v[240:243], v186 offset:37888
	ds_read_b128 v[244:247], v186 offset:38912
	ds_read_b128 v[248:251], v186 offset:39936
	global_load_lds_dwordx4 v130, s[46:47]
	s_mov_b32 m0, s48
	s_nop 0
	global_load_lds_dwordx4 v134, s[46:47]
	s_waitcnt vmcnt(8)
	s_waitcnt lgkmcnt(0)
	s_barrier
; #define PG8_STAGE(bufoff, gbase, voff) do { _Pragma("unroll") for (int _i = 0; _i < 2; ++_i) \
;         __builtin_amdgcn_global_load_lds((const unsigned*)((const char*)(gbase) + (voff)[_i]), (PG8_LAS unsigned*)(lds + (bufoff) + ldsw + _i * 8192), 16, 0, 0); } while (0)
; #define PG8_LDA(dst, b, h) do { _Pragma("unroll") for (int m = 0; m < 4; ++m) _Pragma("unroll") for (int k = 0; k < 2; ++k) dst[m][k] = *(const PG8_LAS bf16x8*)(lds + PG8_SA(b, h) + aoff + m * 2048 + k * 1024); } while (0)
; #define PG8_MMA(ai, bj, At, Bt) do { __builtin_amdgcn_s_setprio(1); _Pragma("unroll") for (int m = 0; m < 4; ++m) _Pragma("unroll") for (int n = 0; n < 2; ++n) _Pragma("unroll") for (int k = 0; k < 2; ++k) \
;         acc[ai][bj][m][n] = __builtin_amdgcn_mfma_f32_16x16x32_bf16(Bt[n][k], At[m][k], acc[ai][bj][m][n], 0, 0, 0); __builtin_amdgcn_s_setprio(0); } while (0)
; #define PG8_WAIT_V(n) asm volatile("s_waitcnt vmcnt(" #n ")" ::: "memory")
; #define PG8_WAIT_L(n) asm volatile("s_waitcnt lgkmcnt(" #n ")" ::: "memory")
; #define PG8_BAR __builtin_amdgcn_s_barrier()
; #define PG8_SCHED __builtin_amdgcn_sched_barrier(0)
; template <class Epi, class Sched, bool ALIGN_EPI = false, bool SP2 = false>
; __device__ __forceinline__ void gemm_phase(PG8_LAS unsigned char* lds, const Gemm g, const Sched& S, const Epi& E) {
;     ...
;             PG8_WAIT_V(8); PG8_WAIT_L(0); PG8_BAR; PG8_MMA(0, 0, At, B0); PG8_MMA(0, 1, At, B1); PG8_BAR; PG8_SCHED;
;             PG8_LDA(At, 1, 1); PG8_STAGE(PG8_SB(1, 0), b3, voffB); PG8_STAGE(PG8_SB(1, 1), b3 + hstep, voffB); PG8_STAGE(PG8_SA(1, 0), a3, voffA);
;             PG8_WAIT_V(8); PG8_WAIT_L(0); PG8_BAR; PG8_MMA(1, 0, At, B0); PG8_MMA(1, 1, At, B1); PG8_BAR; PG8_SCHED;
	s_setprio 0
	s_waitcnt lgkmcnt(0)
	v_mfma_f32_16x16x32_bf16 v[126:129], v[156:159], v[220:223], v[126:129]
	v_mfma_f32_16x16x32_bf16 v[126:129], v[160:163], v[224:227], v[126:129]
	v_mfma_f32_16x16x32_bf16 v[110:113], v[156:159], v[228:231], v[110:113]
	v_mfma_f32_16x16x32_bf16 v[110:113], v[160:163], v[232:235], v[110:113]
	v_mfma_f32_16x16x32_bf16 v[94:97], v[156:159], v[236:239], v[94:97]
	v_mfma_f32_16x16x32_bf16 v[94:97], v[160:163], v[240:243], v[94:97]
	v_mfma_f32_16x16x32_bf16 v[78:81], v[156:159], v[244:247], v[78:81]
	v_mfma_f32_16x16x32_bf16 v[78:81], v[160:163], v[248:251], v[78:81]
	v_mfma_f32_16x16x32_bf16 v[74:77], v[196:199], v[244:247], v[74:77]
	v_mfma_f32_16x16x32_bf16 v[74:77], v[200:203], v[248:251], v[74:77]
	v_mfma_f32_16x16x32_bf16 v[90:93], v[196:199], v[236:239], v[90:93]
	v_mfma_f32_16x16x32_bf16 v[90:93], v[200:203], v[240:243], v[90:93]
	v_mfma_f32_16x16x32_bf16 v[106:109], v[196:199], v[228:231], v[106:109]
	v_mfma_f32_16x16x32_bf16 v[106:109], v[200:203], v[232:235], v[106:109]
	v_mfma_f32_16x16x32_bf16 v[122:125], v[196:199], v[220:223], v[122:125]
	v_mfma_f32_16x16x32_bf16 v[122:125], v[200:203], v[224:227], v[122:125]
	v_mfma_f32_16x16x32_bf16 v[118:121], v[204:207], v[220:223], v[118:121]
	v_mfma_f32_16x16x32_bf16 v[118:121], v[208:211], v[224:227], v[118:121]
	v_mfma_f32_16x16x32_bf16 v[102:105], v[204:207], v[228:231], v[102:105]
	v_mfma_f32_16x16x32_bf16 v[102:105], v[208:211], v[232:235], v[102:105]
	v_mfma_f32_16x16x32_bf16 v[86:89], v[204:207], v[236:239], v[86:89]
	v_mfma_f32_16x16x32_bf16 v[86:89], v[208:211], v[240:243], v[86:89]
	v_mfma_f32_16x16x32_bf16 v[70:73], v[204:207], v[244:247], v[70:73]
	v_mfma_f32_16x16x32_bf16 v[70:73], v[208:211], v[248:251], v[70:73]
	v_mfma_f32_16x16x32_bf16 v[66:69], v[212:215], v[244:247], v[66:69]
	v_mfma_f32_16x16x32_bf16 v[66:69], v[216:219], v[248:251], v[66:69]
	v_mfma_f32_16x16x32_bf16 v[82:85], v[212:215], v[236:239], v[82:85]
	v_mfma_f32_16x16x32_bf16 v[82:85], v[216:219], v[240:243], v[82:85]
	v_mfma_f32_16x16x32_bf16 v[98:101], v[212:215], v[228:231], v[98:101]
	v_mfma_f32_16x16x32_bf16 v[98:101], v[216:219], v[232:235], v[98:101]
	v_mfma_f32_16x16x32_bf16 v[114:117], v[212:215], v[220:223], v[114:117]
	v_mfma_f32_16x16x32_bf16 v[114:117], v[216:219], v[224:227], v[114:117]
	s_setprio 1
	s_barrier
	s_add_u32 s46, s44, 0x8000
	s_addc_u32 s47, s45, 0
	s_add_i32 s62, s62, s29
	s_mov_b32 m0, s62
	ds_read_b128 v[220:223], v186 offset:49152
	ds_read_b128 v[224:227], v186 offset:50176
	ds_read_b128 v[228:231], v186 offset:51200
	ds_read_b128 v[232:235], v186 offset:52224
	ds_read_b128 v[236:239], v186 offset:53248
	ds_read_b128 v[240:243], v186 offset:54272
	ds_read_b128 v[244:247], v186 offset:55296
	ds_read_b128 v[248:251], v186 offset:56320
	global_load_lds_dwordx4 v132, s[46:47]
	s_add_i32 m0, s62, 0x2000
	s_add_u32 s44, s44, 0xc000
	v_lshl_add_u64 v[164:165], s[46:47], 0, v[136:137]
	s_addc_u32 s45, s45, 0
	s_add_i32 s46, s63, s29
	global_load_lds_dwordx4 v[164:165], off
	s_mov_b32 m0, s46
	s_nop 0
	global_load_lds_dwordx4 v132, s[44:45]
	s_add_i32 m0, s46, 0x2000
	s_nop 0
	global_load_lds_dwordx4 v136, s[44:45]
	s_waitcnt vmcnt(6)
	s_waitcnt lgkmcnt(0)
	s_barrier
	s_setprio 0
	s_waitcnt lgkmcnt(0)
	v_mfma_f32_16x16x32_bf16 v[62:65], v[156:159], v[220:223], v[62:65]
	v_mfma_f32_16x16x32_bf16 v[62:65], v[160:163], v[224:227], v[62:65]
	v_mfma_f32_16x16x32_bf16 v[46:49], v[156:159], v[228:231], v[46:49]
	v_mfma_f32_16x16x32_bf16 v[46:49], v[160:163], v[232:235], v[46:49]
	v_mfma_f32_16x16x32_bf16 v[30:33], v[156:159], v[236:239], v[30:33]
	v_mfma_f32_16x16x32_bf16 v[30:33], v[160:163], v[240:243], v[30:33]
	v_mfma_f32_16x16x32_bf16 v[14:17], v[156:159], v[244:247], v[14:17]
	v_mfma_f32_16x16x32_bf16 v[14:17], v[160:163], v[248:251], v[14:17]
	v_mfma_f32_16x16x32_bf16 v[10:13], v[196:199], v[244:247], v[10:13]
	v_mfma_f32_16x16x32_bf16 v[10:13], v[200:203], v[248:251], v[10:13]
	v_mfma_f32_16x16x32_bf16 v[26:29], v[196:199], v[236:239], v[26:29]
	v_mfma_f32_16x16x32_bf16 v[26:29], v[200:203], v[240:243], v[26:29]
	v_mfma_f32_16x16x32_bf16 v[42:45], v[196:199], v[228:231], v[42:45]
	v_mfma_f32_16x16x32_bf16 v[42:45], v[200:203], v[232:235], v[42:45]
	v_mfma_f32_16x16x32_bf16 v[58:61], v[196:199], v[220:223], v[58:61]
	v_mfma_f32_16x16x32_bf16 v[58:61], v[200:203], v[224:227], v[58:61]
	v_mfma_f32_16x16x32_bf16 v[54:57], v[204:207], v[220:223], v[54:57]
	v_mfma_f32_16x16x32_bf16 v[54:57], v[208:211], v[224:227], v[54:57]
	v_mfma_f32_16x16x32_bf16 v[38:41], v[204:207], v[228:231], v[38:41]
	v_mfma_f32_16x16x32_bf16 v[38:41], v[208:211], v[232:235], v[38:41]
	v_mfma_f32_16x16x32_bf16 v[22:25], v[204:207], v[236:239], v[22:25]
	v_mfma_f32_16x16x32_bf16 v[22:25], v[208:211], v[240:243], v[22:25]
	v_mfma_f32_16x16x32_bf16 v[6:9], v[204:207], v[244:247], v[6:9]
	v_mfma_f32_16x16x32_bf16 v[6:9], v[208:211], v[248:251], v[6:9]
	v_mfma_f32_16x16x32_bf16 v[2:5], v[212:215], v[244:247], v[2:5]
	v_mfma_f32_16x16x32_bf16 v[2:5], v[216:219], v[248:251], v[2:5]
	v_mfma_f32_16x16x32_bf16 v[18:21], v[212:215], v[236:239], v[18:21]
	v_mfma_f32_16x16x32_bf16 v[18:21], v[216:219], v[240:243], v[18:21]
	v_mfma_f32_16x16x32_bf16 v[34:37], v[212:215], v[228:231], v[34:37]
	v_mfma_f32_16x16x32_bf16 v[34:37], v[216:219], v[232:235], v[34:37]
	v_mfma_f32_16x16x32_bf16 v[50:53], v[212:215], v[220:223], v[50:53]
	v_mfma_f32_16x16x32_bf16 v[50:53], v[216:219], v[224:227], v[50:53]
	s_setprio 1
	s_barrier
	s_cmpk_gt_u32 s59, 0xa9
	s_mov_b32 s59, s24
	s_cbranch_scc0 .LBB0_939
	s_setprio 0
	s_and_b64 vcc, exec, s[38:39]
	s_cbranch_vccz .LBB0_942
	s_barrier
